# GEMM main loops: loop-counter and pointer SALU block hoisted into the last MFMA burst; s_setprio 0 after the loop-back barrier
# baseline (speedup 1.0000x reference)
.LBB0_139:
	v_add_u32_e32 v253, 0x10000, v146
	ds_read_b128 v[140:143], v253
	ds_read_b128 v[150:153], v253 offset:1024
	ds_read_b128 v[154:157], v253 offset:2048
	ds_read_b128 v[158:161], v253 offset:3072
	s_add_u32 s10, s6, 0xfff80080
	s_addc_u32 s11, s7, -1
	s_cmp_eq_u32 s41, 28
	s_cselect_b32 s11, s63, s11
	s_cselect_b32 s10, s62, s10
	s_cselect_b32 s53, s61, s29
	s_cselect_b32 s52, s60, s28
	s_mov_b32 m0, s12
	ds_read_b128 v[162:165], v145
	ds_read_b128 v[166:169], v145 offset:1024
	ds_read_b128 v[170:173], v145 offset:2048
	ds_read_b128 v[174:177], v145 offset:3072
	ds_read_b128 v[178:181], v145 offset:4096
	ds_read_b128 v[182:185], v145 offset:5120
	ds_read_b128 v[186:189], v145 offset:6144
	ds_read_b128 v[190:193], v145 offset:7168
	global_load_lds_dwordx4 v136, s[6:7]
	s_mov_b32 m0, s78
	s_nop 0
	global_load_lds_dwordx4 v138, s[6:7]
	s_waitcnt lgkmcnt(8)
	s_setprio 1
	s_barrier
	s_waitcnt lgkmcnt(0)
	v_mfma_f32_16x16x32_bf16 v[126:129], v[140:143], v[162:165], v[126:129]
	v_mfma_f32_16x16x32_bf16 v[122:125], v[154:157], v[162:165], v[122:125]
	v_mfma_f32_16x16x32_bf16 v[118:121], v[140:143], v[170:173], v[118:121]
	v_mfma_f32_16x16x32_bf16 v[110:113], v[154:157], v[170:173], v[110:113]
	v_mfma_f32_16x16x32_bf16 v[102:105], v[140:143], v[178:181], v[102:105]
	v_mfma_f32_16x16x32_bf16 v[94:97], v[154:157], v[178:181], v[94:97]
	v_mfma_f32_16x16x32_bf16 v[86:89], v[140:143], v[186:189], v[86:89]
	v_mfma_f32_16x16x32_bf16 v[78:81], v[154:157], v[186:189], v[78:81]
	v_mfma_f32_16x16x32_bf16 v[126:129], v[150:153], v[166:169], v[126:129]
	v_mfma_f32_16x16x32_bf16 v[122:125], v[158:161], v[166:169], v[122:125]
	v_mfma_f32_16x16x32_bf16 v[118:121], v[150:153], v[174:177], v[118:121]
	v_mfma_f32_16x16x32_bf16 v[110:113], v[158:161], v[174:177], v[110:113]
	v_mfma_f32_16x16x32_bf16 v[102:105], v[150:153], v[182:185], v[102:105]
	v_mfma_f32_16x16x32_bf16 v[94:97], v[158:161], v[182:185], v[94:97]
	v_mfma_f32_16x16x32_bf16 v[86:89], v[150:153], v[190:193], v[86:89]
	v_mfma_f32_16x16x32_bf16 v[78:81], v[158:161], v[190:193], v[78:81]
	s_barrier
	s_setprio 0
	s_mov_b32 m0, s83
	ds_read_b128 v[206:209], v253 offset:16384
	ds_read_b128 v[210:213], v253 offset:17408
	v_lshl_add_u64 v[222:223], s[52:53], 0, v[194:195]
	ds_read_b128 v[214:217], v253 offset:18432
	ds_read_b128 v[218:221], v253 offset:19456
	global_load_lds_dwordx4 v[222:223], off
	v_lshl_add_u64 v[224:225], s[52:53], 0, v[134:135]
	s_mov_b32 m0, s54
	s_nop 0
	global_load_lds_dwordx4 v[224:225], off
	s_setprio 1
	s_barrier
	s_waitcnt lgkmcnt(0)
	v_mfma_f32_16x16x32_bf16 v[114:117], v[206:209], v[162:165], v[114:117]
	v_mfma_f32_16x16x32_bf16 v[106:109], v[214:217], v[162:165], v[106:109]
	v_mfma_f32_16x16x32_bf16 v[98:101], v[206:209], v[170:173], v[98:101]
	v_mfma_f32_16x16x32_bf16 v[90:93], v[214:217], v[170:173], v[90:93]
	v_mfma_f32_16x16x32_bf16 v[82:85], v[206:209], v[178:181], v[82:85]
	v_mfma_f32_16x16x32_bf16 v[74:77], v[214:217], v[178:181], v[74:77]
	v_mfma_f32_16x16x32_bf16 v[70:73], v[206:209], v[186:189], v[70:73]
	v_mfma_f32_16x16x32_bf16 v[66:69], v[214:217], v[186:189], v[66:69]
	v_mfma_f32_16x16x32_bf16 v[114:117], v[210:213], v[166:169], v[114:117]
	v_mfma_f32_16x16x32_bf16 v[106:109], v[218:221], v[166:169], v[106:109]
	v_mfma_f32_16x16x32_bf16 v[98:101], v[210:213], v[174:177], v[98:101]
	v_mfma_f32_16x16x32_bf16 v[90:93], v[218:221], v[174:177], v[90:93]
	v_mfma_f32_16x16x32_bf16 v[82:85], v[210:213], v[182:185], v[82:85]
	v_mfma_f32_16x16x32_bf16 v[74:77], v[218:221], v[182:185], v[74:77]
	s_mov_b32 m0, s55
	v_mfma_f32_16x16x32_bf16 v[70:73], v[210:213], v[190:193], v[70:73]
	v_lshl_add_u64 v[226:227], s[10:11], 0, v[130:131]
	v_mfma_f32_16x16x32_bf16 v[66:69], v[218:221], v[190:193], v[66:69]
	s_barrier
	s_setprio 0
	ds_read_b128 v[162:165], v145 offset:16384
	ds_read_b128 v[166:169], v145 offset:17408
	ds_read_b128 v[170:173], v145 offset:18432
	ds_read_b128 v[174:177], v145 offset:19456
	ds_read_b128 v[178:181], v145 offset:20480
	ds_read_b128 v[182:185], v145 offset:21504
	ds_read_b128 v[186:189], v145 offset:22528
	ds_read_b128 v[190:193], v145 offset:23552
	global_load_lds_dwordx4 v[226:227], off
	v_lshl_add_u64 v[228:229], s[10:11], 0, v[132:133]
	s_mov_b32 m0, s34
	s_nop 0
	global_load_lds_dwordx4 v[228:229], off
	s_setprio 1
	s_barrier
	s_waitcnt lgkmcnt(0)
	v_mfma_f32_16x16x32_bf16 v[62:65], v[140:143], v[162:165], v[62:65]
	v_mfma_f32_16x16x32_bf16 v[58:61], v[154:157], v[162:165], v[58:61]
	v_mfma_f32_16x16x32_bf16 v[54:57], v[140:143], v[170:173], v[54:57]
	v_mfma_f32_16x16x32_bf16 v[46:49], v[154:157], v[170:173], v[46:49]
	v_mfma_f32_16x16x32_bf16 v[38:41], v[140:143], v[178:181], v[38:41]
	v_mfma_f32_16x16x32_bf16 v[30:33], v[154:157], v[178:181], v[30:33]
	v_mfma_f32_16x16x32_bf16 v[22:25], v[140:143], v[186:189], v[22:25]
	v_mfma_f32_16x16x32_bf16 v[14:17], v[154:157], v[186:189], v[14:17]
	v_mfma_f32_16x16x32_bf16 v[62:65], v[150:153], v[166:169], v[62:65]
	v_mfma_f32_16x16x32_bf16 v[58:61], v[158:161], v[166:169], v[58:61]
	v_mfma_f32_16x16x32_bf16 v[54:57], v[150:153], v[174:177], v[54:57]
	v_mfma_f32_16x16x32_bf16 v[46:49], v[158:161], v[174:177], v[46:49]
	v_mfma_f32_16x16x32_bf16 v[38:41], v[150:153], v[182:185], v[38:41]
	v_mfma_f32_16x16x32_bf16 v[30:33], v[158:161], v[182:185], v[30:33]
	v_mfma_f32_16x16x32_bf16 v[22:25], v[150:153], v[190:193], v[22:25]
	v_mfma_f32_16x16x32_bf16 v[14:17], v[158:161], v[190:193], v[14:17]
	s_barrier
	s_setprio 0
	s_add_u32 s58, s52, 0x80000
	s_addc_u32 s59, s53, 0
	s_mov_b32 m0, s4
	s_nop 0
	global_load_lds_dwordx4 v194, s[58:59]
	s_mov_b32 m0, s5
	s_nop 0
	global_load_lds_dwordx4 v134, s[58:59]
	s_waitcnt vmcnt(6)
	s_setprio 1
	s_barrier
	v_mfma_f32_16x16x32_bf16 v[50:53], v[206:209], v[162:165], v[50:53]
	v_mfma_f32_16x16x32_bf16 v[42:45], v[214:217], v[162:165], v[42:45]
	v_mfma_f32_16x16x32_bf16 v[34:37], v[206:209], v[170:173], v[34:37]
	v_mfma_f32_16x16x32_bf16 v[26:29], v[214:217], v[170:173], v[26:29]
	v_mfma_f32_16x16x32_bf16 v[18:21], v[206:209], v[178:181], v[18:21]
	v_mfma_f32_16x16x32_bf16 v[10:13], v[214:217], v[178:181], v[10:13]
	v_mfma_f32_16x16x32_bf16 v[6:9], v[206:209], v[186:189], v[6:9]
	v_mfma_f32_16x16x32_bf16 v[2:5], v[214:217], v[186:189], v[2:5]
	v_mfma_f32_16x16x32_bf16 v[50:53], v[210:213], v[166:169], v[50:53]
	v_mfma_f32_16x16x32_bf16 v[42:45], v[218:221], v[166:169], v[42:45]
	v_mfma_f32_16x16x32_bf16 v[34:37], v[210:213], v[174:177], v[34:37]
	v_mfma_f32_16x16x32_bf16 v[26:29], v[218:221], v[174:177], v[26:29]
	v_mfma_f32_16x16x32_bf16 v[18:21], v[210:213], v[182:185], v[18:21]
	v_mfma_f32_16x16x32_bf16 v[10:13], v[218:221], v[182:185], v[10:13]
	v_mfma_f32_16x16x32_bf16 v[6:9], v[210:213], v[190:193], v[6:9]
	v_mfma_f32_16x16x32_bf16 v[2:5], v[218:221], v[190:193], v[2:5]
	s_barrier
	s_setprio 0
	ds_read_b128 v[140:143], v253 offset:32768
	ds_read_b128 v[150:153], v253 offset:33792
	ds_read_b128 v[154:157], v253 offset:34816
	ds_read_b128 v[158:161], v253 offset:35840
	s_add_u32 s10, s10, 0x80000
	s_addc_u32 s11, s11, 0
	s_mov_b32 m0, s56
	ds_read_b128 v[162:165], v145 offset:32768
	ds_read_b128 v[166:169], v145 offset:33792
	ds_read_b128 v[170:173], v145 offset:34816
	ds_read_b128 v[174:177], v145 offset:35840
	ds_read_b128 v[178:181], v145 offset:36864
	ds_read_b128 v[182:185], v145 offset:37888
	ds_read_b128 v[186:189], v145 offset:38912
	ds_read_b128 v[190:193], v145 offset:39936
	global_load_lds_dwordx4 v130, s[10:11]
	s_mov_b32 m0, s57
	s_nop 0
	global_load_lds_dwordx4 v132, s[10:11]
	s_waitcnt lgkmcnt(8)
	s_setprio 1
	s_barrier
	s_waitcnt lgkmcnt(0)
	v_mfma_f32_16x16x32_bf16 v[126:129], v[140:143], v[162:165], v[126:129]
	v_mfma_f32_16x16x32_bf16 v[122:125], v[154:157], v[162:165], v[122:125]
	v_mfma_f32_16x16x32_bf16 v[118:121], v[140:143], v[170:173], v[118:121]
	v_mfma_f32_16x16x32_bf16 v[110:113], v[154:157], v[170:173], v[110:113]
	v_mfma_f32_16x16x32_bf16 v[102:105], v[140:143], v[178:181], v[102:105]
	v_mfma_f32_16x16x32_bf16 v[94:97], v[154:157], v[178:181], v[94:97]
	v_mfma_f32_16x16x32_bf16 v[86:89], v[140:143], v[186:189], v[86:89]
	v_mfma_f32_16x16x32_bf16 v[78:81], v[154:157], v[186:189], v[78:81]
	v_mfma_f32_16x16x32_bf16 v[126:129], v[150:153], v[166:169], v[126:129]
	v_mfma_f32_16x16x32_bf16 v[122:125], v[158:161], v[166:169], v[122:125]
	v_mfma_f32_16x16x32_bf16 v[118:121], v[150:153], v[174:177], v[118:121]
	v_mfma_f32_16x16x32_bf16 v[110:113], v[158:161], v[174:177], v[110:113]
	v_mfma_f32_16x16x32_bf16 v[102:105], v[150:153], v[182:185], v[102:105]
	v_mfma_f32_16x16x32_bf16 v[94:97], v[158:161], v[182:185], v[94:97]
	v_mfma_f32_16x16x32_bf16 v[86:89], v[150:153], v[190:193], v[86:89]
	v_mfma_f32_16x16x32_bf16 v[78:81], v[158:161], v[190:193], v[78:81]
	s_barrier
	s_setprio 0
	s_mov_b32 m0, s70
	ds_read_b128 v[206:209], v253 offset:49152
	ds_read_b128 v[210:213], v253 offset:50176
	v_lshl_add_u64 v[222:223], v[222:223], 0, s[76:77]
	ds_read_b128 v[214:217], v253 offset:51200
	ds_read_b128 v[218:221], v253 offset:52224
	global_load_lds_dwordx4 v[222:223], off
	v_lshl_add_u64 v[222:223], v[224:225], 0, s[76:77]
	s_mov_b32 m0, s71
	s_nop 0
	global_load_lds_dwordx4 v[222:223], off
	s_setprio 1
	s_barrier
	s_waitcnt lgkmcnt(0)
	v_mfma_f32_16x16x32_bf16 v[114:117], v[206:209], v[162:165], v[114:117]
	v_mfma_f32_16x16x32_bf16 v[106:109], v[214:217], v[162:165], v[106:109]
	v_mfma_f32_16x16x32_bf16 v[98:101], v[206:209], v[170:173], v[98:101]
	v_mfma_f32_16x16x32_bf16 v[90:93], v[214:217], v[170:173], v[90:93]
	v_mfma_f32_16x16x32_bf16 v[82:85], v[206:209], v[178:181], v[82:85]
	v_mfma_f32_16x16x32_bf16 v[74:77], v[214:217], v[178:181], v[74:77]
	v_mfma_f32_16x16x32_bf16 v[70:73], v[206:209], v[186:189], v[70:73]
	v_mfma_f32_16x16x32_bf16 v[66:69], v[214:217], v[186:189], v[66:69]
	v_mfma_f32_16x16x32_bf16 v[114:117], v[210:213], v[166:169], v[114:117]
	v_mfma_f32_16x16x32_bf16 v[106:109], v[218:221], v[166:169], v[106:109]
	v_mfma_f32_16x16x32_bf16 v[98:101], v[210:213], v[174:177], v[98:101]
	v_mfma_f32_16x16x32_bf16 v[90:93], v[218:221], v[174:177], v[90:93]
	v_mfma_f32_16x16x32_bf16 v[82:85], v[210:213], v[182:185], v[82:85]
	v_mfma_f32_16x16x32_bf16 v[74:77], v[218:221], v[182:185], v[74:77]
	s_mov_b32 m0, s33
	v_mfma_f32_16x16x32_bf16 v[70:73], v[210:213], v[190:193], v[70:73]
	v_lshl_add_u64 v[222:223], v[226:227], 0, s[76:77]
	v_mfma_f32_16x16x32_bf16 v[66:69], v[218:221], v[190:193], v[66:69]
	s_barrier
	s_setprio 0
	ds_read_b128 v[162:165], v145 offset:49152
	ds_read_b128 v[166:169], v145 offset:50176
	ds_read_b128 v[170:173], v145 offset:51200
	ds_read_b128 v[174:177], v145 offset:52224
	ds_read_b128 v[178:181], v145 offset:53248
	ds_read_b128 v[182:185], v145 offset:54272
	ds_read_b128 v[186:189], v145 offset:55296
	ds_read_b128 v[190:193], v145 offset:56320
	global_load_lds_dwordx4 v[222:223], off
	v_lshl_add_u64 v[222:223], v[228:229], 0, s[76:77]
	s_mov_b32 m0, s35
	s_nop 0
	global_load_lds_dwordx4 v[222:223], off
	s_setprio 1
	s_barrier
	s_waitcnt lgkmcnt(0)
	v_mfma_f32_16x16x32_bf16 v[62:65], v[140:143], v[162:165], v[62:65]
	v_mfma_f32_16x16x32_bf16 v[58:61], v[154:157], v[162:165], v[58:61]
	v_mfma_f32_16x16x32_bf16 v[54:57], v[140:143], v[170:173], v[54:57]
	v_mfma_f32_16x16x32_bf16 v[46:49], v[154:157], v[170:173], v[46:49]
	v_mfma_f32_16x16x32_bf16 v[38:41], v[140:143], v[178:181], v[38:41]
	v_mfma_f32_16x16x32_bf16 v[30:33], v[154:157], v[178:181], v[30:33]
	v_mfma_f32_16x16x32_bf16 v[22:25], v[140:143], v[186:189], v[22:25]
	v_mfma_f32_16x16x32_bf16 v[14:17], v[154:157], v[186:189], v[14:17]
	v_mfma_f32_16x16x32_bf16 v[62:65], v[150:153], v[166:169], v[62:65]
	v_mfma_f32_16x16x32_bf16 v[58:61], v[158:161], v[166:169], v[58:61]
	v_mfma_f32_16x16x32_bf16 v[54:57], v[150:153], v[174:177], v[54:57]
	v_mfma_f32_16x16x32_bf16 v[46:49], v[158:161], v[174:177], v[46:49]
	v_mfma_f32_16x16x32_bf16 v[38:41], v[150:153], v[182:185], v[38:41]
	v_mfma_f32_16x16x32_bf16 v[30:33], v[158:161], v[182:185], v[30:33]
	v_mfma_f32_16x16x32_bf16 v[22:25], v[150:153], v[190:193], v[22:25]
	v_mfma_f32_16x16x32_bf16 v[14:17], v[158:161], v[190:193], v[14:17]
	s_barrier
	s_setprio 0
	s_add_u32 s10, s52, 0x80080
	s_addc_u32 s11, s53, 0
	s_mov_b32 m0, s67
	s_nop 0
	global_load_lds_dwordx4 v194, s[10:11]
	s_mov_b32 m0, s17
	s_nop 0
	global_load_lds_dwordx4 v134, s[10:11]
	s_waitcnt vmcnt(6)
	s_setprio 1
	s_barrier
	v_mfma_f32_16x16x32_bf16 v[50:53], v[206:209], v[162:165], v[50:53]
	v_mfma_f32_16x16x32_bf16 v[42:45], v[214:217], v[162:165], v[42:45]
	v_mfma_f32_16x16x32_bf16 v[34:37], v[206:209], v[170:173], v[34:37]
	v_mfma_f32_16x16x32_bf16 v[26:29], v[214:217], v[170:173], v[26:29]
	v_mfma_f32_16x16x32_bf16 v[18:21], v[206:209], v[178:181], v[18:21]
	v_mfma_f32_16x16x32_bf16 v[10:13], v[214:217], v[178:181], v[10:13]
	v_mfma_f32_16x16x32_bf16 v[6:9], v[206:209], v[186:189], v[6:9]
	v_mfma_f32_16x16x32_bf16 v[2:5], v[214:217], v[186:189], v[2:5]
	s_add_i32 s41, s41, 2
	s_add_u32 s6, s6, 0x100
	s_addc_u32 s7, s7, 0
	s_add_u32 s28, s28, 0x100
	s_addc_u32 s29, s29, 0
	s_cmp_gt_u32 s41, 29
	v_mfma_f32_16x16x32_bf16 v[50:53], v[210:213], v[166:169], v[50:53]
	v_mfma_f32_16x16x32_bf16 v[42:45], v[218:221], v[166:169], v[42:45]
	v_mfma_f32_16x16x32_bf16 v[34:37], v[210:213], v[174:177], v[34:37]
	v_mfma_f32_16x16x32_bf16 v[26:29], v[218:221], v[174:177], v[26:29]
	v_mfma_f32_16x16x32_bf16 v[18:21], v[210:213], v[182:185], v[18:21]
	v_mfma_f32_16x16x32_bf16 v[10:13], v[218:221], v[182:185], v[10:13]
	v_mfma_f32_16x16x32_bf16 v[6:9], v[210:213], v[190:193], v[6:9]
	v_mfma_f32_16x16x32_bf16 v[2:5], v[218:221], v[190:193], v[2:5]
	s_barrier
	s_setprio 0
	s_cbranch_scc0 .LBB0_139
	s_cmp_gt_i32 s79, 3
	s_mov_b64 s[6:7], -1
	s_cbranch_scc0 .LBB0_146
	s_lshl_b32 s10, s82, 8
	v_lshl_or_b32 v140, s80, 8, v149
	s_cmp_lg_u32 s79, 4
	v_ashrrev_i32_e32 v141, 31, v140
	s_cbranch_scc0 .LBB0_143
	v_readlane_b32 s6, v252, 55
	v_readlane_b32 s7, v252, 56
	v_add_u32_e32 v150, s10, v147
	s_nop 0
	v_mov_b64_e32 v[142:143], s[6:7]
	s_mov_b32 s6, 0x9000
	v_mad_i64_i32 v[142:143], s[6:7], v150, s6, v[142:143]
	v_lshl_add_u64 v[142:143], v[140:141], 1, v[142:143]
	v_cvt_pk_bf16_f32 v150, v126, v127
	v_cvt_pk_bf16_f32 v151, v128, v129
	v_cvt_pk_bf16_f32 v152, v122, v123
	v_cvt_pk_bf16_f32 v153, v124, v125
	global_store_dwordx4 v[142:143], v[150:153], off
	v_add_co_u32_e32 v154, vcc, s44, v142
	s_nop 0
	v_cvt_pk_bf16_f32 v150, v114, v115
	v_cvt_pk_bf16_f32 v151, v116, v117
	v_cvt_pk_bf16_f32 v152, v106, v107
	v_cvt_pk_bf16_f32 v153, v108, v109
	global_store_dwordx4 v[142:143], v[150:153], off offset:256
	v_addc_co_u32_e32 v155, vcc, 0, v143, vcc
	s_nop 0
	v_cvt_pk_bf16_f32 v150, v118, v119
	v_cvt_pk_bf16_f32 v151, v120, v121
	v_cvt_pk_bf16_f32 v152, v110, v111
	v_cvt_pk_bf16_f32 v153, v112, v113
	global_store_dwordx4 v[154:155], v[150:153], off
	s_mov_b64 s[6:7], 0
	s_nop 0
	v_cvt_pk_bf16_f32 v150, v98, v99
	v_cvt_pk_bf16_f32 v151, v100, v101
	v_cvt_pk_bf16_f32 v152, v90, v91
	v_cvt_pk_bf16_f32 v153, v92, v93
	global_store_dwordx4 v[154:155], v[150:153], off offset:256
	v_add_co_u32_e32 v154, vcc, s45, v142
	s_nop 0
	v_cvt_pk_bf16_f32 v150, v102, v103
	v_cvt_pk_bf16_f32 v151, v104, v105
	v_cvt_pk_bf16_f32 v152, v94, v95
	v_cvt_pk_bf16_f32 v153, v96, v97
	s_nop 0
	v_addc_co_u32_e32 v155, vcc, 0, v143, vcc
	global_store_dwordx4 v[154:155], v[150:153], off
	s_nop 1
	v_cvt_pk_bf16_f32 v150, v82, v83
	v_cvt_pk_bf16_f32 v151, v84, v85
	v_cvt_pk_bf16_f32 v152, v74, v75
	v_cvt_pk_bf16_f32 v153, v76, v77
	global_store_dwordx4 v[154:155], v[150:153], off offset:256
	v_add_co_u32_e32 v154, vcc, s90, v142
	s_nop 0
	v_cvt_pk_bf16_f32 v150, v86, v87
	v_cvt_pk_bf16_f32 v151, v88, v89
	v_cvt_pk_bf16_f32 v152, v78, v79
	v_cvt_pk_bf16_f32 v153, v80, v81
	s_nop 0
	v_addc_co_u32_e32 v155, vcc, 0, v143, vcc
	global_store_dwordx4 v[154:155], v[150:153], off
	s_nop 1
	v_cvt_pk_bf16_f32 v150, v70, v71
	v_cvt_pk_bf16_f32 v151, v72, v73
	v_cvt_pk_bf16_f32 v152, v66, v67
	v_cvt_pk_bf16_f32 v153, v68, v69
	global_store_dwordx4 v[154:155], v[150:153], off offset:256
	v_add_co_u32_e32 v154, vcc, s20, v142
	s_nop 0
	v_cvt_pk_bf16_f32 v150, v62, v63
	v_cvt_pk_bf16_f32 v151, v64, v65
	v_cvt_pk_bf16_f32 v152, v58, v59
	v_cvt_pk_bf16_f32 v153, v60, v61
	s_nop 0
	v_addc_co_u32_e32 v155, vcc, 0, v143, vcc
	global_store_dwordx4 v[154:155], v[150:153], off
	s_nop 1
	v_cvt_pk_bf16_f32 v150, v50, v51
	v_cvt_pk_bf16_f32 v151, v52, v53
	v_cvt_pk_bf16_f32 v152, v42, v43
	v_cvt_pk_bf16_f32 v153, v44, v45
	global_store_dwordx4 v[154:155], v[150:153], off offset:256
	v_add_co_u32_e32 v154, vcc, s21, v142
	s_nop 0
	v_cvt_pk_bf16_f32 v150, v54, v55
	v_cvt_pk_bf16_f32 v151, v56, v57
	v_cvt_pk_bf16_f32 v152, v46, v47
	v_cvt_pk_bf16_f32 v153, v48, v49
	s_nop 0
	v_addc_co_u32_e32 v155, vcc, 0, v143, vcc
	global_store_dwordx4 v[154:155], v[150:153], off
	s_nop 1
	v_cvt_pk_bf16_f32 v150, v34, v35
	v_cvt_pk_bf16_f32 v151, v36, v37
	v_cvt_pk_bf16_f32 v152, v26, v27
	v_cvt_pk_bf16_f32 v153, v28, v29
	global_store_dwordx4 v[154:155], v[150:153], off offset:256
	v_add_co_u32_e32 v154, vcc, s22, v142
	s_nop 0
	v_cvt_pk_bf16_f32 v150, v38, v39
	v_cvt_pk_bf16_f32 v151, v40, v41
	v_cvt_pk_bf16_f32 v152, v30, v31
	v_cvt_pk_bf16_f32 v153, v32, v33
	s_nop 0
	v_addc_co_u32_e32 v155, vcc, 0, v143, vcc
	global_store_dwordx4 v[154:155], v[150:153], off
	v_add_co_u32_e32 v142, vcc, s23, v142
	s_nop 0
	v_cvt_pk_bf16_f32 v150, v18, v19
	v_cvt_pk_bf16_f32 v151, v20, v21
	v_cvt_pk_bf16_f32 v152, v10, v11
	v_cvt_pk_bf16_f32 v153, v12, v13
	global_store_dwordx4 v[154:155], v[150:153], off offset:256
	v_addc_co_u32_e32 v143, vcc, 0, v143, vcc
	s_nop 0
	v_cvt_pk_bf16_f32 v150, v22, v23
	v_cvt_pk_bf16_f32 v151, v24, v25
	v_cvt_pk_bf16_f32 v152, v14, v15
	v_cvt_pk_bf16_f32 v153, v16, v17
	global_store_dwordx4 v[142:143], v[150:153], off
	s_nop 1
	v_cvt_pk_bf16_f32 v150, v6, v7
	v_cvt_pk_bf16_f32 v151, v8, v9
	v_cvt_pk_bf16_f32 v152, v2, v3
	v_cvt_pk_bf16_f32 v153, v4, v5
	global_store_dwordx4 v[142:143], v[150:153], off offset:256

.LBB0_255:
	v_add_u32_e32 v253, 0x10000, v182
	ds_read_b128 v[130:133], v253
	ds_read_b128 v[134:137], v253 offset:1024
	ds_read_b128 v[138:141], v253 offset:2048
	ds_read_b128 v[142:145], v253 offset:3072
	s_add_u32 s8, s6, 0xfff00080
	s_addc_u32 s9, s7, -1
	s_cmp_eq_u32 s79, 60
	s_cselect_b32 s11, s53, s9
	s_cselect_b32 s10, s52, s8
	s_cselect_b32 s9, s61, s78
	s_cselect_b32 s8, s60, s1
	s_add_i32 m0, s5, 0xc000
	ds_read_b128 v[146:149], v181
	ds_read_b128 v[150:153], v181 offset:1024
	ds_read_b128 v[154:157], v181 offset:2048
	ds_read_b128 v[170:173], v181 offset:3072
	ds_read_b128 v[174:177], v181 offset:4096
	ds_read_b128 v[184:187], v181 offset:5120
	ds_read_b128 v[188:191], v181 offset:6144
	ds_read_b128 v[206:209], v181 offset:7168
	global_load_lds_dwordx4 v166, s[6:7]
	s_add_i32 m0, s5, 0xe000
	s_nop 0
	global_load_lds_dwordx4 v168, s[6:7]
	s_waitcnt lgkmcnt(8)
	s_setprio 1
	s_barrier
	s_waitcnt lgkmcnt(0)
	v_mfma_f32_16x16x32_bf16 v[126:129], v[130:133], v[146:149], v[126:129]
	v_mfma_f32_16x16x32_bf16 v[122:125], v[138:141], v[146:149], v[122:125]
	v_mfma_f32_16x16x32_bf16 v[110:113], v[130:133], v[154:157], v[110:113]
	v_mfma_f32_16x16x32_bf16 v[106:109], v[138:141], v[154:157], v[106:109]
	v_mfma_f32_16x16x32_bf16 v[94:97], v[130:133], v[174:177], v[94:97]
	v_mfma_f32_16x16x32_bf16 v[90:93], v[138:141], v[174:177], v[90:93]
	v_mfma_f32_16x16x32_bf16 v[78:81], v[130:133], v[188:191], v[78:81]
	v_mfma_f32_16x16x32_bf16 v[74:77], v[138:141], v[188:191], v[74:77]
	v_mfma_f32_16x16x32_bf16 v[126:129], v[134:137], v[150:153], v[126:129]
	v_mfma_f32_16x16x32_bf16 v[122:125], v[142:145], v[150:153], v[122:125]
	v_mfma_f32_16x16x32_bf16 v[110:113], v[134:137], v[170:173], v[110:113]
	v_mfma_f32_16x16x32_bf16 v[106:109], v[142:145], v[170:173], v[106:109]
	v_mfma_f32_16x16x32_bf16 v[94:97], v[134:137], v[184:187], v[94:97]
	v_mfma_f32_16x16x32_bf16 v[90:93], v[142:145], v[184:187], v[90:93]
	v_mfma_f32_16x16x32_bf16 v[78:81], v[134:137], v[206:209], v[78:81]
	v_mfma_f32_16x16x32_bf16 v[74:77], v[142:145], v[206:209], v[74:77]
	s_barrier
	s_setprio 0
	ds_read_b128 v[210:213], v253 offset:16384
	ds_read_b128 v[214:217], v253 offset:17408
	s_mov_b32 m0, s12
	ds_read_b128 v[218:221], v253 offset:18432
	ds_read_b128 v[222:225], v253 offset:19456
	v_lshl_add_u64 v[178:179], s[8:9], 0, v[162:163]
	global_load_lds_dwordx4 v[178:179], off
	v_lshl_add_u64 v[192:193], s[8:9], 0, v[158:159]
	s_mov_b32 m0, s17
	s_nop 0
	global_load_lds_dwordx4 v[192:193], off
	s_setprio 1
	s_barrier
	s_waitcnt lgkmcnt(0)
	v_mfma_f32_16x16x32_bf16 v[118:121], v[210:213], v[146:149], v[118:121]
	v_mfma_f32_16x16x32_bf16 v[114:117], v[218:221], v[146:149], v[114:117]
	v_mfma_f32_16x16x32_bf16 v[102:105], v[210:213], v[154:157], v[102:105]
	v_mfma_f32_16x16x32_bf16 v[98:101], v[218:221], v[154:157], v[98:101]
	v_mfma_f32_16x16x32_bf16 v[86:89], v[210:213], v[174:177], v[86:89]
	v_mfma_f32_16x16x32_bf16 v[82:85], v[218:221], v[174:177], v[82:85]
	v_mfma_f32_16x16x32_bf16 v[70:73], v[210:213], v[188:191], v[70:73]
	v_mfma_f32_16x16x32_bf16 v[66:69], v[218:221], v[188:191], v[66:69]
	v_mfma_f32_16x16x32_bf16 v[118:121], v[214:217], v[150:153], v[118:121]
	v_mfma_f32_16x16x32_bf16 v[114:117], v[222:225], v[150:153], v[114:117]
	v_mfma_f32_16x16x32_bf16 v[102:105], v[214:217], v[170:173], v[102:105]
	v_mfma_f32_16x16x32_bf16 v[98:101], v[222:225], v[170:173], v[98:101]
	v_mfma_f32_16x16x32_bf16 v[86:89], v[214:217], v[184:187], v[86:89]
	v_mfma_f32_16x16x32_bf16 v[82:85], v[222:225], v[184:187], v[82:85]
	s_mov_b32 m0, s5
	v_mfma_f32_16x16x32_bf16 v[70:73], v[214:217], v[206:209], v[70:73]
	v_lshl_add_u64 v[226:227], s[10:11], 0, v[164:165]
	v_mfma_f32_16x16x32_bf16 v[66:69], v[222:225], v[206:209], v[66:69]
	s_barrier
	s_setprio 0
	ds_read_b128 v[146:149], v181 offset:16384
	ds_read_b128 v[150:153], v181 offset:17408
	ds_read_b128 v[154:157], v181 offset:18432
	ds_read_b128 v[170:173], v181 offset:19456
	ds_read_b128 v[174:177], v181 offset:20480
	ds_read_b128 v[184:187], v181 offset:21504
	ds_read_b128 v[188:191], v181 offset:22528
	ds_read_b128 v[206:209], v181 offset:23552
	global_load_lds_dwordx4 v[226:227], off
	v_lshl_add_u64 v[228:229], s[10:11], 0, v[160:161]
	s_mov_b32 m0, s26
	s_nop 0
	global_load_lds_dwordx4 v[228:229], off
	s_setprio 1
	s_barrier
	s_waitcnt lgkmcnt(0)
	v_mfma_f32_16x16x32_bf16 v[62:65], v[130:133], v[146:149], v[62:65]
	v_mfma_f32_16x16x32_bf16 v[58:61], v[138:141], v[146:149], v[58:61]
	v_mfma_f32_16x16x32_bf16 v[46:49], v[130:133], v[154:157], v[46:49]
	v_mfma_f32_16x16x32_bf16 v[42:45], v[138:141], v[154:157], v[42:45]
	v_mfma_f32_16x16x32_bf16 v[30:33], v[130:133], v[174:177], v[30:33]
	v_mfma_f32_16x16x32_bf16 v[26:29], v[138:141], v[174:177], v[26:29]
	v_mfma_f32_16x16x32_bf16 v[14:17], v[130:133], v[188:191], v[14:17]
	v_mfma_f32_16x16x32_bf16 v[10:13], v[138:141], v[188:191], v[10:13]
	v_mfma_f32_16x16x32_bf16 v[62:65], v[134:137], v[150:153], v[62:65]
	v_mfma_f32_16x16x32_bf16 v[58:61], v[142:145], v[150:153], v[58:61]
	v_mfma_f32_16x16x32_bf16 v[46:49], v[134:137], v[170:173], v[46:49]
	v_mfma_f32_16x16x32_bf16 v[42:45], v[142:145], v[170:173], v[42:45]
	v_mfma_f32_16x16x32_bf16 v[30:33], v[134:137], v[184:187], v[30:33]
	v_mfma_f32_16x16x32_bf16 v[26:29], v[142:145], v[184:187], v[26:29]
	v_mfma_f32_16x16x32_bf16 v[14:17], v[134:137], v[206:209], v[14:17]
	v_mfma_f32_16x16x32_bf16 v[10:13], v[142:145], v[206:209], v[10:13]
	s_barrier
	s_setprio 0
	s_add_u32 s80, s8, 0x100000
	s_addc_u32 s81, s9, 0
	s_mov_b32 m0, s34
	s_nop 0
	global_load_lds_dwordx4 v162, s[80:81]
	s_mov_b32 m0, s35
	s_nop 0
	global_load_lds_dwordx4 v158, s[80:81]
	s_waitcnt vmcnt(6)
	s_setprio 1
	s_barrier
	v_mfma_f32_16x16x32_bf16 v[54:57], v[210:213], v[146:149], v[54:57]
	v_mfma_f32_16x16x32_bf16 v[50:53], v[218:221], v[146:149], v[50:53]
	v_mfma_f32_16x16x32_bf16 v[38:41], v[210:213], v[154:157], v[38:41]
	v_mfma_f32_16x16x32_bf16 v[34:37], v[218:221], v[154:157], v[34:37]
	v_mfma_f32_16x16x32_bf16 v[22:25], v[210:213], v[174:177], v[22:25]
	v_mfma_f32_16x16x32_bf16 v[18:21], v[218:221], v[174:177], v[18:21]
	v_mfma_f32_16x16x32_bf16 v[6:9], v[210:213], v[188:191], v[6:9]
	v_mfma_f32_16x16x32_bf16 v[2:5], v[218:221], v[188:191], v[2:5]
	v_mfma_f32_16x16x32_bf16 v[54:57], v[214:217], v[150:153], v[54:57]
	v_mfma_f32_16x16x32_bf16 v[50:53], v[222:225], v[150:153], v[50:53]
	v_mfma_f32_16x16x32_bf16 v[38:41], v[214:217], v[170:173], v[38:41]
	v_mfma_f32_16x16x32_bf16 v[34:37], v[222:225], v[170:173], v[34:37]
	v_mfma_f32_16x16x32_bf16 v[22:25], v[214:217], v[184:187], v[22:25]
	v_mfma_f32_16x16x32_bf16 v[18:21], v[222:225], v[184:187], v[18:21]
	v_mfma_f32_16x16x32_bf16 v[6:9], v[214:217], v[206:209], v[6:9]
	v_mfma_f32_16x16x32_bf16 v[2:5], v[222:225], v[206:209], v[2:5]
	s_barrier
	s_setprio 0
	ds_read_b128 v[130:133], v253 offset:32768
	ds_read_b128 v[134:137], v253 offset:33792
	ds_read_b128 v[138:141], v253 offset:34816
	ds_read_b128 v[142:145], v253 offset:35840
	s_add_u32 s10, s10, 0x100000
	s_addc_u32 s11, s11, 0
	s_mov_b32 m0, s42
	ds_read_b128 v[146:149], v181 offset:32768
	ds_read_b128 v[150:153], v181 offset:33792
	ds_read_b128 v[154:157], v181 offset:34816
	ds_read_b128 v[170:173], v181 offset:35840
	ds_read_b128 v[174:177], v181 offset:36864
	ds_read_b128 v[184:187], v181 offset:37888
	ds_read_b128 v[188:191], v181 offset:38912
	ds_read_b128 v[206:209], v181 offset:39936
	global_load_lds_dwordx4 v164, s[10:11]
	s_mov_b32 m0, s54
	s_nop 0
	global_load_lds_dwordx4 v160, s[10:11]
	s_waitcnt lgkmcnt(8)
	s_setprio 1
	s_barrier
	s_waitcnt lgkmcnt(0)
	v_mfma_f32_16x16x32_bf16 v[126:129], v[130:133], v[146:149], v[126:129]
	v_mfma_f32_16x16x32_bf16 v[122:125], v[138:141], v[146:149], v[122:125]
	v_mfma_f32_16x16x32_bf16 v[110:113], v[130:133], v[154:157], v[110:113]
	v_mfma_f32_16x16x32_bf16 v[106:109], v[138:141], v[154:157], v[106:109]
	v_mfma_f32_16x16x32_bf16 v[94:97], v[130:133], v[174:177], v[94:97]
	v_mfma_f32_16x16x32_bf16 v[90:93], v[138:141], v[174:177], v[90:93]
	v_mfma_f32_16x16x32_bf16 v[78:81], v[130:133], v[188:191], v[78:81]
	v_mfma_f32_16x16x32_bf16 v[74:77], v[138:141], v[188:191], v[74:77]
	v_mfma_f32_16x16x32_bf16 v[126:129], v[134:137], v[150:153], v[126:129]
	v_mfma_f32_16x16x32_bf16 v[122:125], v[142:145], v[150:153], v[122:125]
	v_mfma_f32_16x16x32_bf16 v[110:113], v[134:137], v[170:173], v[110:113]
	v_mfma_f32_16x16x32_bf16 v[106:109], v[142:145], v[170:173], v[106:109]
	v_mfma_f32_16x16x32_bf16 v[94:97], v[134:137], v[184:187], v[94:97]
	v_mfma_f32_16x16x32_bf16 v[90:93], v[142:145], v[184:187], v[90:93]
	v_mfma_f32_16x16x32_bf16 v[78:81], v[134:137], v[206:209], v[78:81]
	v_mfma_f32_16x16x32_bf16 v[74:77], v[142:145], v[206:209], v[74:77]
	s_barrier
	s_setprio 0
	s_mov_b32 m0, s55
	ds_read_b128 v[210:213], v253 offset:49152
	ds_read_b128 v[214:217], v253 offset:50176
	v_lshl_add_u64 v[178:179], v[178:179], 0, s[76:77]
	ds_read_b128 v[218:221], v253 offset:51200
	ds_read_b128 v[222:225], v253 offset:52224
	global_load_lds_dwordx4 v[178:179], off
	v_lshl_add_u64 v[178:179], v[192:193], 0, s[76:77]
	s_mov_b32 m0, s56
	s_nop 0
	global_load_lds_dwordx4 v[178:179], off
	s_setprio 1
	s_barrier
	s_waitcnt lgkmcnt(0)
	v_mfma_f32_16x16x32_bf16 v[118:121], v[210:213], v[146:149], v[118:121]
	v_mfma_f32_16x16x32_bf16 v[114:117], v[218:221], v[146:149], v[114:117]
	v_mfma_f32_16x16x32_bf16 v[102:105], v[210:213], v[154:157], v[102:105]
	v_mfma_f32_16x16x32_bf16 v[98:101], v[218:221], v[154:157], v[98:101]
	v_mfma_f32_16x16x32_bf16 v[86:89], v[210:213], v[174:177], v[86:89]
	v_mfma_f32_16x16x32_bf16 v[82:85], v[218:221], v[174:177], v[82:85]
	v_mfma_f32_16x16x32_bf16 v[70:73], v[210:213], v[188:191], v[70:73]
	v_mfma_f32_16x16x32_bf16 v[66:69], v[218:221], v[188:191], v[66:69]
	v_mfma_f32_16x16x32_bf16 v[118:121], v[214:217], v[150:153], v[118:121]
	v_mfma_f32_16x16x32_bf16 v[114:117], v[222:225], v[150:153], v[114:117]
	v_mfma_f32_16x16x32_bf16 v[102:105], v[214:217], v[170:173], v[102:105]
	v_mfma_f32_16x16x32_bf16 v[98:101], v[222:225], v[170:173], v[98:101]
	v_mfma_f32_16x16x32_bf16 v[86:89], v[214:217], v[184:187], v[86:89]
	v_mfma_f32_16x16x32_bf16 v[82:85], v[222:225], v[184:187], v[82:85]
	s_mov_b32 m0, s57
	v_mfma_f32_16x16x32_bf16 v[70:73], v[214:217], v[206:209], v[70:73]
	v_lshl_add_u64 v[178:179], v[226:227], 0, s[76:77]
	v_mfma_f32_16x16x32_bf16 v[66:69], v[222:225], v[206:209], v[66:69]
	s_barrier
	s_setprio 0
	ds_read_b128 v[146:149], v181 offset:49152
	ds_read_b128 v[150:153], v181 offset:50176
	ds_read_b128 v[154:157], v181 offset:51200
	ds_read_b128 v[170:173], v181 offset:52224
	ds_read_b128 v[174:177], v181 offset:53248
	ds_read_b128 v[184:187], v181 offset:54272
	ds_read_b128 v[188:191], v181 offset:55296
	ds_read_b128 v[206:209], v181 offset:56320
	global_load_lds_dwordx4 v[178:179], off
	v_lshl_add_u64 v[178:179], v[228:229], 0, s[76:77]
	s_mov_b32 m0, s58
	s_nop 0
	global_load_lds_dwordx4 v[178:179], off
	s_setprio 1
	s_barrier
	s_waitcnt lgkmcnt(0)
	v_mfma_f32_16x16x32_bf16 v[62:65], v[130:133], v[146:149], v[62:65]
	v_mfma_f32_16x16x32_bf16 v[58:61], v[138:141], v[146:149], v[58:61]
	v_mfma_f32_16x16x32_bf16 v[46:49], v[130:133], v[154:157], v[46:49]
	v_mfma_f32_16x16x32_bf16 v[42:45], v[138:141], v[154:157], v[42:45]
	v_mfma_f32_16x16x32_bf16 v[30:33], v[130:133], v[174:177], v[30:33]
	v_mfma_f32_16x16x32_bf16 v[26:29], v[138:141], v[174:177], v[26:29]
	v_mfma_f32_16x16x32_bf16 v[14:17], v[130:133], v[188:191], v[14:17]
	v_mfma_f32_16x16x32_bf16 v[10:13], v[138:141], v[188:191], v[10:13]
	v_mfma_f32_16x16x32_bf16 v[62:65], v[134:137], v[150:153], v[62:65]
	v_mfma_f32_16x16x32_bf16 v[58:61], v[142:145], v[150:153], v[58:61]
	v_mfma_f32_16x16x32_bf16 v[46:49], v[134:137], v[170:173], v[46:49]
	v_mfma_f32_16x16x32_bf16 v[42:45], v[142:145], v[170:173], v[42:45]
	v_mfma_f32_16x16x32_bf16 v[30:33], v[134:137], v[184:187], v[30:33]
	v_mfma_f32_16x16x32_bf16 v[26:29], v[142:145], v[184:187], v[26:29]
	v_mfma_f32_16x16x32_bf16 v[14:17], v[134:137], v[206:209], v[14:17]
	v_mfma_f32_16x16x32_bf16 v[10:13], v[142:145], v[206:209], v[10:13]
	s_barrier
	s_setprio 0
	s_add_u32 s8, s8, 0x100080
	s_addc_u32 s9, s9, 0
	s_mov_b32 m0, s59
	s_nop 0
	global_load_lds_dwordx4 v162, s[8:9]
	s_mov_b32 m0, s67
	s_nop 0
	global_load_lds_dwordx4 v158, s[8:9]
	s_waitcnt vmcnt(6)
	s_setprio 1
	s_barrier
	v_mfma_f32_16x16x32_bf16 v[54:57], v[210:213], v[146:149], v[54:57]
	v_mfma_f32_16x16x32_bf16 v[50:53], v[218:221], v[146:149], v[50:53]
	v_mfma_f32_16x16x32_bf16 v[38:41], v[210:213], v[154:157], v[38:41]
	v_mfma_f32_16x16x32_bf16 v[34:37], v[218:221], v[154:157], v[34:37]
	v_mfma_f32_16x16x32_bf16 v[22:25], v[210:213], v[174:177], v[22:25]
	v_mfma_f32_16x16x32_bf16 v[18:21], v[218:221], v[174:177], v[18:21]
	v_mfma_f32_16x16x32_bf16 v[6:9], v[210:213], v[188:191], v[6:9]
	v_mfma_f32_16x16x32_bf16 v[2:5], v[218:221], v[188:191], v[2:5]
	s_add_i32 s79, s79, 2
	s_add_u32 s6, s6, 0x100
	s_addc_u32 s7, s7, 0
	s_add_u32 s1, s1, 0x100
	s_addc_u32 s78, s78, 0
	s_cmp_gt_u32 s79, 61
	v_mfma_f32_16x16x32_bf16 v[54:57], v[214:217], v[150:153], v[54:57]
	v_mfma_f32_16x16x32_bf16 v[50:53], v[222:225], v[150:153], v[50:53]
	v_mfma_f32_16x16x32_bf16 v[38:41], v[214:217], v[170:173], v[38:41]
	v_mfma_f32_16x16x32_bf16 v[34:37], v[222:225], v[170:173], v[34:37]
	v_mfma_f32_16x16x32_bf16 v[22:25], v[214:217], v[184:187], v[22:25]
	v_mfma_f32_16x16x32_bf16 v[18:21], v[222:225], v[184:187], v[18:21]
	v_mfma_f32_16x16x32_bf16 v[6:9], v[214:217], v[206:209], v[6:9]
	v_mfma_f32_16x16x32_bf16 v[2:5], v[222:225], v[206:209], v[2:5]
	s_barrier
	s_setprio 0
	s_cbranch_scc0 .LBB0_255
	s_lshl_b32 s1, s28, 9
	s_and_b32 s1, s1, 0xfffff800
	s_lshl_b32 s6, s29, 8
	s_add_i32 s1, s1, s6
	v_add_u32_e32 v172, s1, v180
	s_lshl_b32 s1, s28, 8
	s_and_b32 s1, s1, 0x300
	v_or_b32_e32 v132, s1, v183
	v_mov_b64_e32 v[170:171], s[50:51]
	v_mad_i64_i32 v[130:131], s[6:7], v172, s37, v[170:171]
	v_lshlrev_b32_e32 v194, 1, v132
	v_lshl_add_u64 v[130:131], v[130:131], 0, v[194:195]
	v_lshl_add_u64 v[132:133], v[130:131], 0, s[84:85]
	v_add_co_u32_e32 v130, vcc, s16, v130
	v_or_b32_e32 v178, 16, v172
	s_nop 0
	v_addc_co_u32_e32 v131, vcc, 0, v131, vcc
	global_load_dwordx4 v[184:187], v[130:131], off offset:2048
	global_load_dwordx4 v[154:157], v[132:133], off offset:256
	v_mad_i64_i32 v[130:131], s[6:7], v178, s37, v[170:171]
	v_lshl_add_u64 v[130:131], v[130:131], 0, v[194:195]
	v_lshl_add_u64 v[132:133], v[130:131], 0, s[84:85]
	v_add_co_u32_e32 v130, vcc, s16, v130
	v_or_b32_e32 v176, 32, v172
	s_nop 0
	v_addc_co_u32_e32 v131, vcc, 0, v131, vcc
	global_load_dwordx4 v[150:153], v[130:131], off offset:2048
	global_load_dwordx4 v[146:149], v[132:133], off offset:256
	v_mad_i64_i32 v[130:131], s[6:7], v176, s37, v[170:171]
	v_lshl_add_u64 v[130:131], v[130:131], 0, v[194:195]
	v_lshl_add_u64 v[132:133], v[130:131], 0, s[84:85]
	v_add_co_u32_e32 v130, vcc, s16, v130
	v_or_b32_e32 v174, 48, v172
	s_nop 0
	v_addc_co_u32_e32 v131, vcc, 0, v131, vcc
	global_load_dwordx4 v[142:145], v[130:131], off offset:2048
	global_load_dwordx4 v[138:141], v[132:133], off offset:256
	v_mad_i64_i32 v[130:131], s[6:7], v174, s37, v[170:171]
	v_lshl_add_u64 v[130:131], v[130:131], 0, v[194:195]
	v_lshl_add_u64 v[132:133], v[130:131], 0, s[84:85]
	v_add_co_u32_e32 v130, vcc, s16, v130
	v_pk_mul_f32 v[126:127], v[126:127], s[72:73] op_sel_hi:[1,0]
	s_nop 0
	v_addc_co_u32_e32 v131, vcc, 0, v131, vcc
	global_load_dwordx4 v[134:137], v[130:131], off offset:2048
	s_nop 0
	global_load_dwordx4 v[130:133], v[132:133], off offset:256
	v_pk_mul_f32 v[190:191], v[124:125], s[72:73] op_sel_hi:[1,0]
	v_pk_mul_f32 v[128:129], v[128:129], s[72:73] op_sel_hi:[1,0]
	v_pk_mul_f32 v[122:123], v[122:123], s[72:73] op_sel_hi:[1,0]
	v_ashrrev_i32_e32 v173, 31, v172
	v_lshlrev_b64 v[188:189], 11, v[172:173]
	v_pk_mul_f32 v[118:119], v[118:119], s[72:73] op_sel_hi:[1,0]
	v_pk_mul_f32 v[120:121], v[120:121], s[72:73] op_sel_hi:[1,0]
	v_pk_mul_f32 v[110:111], v[110:111], s[72:73] op_sel_hi:[1,0]
	v_pk_mul_f32 v[112:113], v[112:113], s[72:73] op_sel_hi:[1,0]
	v_ashrrev_i32_e32 v179, 31, v178
	v_pk_mul_f32 v[102:103], v[102:103], s[72:73] op_sel_hi:[1,0]
	v_pk_mul_f32 v[104:105], v[104:105], s[72:73] op_sel_hi:[1,0]
	v_pk_mul_f32 v[94:95], v[94:95], s[72:73] op_sel_hi:[1,0]
	v_pk_mul_f32 v[96:97], v[96:97], s[72:73] op_sel_hi:[1,0]
	v_ashrrev_i32_e32 v177, 31, v176
	v_pk_mul_f32 v[86:87], v[86:87], s[72:73] op_sel_hi:[1,0]
	v_pk_mul_f32 v[88:89], v[88:89], s[72:73] op_sel_hi:[1,0]
	v_pk_mul_f32 v[78:79], v[78:79], s[72:73] op_sel_hi:[1,0]
	v_pk_mul_f32 v[80:81], v[80:81], s[72:73] op_sel_hi:[1,0]
	v_ashrrev_i32_e32 v175, 31, v174
	v_pk_mul_f32 v[70:71], v[70:71], s[72:73] op_sel_hi:[1,0]
	v_pk_mul_f32 v[72:73], v[72:73], s[72:73] op_sel_hi:[1,0]
	s_waitcnt vmcnt(0)
	v_lshlrev_b32_e32 v124, 16, v184
	v_and_b32_e32 v125, 0xffff0000, v184
	v_mul_f32_e32 v124, v126, v124
	v_mul_f32_e32 v125, v127, v125
	v_cvt_pk_bf16_f32 v124, v124, v125
	v_lshlrev_b32_e32 v125, 16, v185
	v_and_b32_e32 v126, 0xffff0000, v185
	v_mul_f32_e32 v125, v128, v125
	v_mul_f32_e32 v126, v129, v126
	v_cvt_pk_bf16_f32 v125, v125, v126
	v_lshlrev_b32_e32 v126, 16, v186
	v_mul_f32_e32 v122, v122, v126
	v_and_b32_e32 v126, 0xffff0000, v186
	v_mul_f32_e32 v123, v123, v126
	v_cvt_pk_bf16_f32 v126, v122, v123
	v_lshlrev_b32_e32 v122, 16, v187
	v_and_b32_e32 v123, 0xffff0000, v187
	v_mul_f32_e32 v122, v190, v122
	v_mul_f32_e32 v123, v191, v123
	v_cvt_pk_bf16_f32 v127, v122, v123
	v_lshl_add_u64 v[122:123], s[74:75], 0, v[188:189]
	v_lshl_add_u64 v[122:123], v[122:123], 0, v[194:195]
	global_store_dwordx4 v[122:123], v[124:127], off
	s_nop 1
	v_pk_mul_f32 v[124:125], v[116:117], s[72:73] op_sel_hi:[1,0]
	v_pk_mul_f32 v[116:117], v[114:115], s[72:73] op_sel_hi:[1,0]
	v_lshlrev_b32_e32 v114, 16, v154
	v_and_b32_e32 v115, 0xffff0000, v154
	v_mul_f32_e32 v114, v118, v114
	v_mul_f32_e32 v115, v119, v115
	v_cvt_pk_bf16_f32 v114, v114, v115
	v_lshlrev_b32_e32 v115, 16, v155
	v_and_b32_e32 v118, 0xffff0000, v155
	v_mul_f32_e32 v115, v120, v115
	v_mul_f32_e32 v118, v121, v118
	v_cvt_pk_bf16_f32 v115, v115, v118
	v_lshlrev_b32_e32 v118, 16, v156
	v_mul_f32_e32 v116, v116, v118
	v_and_b32_e32 v118, 0xffff0000, v156
	v_mul_f32_e32 v117, v117, v118
	v_cvt_pk_bf16_f32 v116, v116, v117
	v_lshlrev_b32_e32 v117, 16, v157
	v_mul_f32_e32 v117, v124, v117
	v_and_b32_e32 v118, 0xffff0000, v157
	v_mul_f32_e32 v118, v125, v118
	v_cvt_pk_bf16_f32 v117, v117, v118
	global_store_dwordx4 v[122:123], v[114:117], off offset:256
	s_nop 1
	v_pk_mul_f32 v[116:117], v[108:109], s[72:73] op_sel_hi:[1,0]
	v_pk_mul_f32 v[108:109], v[106:107], s[72:73] op_sel_hi:[1,0]
	v_lshlrev_b32_e32 v106, 16, v150
	v_and_b32_e32 v107, 0xffff0000, v150
	v_mul_f32_e32 v106, v110, v106
	v_mul_f32_e32 v107, v111, v107
	v_cvt_pk_bf16_f32 v106, v106, v107
	v_lshlrev_b32_e32 v107, 16, v151
	v_and_b32_e32 v110, 0xffff0000, v151
	v_mul_f32_e32 v107, v112, v107
	v_mul_f32_e32 v110, v113, v110
	v_cvt_pk_bf16_f32 v107, v107, v110
	v_lshlrev_b32_e32 v110, 16, v152
	v_mul_f32_e32 v108, v108, v110
	v_and_b32_e32 v110, 0xffff0000, v152
	v_mul_f32_e32 v109, v109, v110
	v_cvt_pk_bf16_f32 v108, v108, v109
	v_lshlrev_b32_e32 v109, 16, v153
	v_and_b32_e32 v110, 0xffff0000, v153
	v_lshlrev_b64 v[114:115], 11, v[178:179]
	v_mul_f32_e32 v109, v116, v109
	v_mul_f32_e32 v110, v117, v110
	v_cvt_pk_bf16_f32 v109, v109, v110
	v_lshl_add_u64 v[110:111], s[74:75], 0, v[114:115]
	v_lshl_add_u64 v[110:111], v[110:111], 0, v[194:195]
	global_store_dwordx4 v[110:111], v[106:109], off
	s_nop 1
	v_pk_mul_f32 v[106:107], v[100:101], s[72:73] op_sel_hi:[1,0]
	v_pk_mul_f32 v[100:101], v[98:99], s[72:73] op_sel_hi:[1,0]
	v_lshlrev_b32_e32 v98, 16, v146
	v_and_b32_e32 v99, 0xffff0000, v146
	v_mul_f32_e32 v98, v102, v98
	v_mul_f32_e32 v99, v103, v99
	v_cvt_pk_bf16_f32 v98, v98, v99
	v_lshlrev_b32_e32 v99, 16, v147
	v_and_b32_e32 v102, 0xffff0000, v147
	v_mul_f32_e32 v99, v104, v99
	v_mul_f32_e32 v102, v105, v102
	v_cvt_pk_bf16_f32 v99, v99, v102
	v_lshlrev_b32_e32 v102, 16, v148
	v_mul_f32_e32 v100, v100, v102
	v_and_b32_e32 v102, 0xffff0000, v148
	v_mul_f32_e32 v101, v101, v102
	v_cvt_pk_bf16_f32 v100, v100, v101
	v_lshlrev_b32_e32 v101, 16, v149
	v_mul_f32_e32 v101, v106, v101
	v_and_b32_e32 v102, 0xffff0000, v149
	v_mul_f32_e32 v102, v107, v102
	v_cvt_pk_bf16_f32 v101, v101, v102
	global_store_dwordx4 v[110:111], v[98:101], off offset:256
	s_nop 1
	v_pk_mul_f32 v[100:101], v[92:93], s[72:73] op_sel_hi:[1,0]
	v_pk_mul_f32 v[92:93], v[90:91], s[72:73] op_sel_hi:[1,0]
	v_lshlrev_b32_e32 v90, 16, v142
	v_and_b32_e32 v91, 0xffff0000, v142
	v_mul_f32_e32 v90, v94, v90
	v_mul_f32_e32 v91, v95, v91
	v_cvt_pk_bf16_f32 v90, v90, v91
	v_lshlrev_b32_e32 v91, 16, v143
	v_and_b32_e32 v94, 0xffff0000, v143
	v_mul_f32_e32 v91, v96, v91
	v_mul_f32_e32 v94, v97, v94
	v_cvt_pk_bf16_f32 v91, v91, v94
	v_lshlrev_b32_e32 v94, 16, v144
	v_mul_f32_e32 v92, v92, v94
	v_and_b32_e32 v94, 0xffff0000, v144
	v_mul_f32_e32 v93, v93, v94
	v_cvt_pk_bf16_f32 v92, v92, v93
	v_lshlrev_b32_e32 v93, 16, v145
	v_and_b32_e32 v94, 0xffff0000, v145
	v_lshlrev_b64 v[98:99], 11, v[176:177]
	v_mul_f32_e32 v93, v100, v93
	v_mul_f32_e32 v94, v101, v94
	v_cvt_pk_bf16_f32 v93, v93, v94
	v_lshl_add_u64 v[94:95], s[74:75], 0, v[98:99]
	v_lshl_add_u64 v[94:95], v[94:95], 0, v[194:195]
	global_store_dwordx4 v[94:95], v[90:93], off
	s_nop 1
	v_pk_mul_f32 v[90:91], v[84:85], s[72:73] op_sel_hi:[1,0]
	v_pk_mul_f32 v[84:85], v[82:83], s[72:73] op_sel_hi:[1,0]
	v_lshlrev_b32_e32 v82, 16, v138
	v_and_b32_e32 v83, 0xffff0000, v138
	v_mul_f32_e32 v82, v86, v82
	v_mul_f32_e32 v83, v87, v83
	v_cvt_pk_bf16_f32 v82, v82, v83
	v_lshlrev_b32_e32 v83, 16, v139
	v_and_b32_e32 v86, 0xffff0000, v139
	v_mul_f32_e32 v83, v88, v83
	v_mul_f32_e32 v86, v89, v86
	v_cvt_pk_bf16_f32 v83, v83, v86
	v_lshlrev_b32_e32 v86, 16, v140
	v_mul_f32_e32 v84, v84, v86
	v_and_b32_e32 v86, 0xffff0000, v140
	v_mul_f32_e32 v85, v85, v86
	v_cvt_pk_bf16_f32 v84, v84, v85
	v_lshlrev_b32_e32 v85, 16, v141
	v_mul_f32_e32 v85, v90, v85
	v_and_b32_e32 v86, 0xffff0000, v141
	v_mul_f32_e32 v86, v91, v86
	v_cvt_pk_bf16_f32 v85, v85, v86
	global_store_dwordx4 v[94:95], v[82:85], off offset:256
	s_nop 1
	v_pk_mul_f32 v[84:85], v[76:77], s[72:73] op_sel_hi:[1,0]
	v_pk_mul_f32 v[76:77], v[74:75], s[72:73] op_sel_hi:[1,0]
	v_lshlrev_b32_e32 v74, 16, v134
	v_and_b32_e32 v75, 0xffff0000, v134
	v_mul_f32_e32 v74, v78, v74
	v_mul_f32_e32 v75, v79, v75
	v_cvt_pk_bf16_f32 v74, v74, v75
	v_lshlrev_b32_e32 v75, 16, v135
	v_and_b32_e32 v78, 0xffff0000, v135
	v_mul_f32_e32 v75, v80, v75
	v_mul_f32_e32 v78, v81, v78
	v_cvt_pk_bf16_f32 v75, v75, v78
	v_lshlrev_b32_e32 v78, 16, v136
	v_mul_f32_e32 v76, v76, v78
	v_and_b32_e32 v78, 0xffff0000, v136
	v_mul_f32_e32 v77, v77, v78
	v_cvt_pk_bf16_f32 v76, v76, v77
	v_lshlrev_b32_e32 v77, 16, v137
	v_and_b32_e32 v78, 0xffff0000, v137
	v_lshlrev_b64 v[82:83], 11, v[174:175]
	v_mul_f32_e32 v77, v84, v77
	v_mul_f32_e32 v78, v85, v78
	v_cvt_pk_bf16_f32 v77, v77, v78
	v_lshl_add_u64 v[78:79], s[74:75], 0, v[82:83]
	v_lshl_add_u64 v[78:79], v[78:79], 0, v[194:195]
	global_store_dwordx4 v[78:79], v[74:77], off
	s_nop 1
	v_pk_mul_f32 v[74:75], v[68:69], s[72:73] op_sel_hi:[1,0]
	v_pk_mul_f32 v[68:69], v[66:67], s[72:73] op_sel_hi:[1,0]
	v_lshlrev_b32_e32 v66, 16, v130
	v_and_b32_e32 v67, 0xffff0000, v130
	v_mul_f32_e32 v66, v70, v66
	v_mul_f32_e32 v67, v71, v67
	v_cvt_pk_bf16_f32 v66, v66, v67
	v_lshlrev_b32_e32 v67, 16, v131
	v_and_b32_e32 v70, 0xffff0000, v131
	v_mul_f32_e32 v67, v72, v67
	v_mul_f32_e32 v70, v73, v70
	v_cvt_pk_bf16_f32 v67, v67, v70
	v_lshlrev_b32_e32 v70, 16, v132
	v_mul_f32_e32 v68, v68, v70
	v_and_b32_e32 v70, 0xffff0000, v132
	v_mul_f32_e32 v69, v69, v70
	v_cvt_pk_bf16_f32 v68, v68, v69
	v_lshlrev_b32_e32 v69, 16, v133
	v_mul_f32_e32 v69, v74, v69
	v_and_b32_e32 v70, 0xffff0000, v133
	v_mul_f32_e32 v70, v75, v70
	v_cvt_pk_bf16_f32 v69, v69, v70
	global_store_dwordx4 v[78:79], v[66:69], off offset:256
	v_add_u32_e32 v78, 0x80, v172
	s_nop 0
	v_mad_i64_i32 v[66:67], s[6:7], v78, s37, v[170:171]
	v_lshl_add_u64 v[66:67], v[66:67], 0, v[194:195]
	v_add_co_u32_e32 v68, vcc, s16, v66
	v_add_u32_e32 v86, 0x90, v172
	s_nop 0
	v_addc_co_u32_e32 v69, vcc, 0, v67, vcc
	global_load_dwordx4 v[70:73], v[68:69], off offset:2048
	v_lshl_add_u64 v[66:67], v[66:67], 0, s[84:85]
	global_load_dwordx4 v[74:77], v[66:67], off offset:256
	v_pk_mul_f32 v[96:97], v[56:57], s[72:73] op_sel_hi:[1,0]
	v_mad_i64_i32 v[56:57], s[6:7], v86, s37, v[170:171]
	v_lshl_add_u64 v[56:57], v[56:57], 0, v[194:195]
	v_pk_mul_f32 v[94:95], v[58:59], s[72:73] op_sel_hi:[1,0]
	v_add_co_u32_e32 v58, vcc, s16, v56
	v_pk_mul_f32 v[92:93], v[60:61], s[72:73] op_sel_hi:[1,0]
	s_nop 0
	v_addc_co_u32_e32 v59, vcc, 0, v57, vcc
	global_load_dwordx4 v[58:61], v[58:59], off offset:2048
	v_add_u32_e32 v68, 0xa0, v172
	v_pk_mul_f32 v[102:103], v[50:51], s[72:73] op_sel_hi:[1,0]
	v_mad_i64_i32 v[50:51], s[6:7], v68, s37, v[170:171]
	v_add_u32_e32 v66, 0xb0, v172
	v_lshl_add_u64 v[50:51], v[50:51], 0, v[194:195]
	v_pk_mul_f32 v[100:101], v[52:53], s[72:73] op_sel_hi:[1,0]
	v_mad_i64_i32 v[52:53], s[6:7], v66, s37, v[170:171]
	v_lshl_add_u64 v[82:83], v[50:51], 0, s[84:85]
	v_add_co_u32_e32 v50, vcc, s16, v50
	v_lshl_add_u64 v[52:53], v[52:53], 0, v[194:195]
	s_nop 0
	v_addc_co_u32_e32 v51, vcc, 0, v51, vcc
	v_ashrrev_i32_e32 v79, 31, v78
	v_lshl_add_u64 v[104:105], v[52:53], 0, s[84:85]
	v_add_co_u32_e32 v52, vcc, s16, v52
	v_pk_mul_f32 v[98:99], v[54:55], s[72:73] op_sel_hi:[1,0]
	v_lshlrev_b64 v[54:55], 11, v[78:79]
	v_lshl_add_u64 v[56:57], v[56:57], 0, s[84:85]
	v_addc_co_u32_e32 v53, vcc, 0, v53, vcc
	v_pk_mul_f32 v[88:89], v[64:65], s[72:73] op_sel_hi:[1,0]
	v_pk_mul_f32 v[90:91], v[62:63], s[72:73] op_sel_hi:[1,0]
	v_lshl_add_u64 v[106:107], s[74:75], 0, v[54:55]
	global_load_dwordx4 v[62:65], v[56:57], off offset:256
	global_load_dwordx4 v[78:81], v[50:51], off offset:2048
	s_nop 0
	global_load_dwordx4 v[82:85], v[82:83], off offset:256
	s_nop 0
	global_load_dwordx4 v[54:57], v[52:53], off offset:2048
	s_nop 0
	global_load_dwordx4 v[50:53], v[104:105], off offset:256
	v_lshl_add_u64 v[104:105], v[106:107], 0, v[194:195]
	v_pk_mul_f32 v[46:47], v[46:47], s[72:73] op_sel_hi:[1,0]
	v_pk_mul_f32 v[48:49], v[48:49], s[72:73] op_sel_hi:[1,0]
	v_ashrrev_i32_e32 v87, 31, v86
	v_pk_mul_f32 v[38:39], v[38:39], s[72:73] op_sel_hi:[1,0]
	v_pk_mul_f32 v[40:41], v[40:41], s[72:73] op_sel_hi:[1,0]
	v_pk_mul_f32 v[30:31], v[30:31], s[72:73] op_sel_hi:[1,0]
	v_pk_mul_f32 v[32:33], v[32:33], s[72:73] op_sel_hi:[1,0]
	v_ashrrev_i32_e32 v69, 31, v68
	v_pk_mul_f32 v[22:23], v[22:23], s[72:73] op_sel_hi:[1,0]
	v_pk_mul_f32 v[24:25], v[24:25], s[72:73] op_sel_hi:[1,0]
	v_pk_mul_f32 v[14:15], v[14:15], s[72:73] op_sel_hi:[1,0]
	v_pk_mul_f32 v[16:17], v[16:17], s[72:73] op_sel_hi:[1,0]
	v_ashrrev_i32_e32 v67, 31, v66
	v_pk_mul_f32 v[6:7], v[6:7], s[72:73] op_sel_hi:[1,0]
	v_pk_mul_f32 v[8:9], v[8:9], s[72:73] op_sel_hi:[1,0]
	s_waitcnt vmcnt(0)
	v_lshlrev_b32_e32 v106, 16, v70
	v_and_b32_e32 v70, 0xffff0000, v70
	v_lshlrev_b32_e32 v107, 16, v71
	v_and_b32_e32 v71, 0xffff0000, v71
	v_lshlrev_b32_e32 v108, 16, v72
	v_and_b32_e32 v72, 0xffff0000, v72
	v_lshlrev_b32_e32 v109, 16, v73
	v_and_b32_e32 v73, 0xffff0000, v73
	v_mul_f32_e32 v70, v91, v70
	v_mul_f32_e32 v71, v89, v71
	v_mul_f32_e32 v72, v95, v72
	v_mul_f32_e32 v73, v93, v73
	v_mul_f32_e32 v90, v90, v106
	v_mul_f32_e32 v88, v88, v107
	v_mul_f32_e32 v89, v94, v108
	v_mul_f32_e32 v91, v92, v109
	v_cvt_pk_bf16_f32 v70, v90, v70
	v_cvt_pk_bf16_f32 v71, v88, v71
	v_cvt_pk_bf16_f32 v72, v89, v72
	v_cvt_pk_bf16_f32 v73, v91, v73
	v_lshlrev_b32_e32 v111, 16, v75
	v_and_b32_e32 v75, 0xffff0000, v75
	global_store_dwordx4 v[104:105], v[70:73], off
	v_lshlrev_b32_e32 v110, 16, v74
	v_and_b32_e32 v74, 0xffff0000, v74
	v_lshlrev_b32_e32 v72, 16, v76
	v_and_b32_e32 v73, 0xffff0000, v76
	v_mul_f32_e32 v71, v97, v75
	v_mul_f32_e32 v72, v102, v72
	v_mul_f32_e32 v73, v103, v73
	v_mul_f32_e32 v92, v98, v110
	v_mul_f32_e32 v74, v99, v74
	v_mul_f32_e32 v93, v96, v111
	v_cvt_pk_bf16_f32 v70, v92, v74
	v_cvt_pk_bf16_f32 v71, v93, v71
	v_cvt_pk_bf16_f32 v72, v72, v73
	v_lshlrev_b32_e32 v73, 16, v77
	v_mul_f32_e32 v73, v100, v73
	v_and_b32_e32 v74, 0xffff0000, v77
	v_mul_f32_e32 v74, v101, v74
	v_cvt_pk_bf16_f32 v73, v73, v74
	global_store_dwordx4 v[104:105], v[70:73], off offset:256
	s_nop 1
	v_pk_mul_f32 v[72:73], v[44:45], s[72:73] op_sel_hi:[1,0]
	v_pk_mul_f32 v[44:45], v[42:43], s[72:73] op_sel_hi:[1,0]
	v_lshlrev_b32_e32 v42, 16, v58
	v_and_b32_e32 v43, 0xffff0000, v58
	v_mul_f32_e32 v42, v46, v42
	v_mul_f32_e32 v43, v47, v43
	v_cvt_pk_bf16_f32 v42, v42, v43
	v_lshlrev_b32_e32 v43, 16, v59
	v_and_b32_e32 v46, 0xffff0000, v59
	v_mul_f32_e32 v43, v48, v43
	v_mul_f32_e32 v46, v49, v46
	v_cvt_pk_bf16_f32 v43, v43, v46
	v_lshlrev_b32_e32 v46, 16, v60
	v_mul_f32_e32 v44, v44, v46
	v_and_b32_e32 v46, 0xffff0000, v60
	v_mul_f32_e32 v45, v45, v46
	v_cvt_pk_bf16_f32 v44, v44, v45
	v_lshlrev_b32_e32 v45, 16, v61
	v_and_b32_e32 v46, 0xffff0000, v61
	v_lshlrev_b64 v[70:71], 11, v[86:87]
	v_mul_f32_e32 v45, v72, v45
	v_mul_f32_e32 v46, v73, v46
	v_cvt_pk_bf16_f32 v45, v45, v46
	v_lshl_add_u64 v[46:47], s[74:75], 0, v[70:71]
	v_lshl_add_u64 v[46:47], v[46:47], 0, v[194:195]
	global_store_dwordx4 v[46:47], v[42:45], off
	s_nop 1
	v_pk_mul_f32 v[42:43], v[36:37], s[72:73] op_sel_hi:[1,0]
	v_pk_mul_f32 v[36:37], v[34:35], s[72:73] op_sel_hi:[1,0]
	v_lshlrev_b32_e32 v34, 16, v62
	v_and_b32_e32 v35, 0xffff0000, v62
	v_mul_f32_e32 v34, v38, v34
	v_mul_f32_e32 v35, v39, v35
	v_cvt_pk_bf16_f32 v34, v34, v35
	v_lshlrev_b32_e32 v35, 16, v63
	v_and_b32_e32 v38, 0xffff0000, v63
	v_mul_f32_e32 v35, v40, v35
	v_mul_f32_e32 v38, v41, v38
	v_cvt_pk_bf16_f32 v35, v35, v38
	v_lshlrev_b32_e32 v38, 16, v64
	v_mul_f32_e32 v36, v36, v38
	v_and_b32_e32 v38, 0xffff0000, v64
	v_mul_f32_e32 v37, v37, v38
	v_cvt_pk_bf16_f32 v36, v36, v37
	v_lshlrev_b32_e32 v37, 16, v65
	v_mul_f32_e32 v37, v42, v37
	v_and_b32_e32 v38, 0xffff0000, v65
	v_mul_f32_e32 v38, v43, v38
	v_cvt_pk_bf16_f32 v37, v37, v38
	global_store_dwordx4 v[46:47], v[34:37], off offset:256
	s_nop 1
	v_pk_mul_f32 v[36:37], v[28:29], s[72:73] op_sel_hi:[1,0]
	v_pk_mul_f32 v[28:29], v[26:27], s[72:73] op_sel_hi:[1,0]
	v_lshlrev_b32_e32 v26, 16, v78
	v_and_b32_e32 v27, 0xffff0000, v78
	v_mul_f32_e32 v26, v30, v26
	v_mul_f32_e32 v27, v31, v27
	v_cvt_pk_bf16_f32 v26, v26, v27
	v_lshlrev_b32_e32 v27, 16, v79
	v_and_b32_e32 v30, 0xffff0000, v79
	v_mul_f32_e32 v27, v32, v27
	v_mul_f32_e32 v30, v33, v30
	v_cvt_pk_bf16_f32 v27, v27, v30
	v_lshlrev_b32_e32 v30, 16, v80
	v_mul_f32_e32 v28, v28, v30
	v_and_b32_e32 v30, 0xffff0000, v80
	v_mul_f32_e32 v29, v29, v30
	v_cvt_pk_bf16_f32 v28, v28, v29
	v_lshlrev_b32_e32 v29, 16, v81
	v_and_b32_e32 v30, 0xffff0000, v81
	v_lshlrev_b64 v[34:35], 11, v[68:69]
	v_mul_f32_e32 v29, v36, v29
	v_mul_f32_e32 v30, v37, v30
	v_cvt_pk_bf16_f32 v29, v29, v30
	v_lshl_add_u64 v[30:31], s[74:75], 0, v[34:35]
	v_lshl_add_u64 v[30:31], v[30:31], 0, v[194:195]
	global_store_dwordx4 v[30:31], v[26:29], off
	s_nop 1
	v_pk_mul_f32 v[26:27], v[20:21], s[72:73] op_sel_hi:[1,0]
	v_pk_mul_f32 v[20:21], v[18:19], s[72:73] op_sel_hi:[1,0]
	v_lshlrev_b32_e32 v18, 16, v82
	v_and_b32_e32 v19, 0xffff0000, v82
	v_mul_f32_e32 v18, v22, v18
	v_mul_f32_e32 v19, v23, v19
	v_cvt_pk_bf16_f32 v18, v18, v19
	v_lshlrev_b32_e32 v19, 16, v83
	v_and_b32_e32 v22, 0xffff0000, v83
	v_mul_f32_e32 v19, v24, v19
	v_mul_f32_e32 v22, v25, v22
	v_cvt_pk_bf16_f32 v19, v19, v22
	v_lshlrev_b32_e32 v22, 16, v84
	v_mul_f32_e32 v20, v20, v22
	v_and_b32_e32 v22, 0xffff0000, v84
	v_mul_f32_e32 v21, v21, v22
	v_cvt_pk_bf16_f32 v20, v20, v21
	v_lshlrev_b32_e32 v21, 16, v85
	v_mul_f32_e32 v21, v26, v21
	v_and_b32_e32 v22, 0xffff0000, v85
	v_mul_f32_e32 v22, v27, v22
	v_cvt_pk_bf16_f32 v21, v21, v22
	global_store_dwordx4 v[30:31], v[18:21], off offset:256
	s_nop 1
	v_pk_mul_f32 v[20:21], v[12:13], s[72:73] op_sel_hi:[1,0]
	v_pk_mul_f32 v[12:13], v[10:11], s[72:73] op_sel_hi:[1,0]
	v_lshlrev_b32_e32 v10, 16, v54
	v_and_b32_e32 v11, 0xffff0000, v54
	v_mul_f32_e32 v10, v14, v10
	v_mul_f32_e32 v11, v15, v11
	v_cvt_pk_bf16_f32 v10, v10, v11
	v_lshlrev_b32_e32 v11, 16, v55
	v_and_b32_e32 v14, 0xffff0000, v55
	v_mul_f32_e32 v11, v16, v11
	v_mul_f32_e32 v14, v17, v14
	v_cvt_pk_bf16_f32 v11, v11, v14
	v_lshlrev_b32_e32 v14, 16, v56
	v_mul_f32_e32 v12, v12, v14
	v_and_b32_e32 v14, 0xffff0000, v56
	v_mul_f32_e32 v13, v13, v14
	v_cvt_pk_bf16_f32 v12, v12, v13
	v_lshlrev_b32_e32 v13, 16, v57
	v_and_b32_e32 v14, 0xffff0000, v57
	v_lshlrev_b64 v[18:19], 11, v[66:67]
	v_mul_f32_e32 v13, v20, v13
	v_mul_f32_e32 v14, v21, v14
	v_cvt_pk_bf16_f32 v13, v13, v14
	v_lshl_add_u64 v[14:15], s[74:75], 0, v[18:19]
	v_lshl_add_u64 v[14:15], v[14:15], 0, v[194:195]
	global_store_dwordx4 v[14:15], v[10:13], off
	s_nop 1
	v_pk_mul_f32 v[10:11], v[4:5], s[72:73] op_sel_hi:[1,0]
	v_pk_mul_f32 v[4:5], v[2:3], s[72:73] op_sel_hi:[1,0]
	v_lshlrev_b32_e32 v2, 16, v50
	v_and_b32_e32 v3, 0xffff0000, v50
	v_mul_f32_e32 v2, v6, v2
	v_mul_f32_e32 v3, v7, v3
	v_cvt_pk_bf16_f32 v2, v2, v3
	v_lshlrev_b32_e32 v3, 16, v51
	v_and_b32_e32 v6, 0xffff0000, v51
	v_mul_f32_e32 v3, v8, v3
	v_mul_f32_e32 v6, v9, v6
	v_cvt_pk_bf16_f32 v3, v3, v6
	v_lshlrev_b32_e32 v6, 16, v52
	v_mul_f32_e32 v4, v4, v6
	v_and_b32_e32 v6, 0xffff0000, v52
	v_mul_f32_e32 v5, v5, v6
	v_cvt_pk_bf16_f32 v4, v4, v5
	v_lshlrev_b32_e32 v5, 16, v53
	v_mul_f32_e32 v5, v10, v5
	v_and_b32_e32 v6, 0xffff0000, v53
	v_mul_f32_e32 v6, v11, v6
	v_cvt_pk_bf16_f32 v5, v5, v6
	global_store_dwordx4 v[14:15], v[2:5], off offset:256
	s_and_b64 vcc, exec, s[62:63]
	s_mov_b32 s29, s71
	s_mov_b32 s28, s0
	s_mov_b64 s[8:9], s[60:61]
	s_mov_b64 s[6:7], s[52:53]
	s_cbranch_vccz .LBB0_252
	s_waitcnt vmcnt(0)
	v_readlane_b32 s28, v250, 12
	s_cmpk_gt_u32 s4, 0xff
	v_readlane_b32 s29, v250, 13
	s_mov_b32 s70, 0x800000
	s_cbranch_scc1 .LBB0_259
	s_barrier

.LBB0_368:
	v_add_u32_e32 v253, 0x10000, v201
	ds_read_b128 v[130:133], v253
	ds_read_b128 v[134:137], v253 offset:1024
	ds_read_b128 v[138:141], v253 offset:2048
	ds_read_b128 v[142:145], v253 offset:3072
	s_add_u32 s10, s8, 0xfffc0080
	s_addc_u32 s11, s9, -1
	s_cmp_eq_u32 s29, 12
	s_cselect_b32 s11, s81, s11
	s_cselect_b32 s10, s80, s10
	s_cselect_b32 s53, s83, s28
	s_cselect_b32 s52, s82, s7
	s_add_i32 m0, s34, 0xc000
	ds_read_b128 v[146:149], v199
	ds_read_b128 v[150:153], v199 offset:1024
	ds_read_b128 v[154:157], v199 offset:2048
	ds_read_b128 v[158:161], v199 offset:3072
	ds_read_b128 v[162:165], v199 offset:4096
	ds_read_b128 v[166:169], v199 offset:5120
	ds_read_b128 v[170:173], v199 offset:6144
	ds_read_b128 v[174:177], v199 offset:7168
	global_load_lds_dwordx4 v212, s[8:9]
	s_add_i32 m0, s34, 0xe000
	s_nop 0
	global_load_lds_dwordx4 v214, s[8:9]
	s_waitcnt lgkmcnt(8)
	s_setprio 1
	s_barrier
	s_waitcnt lgkmcnt(0)
	v_mfma_f32_16x16x32_bf16 v[126:129], v[130:133], v[146:149], v[126:129]
	v_mfma_f32_16x16x32_bf16 v[122:125], v[138:141], v[146:149], v[122:125]
	v_mfma_f32_16x16x32_bf16 v[118:121], v[130:133], v[154:157], v[118:121]
	v_mfma_f32_16x16x32_bf16 v[114:117], v[138:141], v[154:157], v[114:117]
	v_mfma_f32_16x16x32_bf16 v[110:113], v[130:133], v[162:165], v[110:113]
	v_mfma_f32_16x16x32_bf16 v[106:109], v[138:141], v[162:165], v[106:109]
	v_mfma_f32_16x16x32_bf16 v[102:105], v[130:133], v[170:173], v[102:105]
	v_mfma_f32_16x16x32_bf16 v[98:101], v[138:141], v[170:173], v[98:101]
	v_mfma_f32_16x16x32_bf16 v[126:129], v[134:137], v[150:153], v[126:129]
	v_mfma_f32_16x16x32_bf16 v[122:125], v[142:145], v[150:153], v[122:125]
	v_mfma_f32_16x16x32_bf16 v[118:121], v[134:137], v[158:161], v[118:121]
	v_mfma_f32_16x16x32_bf16 v[114:117], v[142:145], v[158:161], v[114:117]
	v_mfma_f32_16x16x32_bf16 v[110:113], v[134:137], v[166:169], v[110:113]
	v_mfma_f32_16x16x32_bf16 v[106:109], v[142:145], v[166:169], v[106:109]
	v_mfma_f32_16x16x32_bf16 v[102:105], v[134:137], v[174:177], v[102:105]
	v_mfma_f32_16x16x32_bf16 v[98:101], v[142:145], v[174:177], v[98:101]
	s_barrier
	s_setprio 0
	s_mov_b32 m0, s35
	v_lshl_add_u64 v[216:217], s[52:53], 0, v[194:195]
	ds_read_b128 v[178:181], v253 offset:16384
	ds_read_b128 v[182:185], v253 offset:17408
	ds_read_b128 v[186:189], v253 offset:18432
	ds_read_b128 v[190:193], v253 offset:19456
	global_load_lds_dwordx4 v[216:217], off
	v_lshl_add_u64 v[218:219], s[52:53], 0, v[210:211]
	s_mov_b32 m0, s42
	s_nop 0
	global_load_lds_dwordx4 v[218:219], off
	s_setprio 1
	s_barrier
	s_waitcnt lgkmcnt(0)
	v_mfma_f32_16x16x32_bf16 v[94:97], v[178:181], v[146:149], v[94:97]
	v_mfma_f32_16x16x32_bf16 v[90:93], v[186:189], v[146:149], v[90:93]
	v_mfma_f32_16x16x32_bf16 v[86:89], v[178:181], v[154:157], v[86:89]
	v_mfma_f32_16x16x32_bf16 v[82:85], v[186:189], v[154:157], v[82:85]
	v_mfma_f32_16x16x32_bf16 v[78:81], v[178:181], v[162:165], v[78:81]
	v_mfma_f32_16x16x32_bf16 v[74:77], v[186:189], v[162:165], v[74:77]
	v_mfma_f32_16x16x32_bf16 v[70:73], v[178:181], v[170:173], v[70:73]
	v_mfma_f32_16x16x32_bf16 v[66:69], v[186:189], v[170:173], v[66:69]
	v_mfma_f32_16x16x32_bf16 v[94:97], v[182:185], v[150:153], v[94:97]
	v_mfma_f32_16x16x32_bf16 v[90:93], v[190:193], v[150:153], v[90:93]
	v_mfma_f32_16x16x32_bf16 v[86:89], v[182:185], v[158:161], v[86:89]
	v_mfma_f32_16x16x32_bf16 v[82:85], v[190:193], v[158:161], v[82:85]
	v_mfma_f32_16x16x32_bf16 v[78:81], v[182:185], v[166:169], v[78:81]
	v_mfma_f32_16x16x32_bf16 v[74:77], v[190:193], v[166:169], v[74:77]
	s_mov_b32 m0, s34
	v_mfma_f32_16x16x32_bf16 v[70:73], v[182:185], v[174:177], v[70:73]
	v_lshl_add_u64 v[220:221], s[10:11], 0, v[206:207]
	v_mfma_f32_16x16x32_bf16 v[66:69], v[190:193], v[174:177], v[66:69]
	s_barrier
	s_setprio 0
	ds_read_b128 v[146:149], v199 offset:16384
	ds_read_b128 v[150:153], v199 offset:17408
	ds_read_b128 v[154:157], v199 offset:18432
	ds_read_b128 v[158:161], v199 offset:19456
	ds_read_b128 v[162:165], v199 offset:20480
	ds_read_b128 v[166:169], v199 offset:21504
	ds_read_b128 v[170:173], v199 offset:22528
	ds_read_b128 v[174:177], v199 offset:23552
	global_load_lds_dwordx4 v[220:221], off
	v_lshl_add_u64 v[222:223], s[10:11], 0, v[208:209]
	s_mov_b32 m0, s56
	s_nop 0
	global_load_lds_dwordx4 v[222:223], off
	s_setprio 1
	s_barrier
	s_waitcnt lgkmcnt(0)
	v_mfma_f32_16x16x32_bf16 v[62:65], v[130:133], v[146:149], v[62:65]
	v_mfma_f32_16x16x32_bf16 v[58:61], v[138:141], v[146:149], v[58:61]
	v_mfma_f32_16x16x32_bf16 v[54:57], v[130:133], v[154:157], v[54:57]
	v_mfma_f32_16x16x32_bf16 v[50:53], v[138:141], v[154:157], v[50:53]
	v_mfma_f32_16x16x32_bf16 v[46:49], v[130:133], v[162:165], v[46:49]
	v_mfma_f32_16x16x32_bf16 v[42:45], v[138:141], v[162:165], v[42:45]
	v_mfma_f32_16x16x32_bf16 v[38:41], v[130:133], v[170:173], v[38:41]
	v_mfma_f32_16x16x32_bf16 v[34:37], v[138:141], v[170:173], v[34:37]
	v_mfma_f32_16x16x32_bf16 v[62:65], v[134:137], v[150:153], v[62:65]
	v_mfma_f32_16x16x32_bf16 v[58:61], v[142:145], v[150:153], v[58:61]
	v_mfma_f32_16x16x32_bf16 v[54:57], v[134:137], v[158:161], v[54:57]
	v_mfma_f32_16x16x32_bf16 v[50:53], v[142:145], v[158:161], v[50:53]
	v_mfma_f32_16x16x32_bf16 v[46:49], v[134:137], v[166:169], v[46:49]
	v_mfma_f32_16x16x32_bf16 v[42:45], v[142:145], v[166:169], v[42:45]
	v_mfma_f32_16x16x32_bf16 v[38:41], v[134:137], v[174:177], v[38:41]
	v_mfma_f32_16x16x32_bf16 v[34:37], v[142:145], v[174:177], v[34:37]
	s_barrier
	s_setprio 0
	s_add_u32 s86, s52, 0x40000
	s_addc_u32 s87, s53, 0
	s_mov_b32 m0, s57
	s_nop 0
	global_load_lds_dwordx4 v194, s[86:87]
	s_mov_b32 m0, s67
	s_nop 0
	global_load_lds_dwordx4 v210, s[86:87]
	s_waitcnt vmcnt(6)
	s_setprio 1
	s_barrier
	v_mfma_f32_16x16x32_bf16 v[30:33], v[178:181], v[146:149], v[30:33]
	v_mfma_f32_16x16x32_bf16 v[26:29], v[186:189], v[146:149], v[26:29]
	v_mfma_f32_16x16x32_bf16 v[22:25], v[178:181], v[154:157], v[22:25]
	v_mfma_f32_16x16x32_bf16 v[18:21], v[186:189], v[154:157], v[18:21]
	v_mfma_f32_16x16x32_bf16 v[14:17], v[178:181], v[162:165], v[14:17]
	v_mfma_f32_16x16x32_bf16 v[10:13], v[186:189], v[162:165], v[10:13]
	v_mfma_f32_16x16x32_bf16 v[6:9], v[178:181], v[170:173], v[6:9]
	v_mfma_f32_16x16x32_bf16 v[2:5], v[186:189], v[170:173], v[2:5]
	v_mfma_f32_16x16x32_bf16 v[30:33], v[182:185], v[150:153], v[30:33]
	v_mfma_f32_16x16x32_bf16 v[26:29], v[190:193], v[150:153], v[26:29]
	v_mfma_f32_16x16x32_bf16 v[22:25], v[182:185], v[158:161], v[22:25]
	v_mfma_f32_16x16x32_bf16 v[18:21], v[190:193], v[158:161], v[18:21]
	v_mfma_f32_16x16x32_bf16 v[14:17], v[182:185], v[166:169], v[14:17]
	v_mfma_f32_16x16x32_bf16 v[10:13], v[190:193], v[166:169], v[10:13]
	v_mfma_f32_16x16x32_bf16 v[6:9], v[182:185], v[174:177], v[6:9]
	v_mfma_f32_16x16x32_bf16 v[2:5], v[190:193], v[174:177], v[2:5]
	s_barrier
	s_setprio 0
	ds_read_b128 v[130:133], v253 offset:32768
	ds_read_b128 v[134:137], v253 offset:33792
	ds_read_b128 v[138:141], v253 offset:34816
	ds_read_b128 v[142:145], v253 offset:35840
	s_add_u32 s10, s10, 0x40000
	s_addc_u32 s11, s11, 0
	s_mov_b32 m0, s70
	ds_read_b128 v[146:149], v199 offset:32768
	ds_read_b128 v[150:153], v199 offset:33792
	ds_read_b128 v[154:157], v199 offset:34816
	ds_read_b128 v[158:161], v199 offset:35840
	ds_read_b128 v[162:165], v199 offset:36864
	ds_read_b128 v[166:169], v199 offset:37888
	ds_read_b128 v[170:173], v199 offset:38912
	ds_read_b128 v[174:177], v199 offset:39936
	global_load_lds_dwordx4 v206, s[10:11]
	s_mov_b32 m0, s71
	s_nop 0
	global_load_lds_dwordx4 v208, s[10:11]
	s_waitcnt lgkmcnt(8)
	s_setprio 1
	s_barrier
	s_waitcnt lgkmcnt(0)
	v_mfma_f32_16x16x32_bf16 v[126:129], v[130:133], v[146:149], v[126:129]
	v_mfma_f32_16x16x32_bf16 v[122:125], v[138:141], v[146:149], v[122:125]
	v_mfma_f32_16x16x32_bf16 v[118:121], v[130:133], v[154:157], v[118:121]
	v_mfma_f32_16x16x32_bf16 v[114:117], v[138:141], v[154:157], v[114:117]
	v_mfma_f32_16x16x32_bf16 v[110:113], v[130:133], v[162:165], v[110:113]
	v_mfma_f32_16x16x32_bf16 v[106:109], v[138:141], v[162:165], v[106:109]
	v_mfma_f32_16x16x32_bf16 v[102:105], v[130:133], v[170:173], v[102:105]
	v_mfma_f32_16x16x32_bf16 v[98:101], v[138:141], v[170:173], v[98:101]
	v_mfma_f32_16x16x32_bf16 v[126:129], v[134:137], v[150:153], v[126:129]
	v_mfma_f32_16x16x32_bf16 v[122:125], v[142:145], v[150:153], v[122:125]
	v_mfma_f32_16x16x32_bf16 v[118:121], v[134:137], v[158:161], v[118:121]
	v_mfma_f32_16x16x32_bf16 v[114:117], v[142:145], v[158:161], v[114:117]
	v_mfma_f32_16x16x32_bf16 v[110:113], v[134:137], v[166:169], v[110:113]
	v_mfma_f32_16x16x32_bf16 v[106:109], v[142:145], v[166:169], v[106:109]
	v_mfma_f32_16x16x32_bf16 v[102:105], v[134:137], v[174:177], v[102:105]
	v_mfma_f32_16x16x32_bf16 v[98:101], v[142:145], v[174:177], v[98:101]
	s_barrier
	s_setprio 0
	s_mov_b32 m0, s78
	v_lshl_add_u64 v[216:217], v[216:217], 0, s[76:77]
	ds_read_b128 v[178:181], v253 offset:49152
	ds_read_b128 v[182:185], v253 offset:50176
	ds_read_b128 v[186:189], v253 offset:51200
	ds_read_b128 v[190:193], v253 offset:52224
	global_load_lds_dwordx4 v[216:217], off
	v_lshl_add_u64 v[216:217], v[218:219], 0, s[76:77]
	s_mov_b32 m0, s79
	s_nop 0
	global_load_lds_dwordx4 v[216:217], off
	s_setprio 1
	s_barrier
	s_waitcnt lgkmcnt(0)
	v_mfma_f32_16x16x32_bf16 v[94:97], v[178:181], v[146:149], v[94:97]
	v_mfma_f32_16x16x32_bf16 v[90:93], v[186:189], v[146:149], v[90:93]
	v_mfma_f32_16x16x32_bf16 v[86:89], v[178:181], v[154:157], v[86:89]
	v_mfma_f32_16x16x32_bf16 v[82:85], v[186:189], v[154:157], v[82:85]
	v_mfma_f32_16x16x32_bf16 v[78:81], v[178:181], v[162:165], v[78:81]
	v_mfma_f32_16x16x32_bf16 v[74:77], v[186:189], v[162:165], v[74:77]
	v_mfma_f32_16x16x32_bf16 v[70:73], v[178:181], v[170:173], v[70:73]
	v_mfma_f32_16x16x32_bf16 v[66:69], v[186:189], v[170:173], v[66:69]
	v_mfma_f32_16x16x32_bf16 v[94:97], v[182:185], v[150:153], v[94:97]
	v_mfma_f32_16x16x32_bf16 v[90:93], v[190:193], v[150:153], v[90:93]
	v_mfma_f32_16x16x32_bf16 v[86:89], v[182:185], v[158:161], v[86:89]
	v_mfma_f32_16x16x32_bf16 v[82:85], v[190:193], v[158:161], v[82:85]
	v_mfma_f32_16x16x32_bf16 v[78:81], v[182:185], v[166:169], v[78:81]
	v_mfma_f32_16x16x32_bf16 v[74:77], v[190:193], v[166:169], v[74:77]
	s_mov_b32 m0, s26
	v_mfma_f32_16x16x32_bf16 v[70:73], v[182:185], v[174:177], v[70:73]
	v_lshl_add_u64 v[216:217], v[220:221], 0, s[76:77]
	v_mfma_f32_16x16x32_bf16 v[66:69], v[190:193], v[174:177], v[66:69]
	s_barrier
	s_setprio 0
	ds_read_b128 v[146:149], v199 offset:49152
	ds_read_b128 v[150:153], v199 offset:50176
	ds_read_b128 v[154:157], v199 offset:51200
	ds_read_b128 v[158:161], v199 offset:52224
	ds_read_b128 v[162:165], v199 offset:53248
	ds_read_b128 v[166:169], v199 offset:54272
	ds_read_b128 v[170:173], v199 offset:55296
	ds_read_b128 v[174:177], v199 offset:56320
	global_load_lds_dwordx4 v[216:217], off
	v_lshl_add_u64 v[216:217], v[222:223], 0, s[76:77]
	s_mov_b32 m0, s4
	s_nop 0
	global_load_lds_dwordx4 v[216:217], off
	s_setprio 1
	s_barrier
	s_waitcnt lgkmcnt(0)
	v_mfma_f32_16x16x32_bf16 v[62:65], v[130:133], v[146:149], v[62:65]
	v_mfma_f32_16x16x32_bf16 v[58:61], v[138:141], v[146:149], v[58:61]
	v_mfma_f32_16x16x32_bf16 v[54:57], v[130:133], v[154:157], v[54:57]
	v_mfma_f32_16x16x32_bf16 v[50:53], v[138:141], v[154:157], v[50:53]
	v_mfma_f32_16x16x32_bf16 v[46:49], v[130:133], v[162:165], v[46:49]
	v_mfma_f32_16x16x32_bf16 v[42:45], v[138:141], v[162:165], v[42:45]
	v_mfma_f32_16x16x32_bf16 v[38:41], v[130:133], v[170:173], v[38:41]
	v_mfma_f32_16x16x32_bf16 v[34:37], v[138:141], v[170:173], v[34:37]
	v_mfma_f32_16x16x32_bf16 v[62:65], v[134:137], v[150:153], v[62:65]
	v_mfma_f32_16x16x32_bf16 v[58:61], v[142:145], v[150:153], v[58:61]
	v_mfma_f32_16x16x32_bf16 v[54:57], v[134:137], v[158:161], v[54:57]
	v_mfma_f32_16x16x32_bf16 v[50:53], v[142:145], v[158:161], v[50:53]
	v_mfma_f32_16x16x32_bf16 v[46:49], v[134:137], v[166:169], v[46:49]
	v_mfma_f32_16x16x32_bf16 v[42:45], v[142:145], v[166:169], v[42:45]
	v_mfma_f32_16x16x32_bf16 v[38:41], v[134:137], v[174:177], v[38:41]
	v_mfma_f32_16x16x32_bf16 v[34:37], v[142:145], v[174:177], v[34:37]
	s_barrier
	s_setprio 0
	s_add_u32 s10, s52, 0x40080
	s_addc_u32 s11, s53, 0
	s_mov_b32 m0, s5
	s_nop 0
	global_load_lds_dwordx4 v194, s[10:11]
	s_mov_b32 m0, s58
	s_nop 0
	global_load_lds_dwordx4 v210, s[10:11]
	s_waitcnt vmcnt(6)
	s_setprio 1
	s_barrier
	v_mfma_f32_16x16x32_bf16 v[30:33], v[178:181], v[146:149], v[30:33]
	v_mfma_f32_16x16x32_bf16 v[26:29], v[186:189], v[146:149], v[26:29]
	v_mfma_f32_16x16x32_bf16 v[22:25], v[178:181], v[154:157], v[22:25]
	v_mfma_f32_16x16x32_bf16 v[18:21], v[186:189], v[154:157], v[18:21]
	v_mfma_f32_16x16x32_bf16 v[14:17], v[178:181], v[162:165], v[14:17]
	v_mfma_f32_16x16x32_bf16 v[10:13], v[186:189], v[162:165], v[10:13]
	v_mfma_f32_16x16x32_bf16 v[6:9], v[178:181], v[170:173], v[6:9]
	v_mfma_f32_16x16x32_bf16 v[2:5], v[186:189], v[170:173], v[2:5]
	s_add_i32 s29, s29, 2
	s_add_u32 s8, s8, 0x100
	s_addc_u32 s9, s9, 0
	s_add_u32 s7, s7, 0x100
	s_addc_u32 s28, s28, 0
	s_cmp_gt_u32 s29, 13
	v_mfma_f32_16x16x32_bf16 v[30:33], v[182:185], v[150:153], v[30:33]
	v_mfma_f32_16x16x32_bf16 v[26:29], v[190:193], v[150:153], v[26:29]
	v_mfma_f32_16x16x32_bf16 v[22:25], v[182:185], v[158:161], v[22:25]
	v_mfma_f32_16x16x32_bf16 v[18:21], v[190:193], v[158:161], v[18:21]
	v_mfma_f32_16x16x32_bf16 v[14:17], v[182:185], v[166:169], v[14:17]
	v_mfma_f32_16x16x32_bf16 v[10:13], v[190:193], v[166:169], v[10:13]
	v_mfma_f32_16x16x32_bf16 v[6:9], v[182:185], v[174:177], v[6:9]
	v_mfma_f32_16x16x32_bf16 v[2:5], v[190:193], v[174:177], v[2:5]
	s_barrier
	s_setprio 0
	s_cbranch_scc0 .LBB0_368
	s_cmp_gt_i32 s95, 1
	s_cselect_b64 s[52:53], -1, 0
	s_mul_i32 s7, s6, 0x680000
	s_lshl_b32 s8, s95, 12
	s_lshl_b32 s9, s54, 9
	s_add_i32 s7, s7, s8
	s_add_i32 s7, s7, s9
	s_add_i32 s7, s7, 0x3800
	s_add_u32 s20, s50, s7
	s_addc_u32 s21, s51, 0
	s_lshl_b32 s7, s6, 20
	s_add_i32 s7, s7, s9
	s_add_u32 s10, s96, s7
	s_addc_u32 s11, s97, 0
	s_mov_b32 s86, 0xbfb8aa3b
	s_mov_b32 s87, 0xbfb8aa3b
	v_mul_u32_u24_e32 v253, 0x6800, v197
	v_lshlrev_b32_e32 v255, 12, v197
	v_lshl_add_u32 v253, v203, 1, v253
	v_lshl_add_u32 v255, v203, 1, v255
	v_add_u32_e32 v254, 0x1000, v253
	s_cmp_eq_u32 s95, 2
	s_cbranch_scc1 .Lem_br2
	global_load_dwordx4 v[130:133], v253, s[20:21]
	global_load_dwordx4 v[134:137], v254, s[20:21]
	global_load_dwordx4 v[138:141], v253, s[20:21] offset:256
	global_load_dwordx4 v[142:145], v254, s[20:21] offset:256
	s_add_u32 s28, s20, 0x68000
	s_addc_u32 s29, s21, 0
	global_load_dwordx4 v[146:149], v253, s[28:29]
	global_load_dwordx4 v[150:153], v254, s[28:29]
	global_load_dwordx4 v[154:157], v253, s[28:29] offset:256
	global_load_dwordx4 v[158:161], v254, s[28:29] offset:256
	s_add_u32 s28, s20, 0xd0000
	s_addc_u32 s29, s21, 0
	global_load_dwordx4 v[162:165], v253, s[28:29]
	global_load_dwordx4 v[166:169], v254, s[28:29]
	global_load_dwordx4 v[170:173], v253, s[28:29] offset:256
	global_load_dwordx4 v[174:177], v254, s[28:29] offset:256
	s_add_u32 s28, s20, 0x138000
	s_addc_u32 s29, s21, 0
	global_load_dwordx4 v[178:181], v253, s[28:29]
	global_load_dwordx4 v[182:185], v254, s[28:29]
	global_load_dwordx4 v[186:189], v253, s[28:29] offset:256
	global_load_dwordx4 v[190:193], v254, s[28:29] offset:256
	s_waitcnt vmcnt(12)
	v_lshlrev_b32_e32 v216, 16, v130
	v_and_b32_e32 v217, 0xffff0000, v130
	v_lshlrev_b32_e32 v218, 16, v131
	v_and_b32_e32 v219, 0xffff0000, v131
	v_lshlrev_b32_e32 v220, 16, v132
	v_and_b32_e32 v221, 0xffff0000, v132
	v_lshlrev_b32_e32 v222, 16, v133
	v_and_b32_e32 v223, 0xffff0000, v133
	v_pk_mul_f32 v[216:217], v[216:217], s[86:87] op_sel_hi:[1,0]
	v_pk_mul_f32 v[218:219], v[218:219], s[86:87] op_sel_hi:[1,0]
	v_pk_mul_f32 v[220:221], v[220:221], s[86:87] op_sel_hi:[1,0]
	v_pk_mul_f32 v[222:223], v[222:223], s[86:87] op_sel_hi:[1,0]
	v_exp_f32_e32 v216, v216
	v_exp_f32_e32 v217, v217
	v_exp_f32_e32 v218, v218
	v_exp_f32_e32 v219, v219
	v_exp_f32_e32 v220, v220
	v_exp_f32_e32 v221, v221
	v_exp_f32_e32 v222, v222
	v_exp_f32_e32 v223, v223
	v_pk_add_f32 v[216:217], v[216:217], 1.0 op_sel_hi:[1,0]
	v_pk_add_f32 v[218:219], v[218:219], 1.0 op_sel_hi:[1,0]
	v_pk_add_f32 v[220:221], v[220:221], 1.0 op_sel_hi:[1,0]
	v_pk_add_f32 v[222:223], v[222:223], 1.0 op_sel_hi:[1,0]
	v_rcp_f32_e32 v216, v216
	v_rcp_f32_e32 v217, v217
	v_rcp_f32_e32 v218, v218
	v_rcp_f32_e32 v219, v219
	v_rcp_f32_e32 v220, v220
	v_rcp_f32_e32 v221, v221
	v_rcp_f32_e32 v222, v222
	v_rcp_f32_e32 v223, v223
	v_lshlrev_b32_e32 v242, 16, v134
	v_and_b32_e32 v243, 0xffff0000, v134
	v_lshlrev_b32_e32 v244, 16, v135
	v_and_b32_e32 v245, 0xffff0000, v135
	v_lshlrev_b32_e32 v246, 16, v136
	v_and_b32_e32 v247, 0xffff0000, v136
	v_lshlrev_b32_e32 v248, 16, v137
	v_and_b32_e32 v249, 0xffff0000, v137
	v_pk_mul_f32 v[242:243], v[242:243], s[86:87] op_sel_hi:[1,0]
	v_pk_mul_f32 v[244:245], v[244:245], s[86:87] op_sel_hi:[1,0]
	v_pk_mul_f32 v[246:247], v[246:247], s[86:87] op_sel_hi:[1,0]
	v_pk_mul_f32 v[248:249], v[248:249], s[86:87] op_sel_hi:[1,0]
	v_exp_f32_e32 v242, v242
	v_exp_f32_e32 v243, v243
	v_exp_f32_e32 v244, v244
	v_exp_f32_e32 v245, v245
	v_exp_f32_e32 v246, v246
	v_exp_f32_e32 v247, v247
	v_exp_f32_e32 v248, v248
	v_exp_f32_e32 v249, v249
	v_pk_add_f32 v[242:243], v[242:243], 1.0 op_sel_hi:[1,0]
	v_pk_add_f32 v[244:245], v[244:245], 1.0 op_sel_hi:[1,0]
	v_pk_add_f32 v[246:247], v[246:247], 1.0 op_sel_hi:[1,0]
	v_pk_add_f32 v[248:249], v[248:249], 1.0 op_sel_hi:[1,0]
	v_pk_mul_f32 v[216:217], v[216:217], v[242:243]
	v_pk_mul_f32 v[218:219], v[218:219], v[244:245]
	v_pk_mul_f32 v[220:221], v[220:221], v[246:247]
	v_pk_mul_f32 v[222:223], v[222:223], v[248:249]
	v_pk_mul_f32 v[126:127], v[126:127], v[216:217]
	v_pk_mul_f32 v[128:129], v[128:129], v[218:219]
	v_pk_mul_f32 v[122:123], v[122:123], v[220:221]
	v_pk_mul_f32 v[124:125], v[124:125], v[222:223]
	v_lshlrev_b32_e32 v216, 16, v138
	v_and_b32_e32 v217, 0xffff0000, v138
	v_lshlrev_b32_e32 v218, 16, v139
	v_and_b32_e32 v219, 0xffff0000, v139
	v_lshlrev_b32_e32 v220, 16, v140
	v_and_b32_e32 v221, 0xffff0000, v140
	v_lshlrev_b32_e32 v222, 16, v141
	v_and_b32_e32 v223, 0xffff0000, v141
	v_pk_mul_f32 v[216:217], v[216:217], s[86:87] op_sel_hi:[1,0]
	v_pk_mul_f32 v[218:219], v[218:219], s[86:87] op_sel_hi:[1,0]
	v_pk_mul_f32 v[220:221], v[220:221], s[86:87] op_sel_hi:[1,0]
	v_pk_mul_f32 v[222:223], v[222:223], s[86:87] op_sel_hi:[1,0]
	v_exp_f32_e32 v216, v216
	v_exp_f32_e32 v217, v217
	v_exp_f32_e32 v218, v218
	v_exp_f32_e32 v219, v219
	v_exp_f32_e32 v220, v220
	v_exp_f32_e32 v221, v221
	v_exp_f32_e32 v222, v222
	v_exp_f32_e32 v223, v223
	v_pk_add_f32 v[216:217], v[216:217], 1.0 op_sel_hi:[1,0]
	v_pk_add_f32 v[218:219], v[218:219], 1.0 op_sel_hi:[1,0]
	v_pk_add_f32 v[220:221], v[220:221], 1.0 op_sel_hi:[1,0]
	v_pk_add_f32 v[222:223], v[222:223], 1.0 op_sel_hi:[1,0]
	v_rcp_f32_e32 v216, v216
	v_rcp_f32_e32 v217, v217
	v_rcp_f32_e32 v218, v218
	v_rcp_f32_e32 v219, v219
	v_rcp_f32_e32 v220, v220
	v_rcp_f32_e32 v221, v221
	v_rcp_f32_e32 v222, v222
	v_rcp_f32_e32 v223, v223
	v_lshlrev_b32_e32 v242, 16, v142
	v_and_b32_e32 v243, 0xffff0000, v142
	v_lshlrev_b32_e32 v244, 16, v143
	v_and_b32_e32 v245, 0xffff0000, v143
	v_lshlrev_b32_e32 v246, 16, v144
	v_and_b32_e32 v247, 0xffff0000, v144
	v_lshlrev_b32_e32 v248, 16, v145
	v_and_b32_e32 v249, 0xffff0000, v145
	v_pk_mul_f32 v[242:243], v[242:243], s[86:87] op_sel_hi:[1,0]
	v_pk_mul_f32 v[244:245], v[244:245], s[86:87] op_sel_hi:[1,0]
	v_pk_mul_f32 v[246:247], v[246:247], s[86:87] op_sel_hi:[1,0]
	v_pk_mul_f32 v[248:249], v[248:249], s[86:87] op_sel_hi:[1,0]
	v_exp_f32_e32 v242, v242
	v_exp_f32_e32 v243, v243
	v_exp_f32_e32 v244, v244
	v_exp_f32_e32 v245, v245
	v_exp_f32_e32 v246, v246
	v_exp_f32_e32 v247, v247
	v_exp_f32_e32 v248, v248
	v_exp_f32_e32 v249, v249
	v_pk_add_f32 v[242:243], v[242:243], 1.0 op_sel_hi:[1,0]
	v_pk_add_f32 v[244:245], v[244:245], 1.0 op_sel_hi:[1,0]
	v_pk_add_f32 v[246:247], v[246:247], 1.0 op_sel_hi:[1,0]
	v_pk_add_f32 v[248:249], v[248:249], 1.0 op_sel_hi:[1,0]
	v_pk_mul_f32 v[216:217], v[216:217], v[242:243]
	v_pk_mul_f32 v[218:219], v[218:219], v[244:245]
	v_pk_mul_f32 v[220:221], v[220:221], v[246:247]
	v_pk_mul_f32 v[222:223], v[222:223], v[248:249]
	v_pk_mul_f32 v[94:95], v[94:95], v[216:217]
	v_pk_mul_f32 v[96:97], v[96:97], v[218:219]
	v_pk_mul_f32 v[90:91], v[90:91], v[220:221]
	v_pk_mul_f32 v[92:93], v[92:93], v[222:223]
	s_add_u32 s28, s20, 0x340000
	s_addc_u32 s29, s21, 0
	global_load_dwordx4 v[130:133], v253, s[28:29]
	global_load_dwordx4 v[134:137], v254, s[28:29]
	global_load_dwordx4 v[138:141], v253, s[28:29] offset:256
	global_load_dwordx4 v[142:145], v254, s[28:29] offset:256
	s_waitcnt vmcnt(12)
	v_lshlrev_b32_e32 v216, 16, v146
	v_and_b32_e32 v217, 0xffff0000, v146
	v_lshlrev_b32_e32 v218, 16, v147
	v_and_b32_e32 v219, 0xffff0000, v147
	v_lshlrev_b32_e32 v220, 16, v148
	v_and_b32_e32 v221, 0xffff0000, v148
	v_lshlrev_b32_e32 v222, 16, v149
	v_and_b32_e32 v223, 0xffff0000, v149
	v_pk_mul_f32 v[216:217], v[216:217], s[86:87] op_sel_hi:[1,0]
	v_pk_mul_f32 v[218:219], v[218:219], s[86:87] op_sel_hi:[1,0]
	v_pk_mul_f32 v[220:221], v[220:221], s[86:87] op_sel_hi:[1,0]
	v_pk_mul_f32 v[222:223], v[222:223], s[86:87] op_sel_hi:[1,0]
	v_exp_f32_e32 v216, v216
	v_exp_f32_e32 v217, v217
	v_exp_f32_e32 v218, v218
	v_exp_f32_e32 v219, v219
	v_exp_f32_e32 v220, v220
	v_exp_f32_e32 v221, v221
	v_exp_f32_e32 v222, v222
	v_exp_f32_e32 v223, v223
	v_pk_add_f32 v[216:217], v[216:217], 1.0 op_sel_hi:[1,0]
	v_pk_add_f32 v[218:219], v[218:219], 1.0 op_sel_hi:[1,0]
	v_pk_add_f32 v[220:221], v[220:221], 1.0 op_sel_hi:[1,0]
	v_pk_add_f32 v[222:223], v[222:223], 1.0 op_sel_hi:[1,0]
	v_rcp_f32_e32 v216, v216
	v_rcp_f32_e32 v217, v217
	v_rcp_f32_e32 v218, v218
	v_rcp_f32_e32 v219, v219
	v_rcp_f32_e32 v220, v220
	v_rcp_f32_e32 v221, v221
	v_rcp_f32_e32 v222, v222
	v_rcp_f32_e32 v223, v223
	v_lshlrev_b32_e32 v242, 16, v150
	v_and_b32_e32 v243, 0xffff0000, v150
	v_lshlrev_b32_e32 v244, 16, v151
	v_and_b32_e32 v245, 0xffff0000, v151
	v_lshlrev_b32_e32 v246, 16, v152
	v_and_b32_e32 v247, 0xffff0000, v152
	v_lshlrev_b32_e32 v248, 16, v153
	v_and_b32_e32 v249, 0xffff0000, v153
	v_pk_mul_f32 v[242:243], v[242:243], s[86:87] op_sel_hi:[1,0]
	v_pk_mul_f32 v[244:245], v[244:245], s[86:87] op_sel_hi:[1,0]
	v_pk_mul_f32 v[246:247], v[246:247], s[86:87] op_sel_hi:[1,0]
	v_pk_mul_f32 v[248:249], v[248:249], s[86:87] op_sel_hi:[1,0]
	v_exp_f32_e32 v242, v242
	v_exp_f32_e32 v243, v243
	v_exp_f32_e32 v244, v244
	v_exp_f32_e32 v245, v245
	v_exp_f32_e32 v246, v246
	v_exp_f32_e32 v247, v247
	v_exp_f32_e32 v248, v248
	v_exp_f32_e32 v249, v249
	v_pk_add_f32 v[242:243], v[242:243], 1.0 op_sel_hi:[1,0]
	v_pk_add_f32 v[244:245], v[244:245], 1.0 op_sel_hi:[1,0]
	v_pk_add_f32 v[246:247], v[246:247], 1.0 op_sel_hi:[1,0]
	v_pk_add_f32 v[248:249], v[248:249], 1.0 op_sel_hi:[1,0]
	v_pk_mul_f32 v[216:217], v[216:217], v[242:243]
	v_pk_mul_f32 v[218:219], v[218:219], v[244:245]
	v_pk_mul_f32 v[220:221], v[220:221], v[246:247]
	v_pk_mul_f32 v[222:223], v[222:223], v[248:249]
	v_pk_mul_f32 v[118:119], v[118:119], v[216:217]
	v_pk_mul_f32 v[120:121], v[120:121], v[218:219]
	v_pk_mul_f32 v[114:115], v[114:115], v[220:221]
	v_pk_mul_f32 v[116:117], v[116:117], v[222:223]
	v_lshlrev_b32_e32 v216, 16, v154
	v_and_b32_e32 v217, 0xffff0000, v154
	v_lshlrev_b32_e32 v218, 16, v155
	v_and_b32_e32 v219, 0xffff0000, v155
	v_lshlrev_b32_e32 v220, 16, v156
	v_and_b32_e32 v221, 0xffff0000, v156
	v_lshlrev_b32_e32 v222, 16, v157
	v_and_b32_e32 v223, 0xffff0000, v157
	v_pk_mul_f32 v[216:217], v[216:217], s[86:87] op_sel_hi:[1,0]
	v_pk_mul_f32 v[218:219], v[218:219], s[86:87] op_sel_hi:[1,0]
	v_pk_mul_f32 v[220:221], v[220:221], s[86:87] op_sel_hi:[1,0]
	v_pk_mul_f32 v[222:223], v[222:223], s[86:87] op_sel_hi:[1,0]
	v_exp_f32_e32 v216, v216
	v_exp_f32_e32 v217, v217
	v_exp_f32_e32 v218, v218
	v_exp_f32_e32 v219, v219
	v_exp_f32_e32 v220, v220
	v_exp_f32_e32 v221, v221
	v_exp_f32_e32 v222, v222
	v_exp_f32_e32 v223, v223
	v_pk_add_f32 v[216:217], v[216:217], 1.0 op_sel_hi:[1,0]
	v_pk_add_f32 v[218:219], v[218:219], 1.0 op_sel_hi:[1,0]
	v_pk_add_f32 v[220:221], v[220:221], 1.0 op_sel_hi:[1,0]
	v_pk_add_f32 v[222:223], v[222:223], 1.0 op_sel_hi:[1,0]
	v_rcp_f32_e32 v216, v216
	v_rcp_f32_e32 v217, v217
	v_rcp_f32_e32 v218, v218
	v_rcp_f32_e32 v219, v219
	v_rcp_f32_e32 v220, v220
	v_rcp_f32_e32 v221, v221
	v_rcp_f32_e32 v222, v222
	v_rcp_f32_e32 v223, v223
	v_lshlrev_b32_e32 v242, 16, v158
	v_and_b32_e32 v243, 0xffff0000, v158
	v_lshlrev_b32_e32 v244, 16, v159
	v_and_b32_e32 v245, 0xffff0000, v159
	v_lshlrev_b32_e32 v246, 16, v160
	v_and_b32_e32 v247, 0xffff0000, v160
	v_lshlrev_b32_e32 v248, 16, v161
	v_and_b32_e32 v249, 0xffff0000, v161
	v_pk_mul_f32 v[242:243], v[242:243], s[86:87] op_sel_hi:[1,0]
	v_pk_mul_f32 v[244:245], v[244:245], s[86:87] op_sel_hi:[1,0]
	v_pk_mul_f32 v[246:247], v[246:247], s[86:87] op_sel_hi:[1,0]
	v_pk_mul_f32 v[248:249], v[248:249], s[86:87] op_sel_hi:[1,0]
	v_exp_f32_e32 v242, v242
	v_exp_f32_e32 v243, v243
	v_exp_f32_e32 v244, v244
	v_exp_f32_e32 v245, v245
	v_exp_f32_e32 v246, v246
	v_exp_f32_e32 v247, v247
	v_exp_f32_e32 v248, v248
	v_exp_f32_e32 v249, v249
	v_pk_add_f32 v[242:243], v[242:243], 1.0 op_sel_hi:[1,0]
	v_pk_add_f32 v[244:245], v[244:245], 1.0 op_sel_hi:[1,0]
	v_pk_add_f32 v[246:247], v[246:247], 1.0 op_sel_hi:[1,0]
	v_pk_add_f32 v[248:249], v[248:249], 1.0 op_sel_hi:[1,0]
	v_pk_mul_f32 v[216:217], v[216:217], v[242:243]
	v_pk_mul_f32 v[218:219], v[218:219], v[244:245]
	v_pk_mul_f32 v[220:221], v[220:221], v[246:247]
	v_pk_mul_f32 v[222:223], v[222:223], v[248:249]
	v_pk_mul_f32 v[86:87], v[86:87], v[216:217]
	v_pk_mul_f32 v[88:89], v[88:89], v[218:219]
	v_pk_mul_f32 v[82:83], v[82:83], v[220:221]
	v_pk_mul_f32 v[84:85], v[84:85], v[222:223]
	s_add_u32 s28, s20, 0x3a8000
	s_addc_u32 s29, s21, 0
	global_load_dwordx4 v[146:149], v253, s[28:29]
	global_load_dwordx4 v[150:153], v254, s[28:29]
	global_load_dwordx4 v[154:157], v253, s[28:29] offset:256
	global_load_dwordx4 v[158:161], v254, s[28:29] offset:256
	s_waitcnt vmcnt(12)
	v_lshlrev_b32_e32 v216, 16, v162
	v_and_b32_e32 v217, 0xffff0000, v162
	v_lshlrev_b32_e32 v218, 16, v163
	v_and_b32_e32 v219, 0xffff0000, v163
	v_lshlrev_b32_e32 v220, 16, v164
	v_and_b32_e32 v221, 0xffff0000, v164
	v_lshlrev_b32_e32 v222, 16, v165
	v_and_b32_e32 v223, 0xffff0000, v165
	v_pk_mul_f32 v[216:217], v[216:217], s[86:87] op_sel_hi:[1,0]
	v_pk_mul_f32 v[218:219], v[218:219], s[86:87] op_sel_hi:[1,0]
	v_pk_mul_f32 v[220:221], v[220:221], s[86:87] op_sel_hi:[1,0]
	v_pk_mul_f32 v[222:223], v[222:223], s[86:87] op_sel_hi:[1,0]
	v_exp_f32_e32 v216, v216
	v_exp_f32_e32 v217, v217
	v_exp_f32_e32 v218, v218
	v_exp_f32_e32 v219, v219
	v_exp_f32_e32 v220, v220
	v_exp_f32_e32 v221, v221
	v_exp_f32_e32 v222, v222
	v_exp_f32_e32 v223, v223
	v_pk_add_f32 v[216:217], v[216:217], 1.0 op_sel_hi:[1,0]
	v_pk_add_f32 v[218:219], v[218:219], 1.0 op_sel_hi:[1,0]
	v_pk_add_f32 v[220:221], v[220:221], 1.0 op_sel_hi:[1,0]
	v_pk_add_f32 v[222:223], v[222:223], 1.0 op_sel_hi:[1,0]
	v_rcp_f32_e32 v216, v216
	v_rcp_f32_e32 v217, v217
	v_rcp_f32_e32 v218, v218
	v_rcp_f32_e32 v219, v219
	v_rcp_f32_e32 v220, v220
	v_rcp_f32_e32 v221, v221
	v_rcp_f32_e32 v222, v222
	v_rcp_f32_e32 v223, v223
	v_lshlrev_b32_e32 v242, 16, v166
	v_and_b32_e32 v243, 0xffff0000, v166
	v_lshlrev_b32_e32 v244, 16, v167
	v_and_b32_e32 v245, 0xffff0000, v167
	v_lshlrev_b32_e32 v246, 16, v168
	v_and_b32_e32 v247, 0xffff0000, v168
	v_lshlrev_b32_e32 v248, 16, v169
	v_and_b32_e32 v249, 0xffff0000, v169
	v_pk_mul_f32 v[242:243], v[242:243], s[86:87] op_sel_hi:[1,0]
	v_pk_mul_f32 v[244:245], v[244:245], s[86:87] op_sel_hi:[1,0]
	v_pk_mul_f32 v[246:247], v[246:247], s[86:87] op_sel_hi:[1,0]
	v_pk_mul_f32 v[248:249], v[248:249], s[86:87] op_sel_hi:[1,0]
	v_exp_f32_e32 v242, v242
	v_exp_f32_e32 v243, v243
	v_exp_f32_e32 v244, v244
	v_exp_f32_e32 v245, v245
	v_exp_f32_e32 v246, v246
	v_exp_f32_e32 v247, v247
	v_exp_f32_e32 v248, v248
	v_exp_f32_e32 v249, v249
	v_pk_add_f32 v[242:243], v[242:243], 1.0 op_sel_hi:[1,0]
	v_pk_add_f32 v[244:245], v[244:245], 1.0 op_sel_hi:[1,0]
	v_pk_add_f32 v[246:247], v[246:247], 1.0 op_sel_hi:[1,0]
	v_pk_add_f32 v[248:249], v[248:249], 1.0 op_sel_hi:[1,0]
	v_pk_mul_f32 v[216:217], v[216:217], v[242:243]
	v_pk_mul_f32 v[218:219], v[218:219], v[244:245]
	v_pk_mul_f32 v[220:221], v[220:221], v[246:247]
	v_pk_mul_f32 v[222:223], v[222:223], v[248:249]
	v_pk_mul_f32 v[110:111], v[110:111], v[216:217]
	v_pk_mul_f32 v[112:113], v[112:113], v[218:219]
	v_pk_mul_f32 v[106:107], v[106:107], v[220:221]
	v_pk_mul_f32 v[108:109], v[108:109], v[222:223]
	v_lshlrev_b32_e32 v216, 16, v170
	v_and_b32_e32 v217, 0xffff0000, v170
	v_lshlrev_b32_e32 v218, 16, v171
	v_and_b32_e32 v219, 0xffff0000, v171
	v_lshlrev_b32_e32 v220, 16, v172
	v_and_b32_e32 v221, 0xffff0000, v172
	v_lshlrev_b32_e32 v222, 16, v173
	v_and_b32_e32 v223, 0xffff0000, v173
	v_pk_mul_f32 v[216:217], v[216:217], s[86:87] op_sel_hi:[1,0]
	v_pk_mul_f32 v[218:219], v[218:219], s[86:87] op_sel_hi:[1,0]
	v_pk_mul_f32 v[220:221], v[220:221], s[86:87] op_sel_hi:[1,0]
	v_pk_mul_f32 v[222:223], v[222:223], s[86:87] op_sel_hi:[1,0]
	v_exp_f32_e32 v216, v216
	v_exp_f32_e32 v217, v217
	v_exp_f32_e32 v218, v218
	v_exp_f32_e32 v219, v219
	v_exp_f32_e32 v220, v220
	v_exp_f32_e32 v221, v221
	v_exp_f32_e32 v222, v222
	v_exp_f32_e32 v223, v223
	v_pk_add_f32 v[216:217], v[216:217], 1.0 op_sel_hi:[1,0]
	v_pk_add_f32 v[218:219], v[218:219], 1.0 op_sel_hi:[1,0]
	v_pk_add_f32 v[220:221], v[220:221], 1.0 op_sel_hi:[1,0]
	v_pk_add_f32 v[222:223], v[222:223], 1.0 op_sel_hi:[1,0]
	v_rcp_f32_e32 v216, v216
	v_rcp_f32_e32 v217, v217
	v_rcp_f32_e32 v218, v218
	v_rcp_f32_e32 v219, v219
	v_rcp_f32_e32 v220, v220
	v_rcp_f32_e32 v221, v221
	v_rcp_f32_e32 v222, v222
	v_rcp_f32_e32 v223, v223
	v_lshlrev_b32_e32 v242, 16, v174
	v_and_b32_e32 v243, 0xffff0000, v174
	v_lshlrev_b32_e32 v244, 16, v175
	v_and_b32_e32 v245, 0xffff0000, v175
	v_lshlrev_b32_e32 v246, 16, v176
	v_and_b32_e32 v247, 0xffff0000, v176
	v_lshlrev_b32_e32 v248, 16, v177
	v_and_b32_e32 v249, 0xffff0000, v177
	v_pk_mul_f32 v[242:243], v[242:243], s[86:87] op_sel_hi:[1,0]
	v_pk_mul_f32 v[244:245], v[244:245], s[86:87] op_sel_hi:[1,0]
	v_pk_mul_f32 v[246:247], v[246:247], s[86:87] op_sel_hi:[1,0]
	v_pk_mul_f32 v[248:249], v[248:249], s[86:87] op_sel_hi:[1,0]
	v_exp_f32_e32 v242, v242
	v_exp_f32_e32 v243, v243
	v_exp_f32_e32 v244, v244
	v_exp_f32_e32 v245, v245
	v_exp_f32_e32 v246, v246
	v_exp_f32_e32 v247, v247
	v_exp_f32_e32 v248, v248
	v_exp_f32_e32 v249, v249
	v_pk_add_f32 v[242:243], v[242:243], 1.0 op_sel_hi:[1,0]
	v_pk_add_f32 v[244:245], v[244:245], 1.0 op_sel_hi:[1,0]
	v_pk_add_f32 v[246:247], v[246:247], 1.0 op_sel_hi:[1,0]
	v_pk_add_f32 v[248:249], v[248:249], 1.0 op_sel_hi:[1,0]
	v_pk_mul_f32 v[216:217], v[216:217], v[242:243]
	v_pk_mul_f32 v[218:219], v[218:219], v[244:245]
	v_pk_mul_f32 v[220:221], v[220:221], v[246:247]
	v_pk_mul_f32 v[222:223], v[222:223], v[248:249]
	v_pk_mul_f32 v[78:79], v[78:79], v[216:217]
	v_pk_mul_f32 v[80:81], v[80:81], v[218:219]
	v_pk_mul_f32 v[74:75], v[74:75], v[220:221]
	v_pk_mul_f32 v[76:77], v[76:77], v[222:223]
	s_add_u32 s28, s20, 0x410000
	s_addc_u32 s29, s21, 0
	global_load_dwordx4 v[162:165], v253, s[28:29]
	global_load_dwordx4 v[166:169], v254, s[28:29]
	global_load_dwordx4 v[170:173], v253, s[28:29] offset:256
	global_load_dwordx4 v[174:177], v254, s[28:29] offset:256
	s_waitcnt vmcnt(12)
	v_lshlrev_b32_e32 v216, 16, v178
	v_and_b32_e32 v217, 0xffff0000, v178
	v_lshlrev_b32_e32 v218, 16, v179
	v_and_b32_e32 v219, 0xffff0000, v179
	v_lshlrev_b32_e32 v220, 16, v180
	v_and_b32_e32 v221, 0xffff0000, v180
	v_lshlrev_b32_e32 v222, 16, v181
	v_and_b32_e32 v223, 0xffff0000, v181
	v_pk_mul_f32 v[216:217], v[216:217], s[86:87] op_sel_hi:[1,0]
	v_pk_mul_f32 v[218:219], v[218:219], s[86:87] op_sel_hi:[1,0]
	v_pk_mul_f32 v[220:221], v[220:221], s[86:87] op_sel_hi:[1,0]
	v_pk_mul_f32 v[222:223], v[222:223], s[86:87] op_sel_hi:[1,0]
	v_exp_f32_e32 v216, v216
	v_exp_f32_e32 v217, v217
	v_exp_f32_e32 v218, v218
	v_exp_f32_e32 v219, v219
	v_exp_f32_e32 v220, v220
	v_exp_f32_e32 v221, v221
	v_exp_f32_e32 v222, v222
	v_exp_f32_e32 v223, v223
	v_pk_add_f32 v[216:217], v[216:217], 1.0 op_sel_hi:[1,0]
	v_pk_add_f32 v[218:219], v[218:219], 1.0 op_sel_hi:[1,0]
	v_pk_add_f32 v[220:221], v[220:221], 1.0 op_sel_hi:[1,0]
	v_pk_add_f32 v[222:223], v[222:223], 1.0 op_sel_hi:[1,0]
	v_rcp_f32_e32 v216, v216
	v_rcp_f32_e32 v217, v217
	v_rcp_f32_e32 v218, v218
	v_rcp_f32_e32 v219, v219
	v_rcp_f32_e32 v220, v220
	v_rcp_f32_e32 v221, v221
	v_rcp_f32_e32 v222, v222
	v_rcp_f32_e32 v223, v223
	v_lshlrev_b32_e32 v242, 16, v182
	v_and_b32_e32 v243, 0xffff0000, v182
	v_lshlrev_b32_e32 v244, 16, v183
	v_and_b32_e32 v245, 0xffff0000, v183
	v_lshlrev_b32_e32 v246, 16, v184
	v_and_b32_e32 v247, 0xffff0000, v184
	v_lshlrev_b32_e32 v248, 16, v185
	v_and_b32_e32 v249, 0xffff0000, v185
	v_pk_mul_f32 v[242:243], v[242:243], s[86:87] op_sel_hi:[1,0]
	v_pk_mul_f32 v[244:245], v[244:245], s[86:87] op_sel_hi:[1,0]
	v_pk_mul_f32 v[246:247], v[246:247], s[86:87] op_sel_hi:[1,0]
	v_pk_mul_f32 v[248:249], v[248:249], s[86:87] op_sel_hi:[1,0]
	v_exp_f32_e32 v242, v242
	v_exp_f32_e32 v243, v243
	v_exp_f32_e32 v244, v244
	v_exp_f32_e32 v245, v245
	v_exp_f32_e32 v246, v246
	v_exp_f32_e32 v247, v247
	v_exp_f32_e32 v248, v248
	v_exp_f32_e32 v249, v249
	v_pk_add_f32 v[242:243], v[242:243], 1.0 op_sel_hi:[1,0]
	v_pk_add_f32 v[244:245], v[244:245], 1.0 op_sel_hi:[1,0]
	v_pk_add_f32 v[246:247], v[246:247], 1.0 op_sel_hi:[1,0]
	v_pk_add_f32 v[248:249], v[248:249], 1.0 op_sel_hi:[1,0]
	v_pk_mul_f32 v[216:217], v[216:217], v[242:243]
	v_pk_mul_f32 v[218:219], v[218:219], v[244:245]
	v_pk_mul_f32 v[220:221], v[220:221], v[246:247]
	v_pk_mul_f32 v[222:223], v[222:223], v[248:249]
	v_pk_mul_f32 v[102:103], v[102:103], v[216:217]
	v_pk_mul_f32 v[104:105], v[104:105], v[218:219]
	v_pk_mul_f32 v[98:99], v[98:99], v[220:221]
	v_pk_mul_f32 v[100:101], v[100:101], v[222:223]
	v_lshlrev_b32_e32 v216, 16, v186
	v_and_b32_e32 v217, 0xffff0000, v186
	v_lshlrev_b32_e32 v218, 16, v187
	v_and_b32_e32 v219, 0xffff0000, v187
	v_lshlrev_b32_e32 v220, 16, v188
	v_and_b32_e32 v221, 0xffff0000, v188
	v_lshlrev_b32_e32 v222, 16, v189
	v_and_b32_e32 v223, 0xffff0000, v189
	v_pk_mul_f32 v[216:217], v[216:217], s[86:87] op_sel_hi:[1,0]
	v_pk_mul_f32 v[218:219], v[218:219], s[86:87] op_sel_hi:[1,0]
	v_pk_mul_f32 v[220:221], v[220:221], s[86:87] op_sel_hi:[1,0]
	v_pk_mul_f32 v[222:223], v[222:223], s[86:87] op_sel_hi:[1,0]
	v_exp_f32_e32 v216, v216
	v_exp_f32_e32 v217, v217
	v_exp_f32_e32 v218, v218
	v_exp_f32_e32 v219, v219
	v_exp_f32_e32 v220, v220
	v_exp_f32_e32 v221, v221
	v_exp_f32_e32 v222, v222
	v_exp_f32_e32 v223, v223
	v_pk_add_f32 v[216:217], v[216:217], 1.0 op_sel_hi:[1,0]
	v_pk_add_f32 v[218:219], v[218:219], 1.0 op_sel_hi:[1,0]
	v_pk_add_f32 v[220:221], v[220:221], 1.0 op_sel_hi:[1,0]
	v_pk_add_f32 v[222:223], v[222:223], 1.0 op_sel_hi:[1,0]
	v_rcp_f32_e32 v216, v216
	v_rcp_f32_e32 v217, v217
	v_rcp_f32_e32 v218, v218
	v_rcp_f32_e32 v219, v219
	v_rcp_f32_e32 v220, v220
	v_rcp_f32_e32 v221, v221
	v_rcp_f32_e32 v222, v222
	v_rcp_f32_e32 v223, v223
	v_lshlrev_b32_e32 v242, 16, v190
	v_and_b32_e32 v243, 0xffff0000, v190
	v_lshlrev_b32_e32 v244, 16, v191
	v_and_b32_e32 v245, 0xffff0000, v191
	v_lshlrev_b32_e32 v246, 16, v192
	v_and_b32_e32 v247, 0xffff0000, v192
	v_lshlrev_b32_e32 v248, 16, v193
	v_and_b32_e32 v249, 0xffff0000, v193
	v_pk_mul_f32 v[242:243], v[242:243], s[86:87] op_sel_hi:[1,0]
	v_pk_mul_f32 v[244:245], v[244:245], s[86:87] op_sel_hi:[1,0]
	v_pk_mul_f32 v[246:247], v[246:247], s[86:87] op_sel_hi:[1,0]
	v_pk_mul_f32 v[248:249], v[248:249], s[86:87] op_sel_hi:[1,0]
	v_exp_f32_e32 v242, v242
	v_exp_f32_e32 v243, v243
	v_exp_f32_e32 v244, v244
	v_exp_f32_e32 v245, v245
	v_exp_f32_e32 v246, v246
	v_exp_f32_e32 v247, v247
	v_exp_f32_e32 v248, v248
	v_exp_f32_e32 v249, v249
	v_pk_add_f32 v[242:243], v[242:243], 1.0 op_sel_hi:[1,0]
	v_pk_add_f32 v[244:245], v[244:245], 1.0 op_sel_hi:[1,0]
	v_pk_add_f32 v[246:247], v[246:247], 1.0 op_sel_hi:[1,0]
	v_pk_add_f32 v[248:249], v[248:249], 1.0 op_sel_hi:[1,0]
	v_pk_mul_f32 v[216:217], v[216:217], v[242:243]
	v_pk_mul_f32 v[218:219], v[218:219], v[244:245]
	v_pk_mul_f32 v[220:221], v[220:221], v[246:247]
	v_pk_mul_f32 v[222:223], v[222:223], v[248:249]
	v_pk_mul_f32 v[70:71], v[70:71], v[216:217]
	v_pk_mul_f32 v[72:73], v[72:73], v[218:219]
	v_pk_mul_f32 v[66:67], v[66:67], v[220:221]
	v_pk_mul_f32 v[68:69], v[68:69], v[222:223]
	s_add_u32 s28, s20, 0x478000
	s_addc_u32 s29, s21, 0
	global_load_dwordx4 v[178:181], v253, s[28:29]
	global_load_dwordx4 v[182:185], v254, s[28:29]
	global_load_dwordx4 v[186:189], v253, s[28:29] offset:256
	global_load_dwordx4 v[190:193], v254, s[28:29] offset:256
	s_waitcnt vmcnt(12)
	v_lshlrev_b32_e32 v216, 16, v130
	v_and_b32_e32 v217, 0xffff0000, v130
	v_lshlrev_b32_e32 v218, 16, v131
	v_and_b32_e32 v219, 0xffff0000, v131
	v_lshlrev_b32_e32 v220, 16, v132
	v_and_b32_e32 v221, 0xffff0000, v132
	v_lshlrev_b32_e32 v222, 16, v133
	v_and_b32_e32 v223, 0xffff0000, v133
	v_pk_mul_f32 v[216:217], v[216:217], s[86:87] op_sel_hi:[1,0]
	v_pk_mul_f32 v[218:219], v[218:219], s[86:87] op_sel_hi:[1,0]
	v_pk_mul_f32 v[220:221], v[220:221], s[86:87] op_sel_hi:[1,0]
	v_pk_mul_f32 v[222:223], v[222:223], s[86:87] op_sel_hi:[1,0]
	v_exp_f32_e32 v216, v216
	v_exp_f32_e32 v217, v217
	v_exp_f32_e32 v218, v218
	v_exp_f32_e32 v219, v219
	v_exp_f32_e32 v220, v220
	v_exp_f32_e32 v221, v221
	v_exp_f32_e32 v222, v222
	v_exp_f32_e32 v223, v223
	v_pk_add_f32 v[216:217], v[216:217], 1.0 op_sel_hi:[1,0]
	v_pk_add_f32 v[218:219], v[218:219], 1.0 op_sel_hi:[1,0]
	v_pk_add_f32 v[220:221], v[220:221], 1.0 op_sel_hi:[1,0]
	v_pk_add_f32 v[222:223], v[222:223], 1.0 op_sel_hi:[1,0]
	v_rcp_f32_e32 v216, v216
	v_rcp_f32_e32 v217, v217
	v_rcp_f32_e32 v218, v218
	v_rcp_f32_e32 v219, v219
	v_rcp_f32_e32 v220, v220
	v_rcp_f32_e32 v221, v221
	v_rcp_f32_e32 v222, v222
	v_rcp_f32_e32 v223, v223
	v_lshlrev_b32_e32 v242, 16, v134
	v_and_b32_e32 v243, 0xffff0000, v134
	v_lshlrev_b32_e32 v244, 16, v135
	v_and_b32_e32 v245, 0xffff0000, v135
	v_lshlrev_b32_e32 v246, 16, v136
	v_and_b32_e32 v247, 0xffff0000, v136
	v_lshlrev_b32_e32 v248, 16, v137
	v_and_b32_e32 v249, 0xffff0000, v137
	v_pk_mul_f32 v[242:243], v[242:243], s[86:87] op_sel_hi:[1,0]
	v_pk_mul_f32 v[244:245], v[244:245], s[86:87] op_sel_hi:[1,0]
	v_pk_mul_f32 v[246:247], v[246:247], s[86:87] op_sel_hi:[1,0]
	v_pk_mul_f32 v[248:249], v[248:249], s[86:87] op_sel_hi:[1,0]
	v_exp_f32_e32 v242, v242
	v_exp_f32_e32 v243, v243
	v_exp_f32_e32 v244, v244
	v_exp_f32_e32 v245, v245
	v_exp_f32_e32 v246, v246
	v_exp_f32_e32 v247, v247
	v_exp_f32_e32 v248, v248
	v_exp_f32_e32 v249, v249
	v_pk_add_f32 v[242:243], v[242:243], 1.0 op_sel_hi:[1,0]
	v_pk_add_f32 v[244:245], v[244:245], 1.0 op_sel_hi:[1,0]
	v_pk_add_f32 v[246:247], v[246:247], 1.0 op_sel_hi:[1,0]
	v_pk_add_f32 v[248:249], v[248:249], 1.0 op_sel_hi:[1,0]
	v_pk_mul_f32 v[216:217], v[216:217], v[242:243]
	v_pk_mul_f32 v[218:219], v[218:219], v[244:245]
	v_pk_mul_f32 v[220:221], v[220:221], v[246:247]
	v_pk_mul_f32 v[222:223], v[222:223], v[248:249]
	v_pk_mul_f32 v[62:63], v[62:63], v[216:217]
	v_pk_mul_f32 v[64:65], v[64:65], v[218:219]
	v_pk_mul_f32 v[58:59], v[58:59], v[220:221]
	v_pk_mul_f32 v[60:61], v[60:61], v[222:223]
	v_lshlrev_b32_e32 v216, 16, v138
	v_and_b32_e32 v217, 0xffff0000, v138
	v_lshlrev_b32_e32 v218, 16, v139
	v_and_b32_e32 v219, 0xffff0000, v139
	v_lshlrev_b32_e32 v220, 16, v140
	v_and_b32_e32 v221, 0xffff0000, v140
	v_lshlrev_b32_e32 v222, 16, v141
	v_and_b32_e32 v223, 0xffff0000, v141
	v_pk_mul_f32 v[216:217], v[216:217], s[86:87] op_sel_hi:[1,0]
	v_pk_mul_f32 v[218:219], v[218:219], s[86:87] op_sel_hi:[1,0]
	v_pk_mul_f32 v[220:221], v[220:221], s[86:87] op_sel_hi:[1,0]
	v_pk_mul_f32 v[222:223], v[222:223], s[86:87] op_sel_hi:[1,0]
	v_exp_f32_e32 v216, v216
	v_exp_f32_e32 v217, v217
	v_exp_f32_e32 v218, v218
	v_exp_f32_e32 v219, v219
	v_exp_f32_e32 v220, v220
	v_exp_f32_e32 v221, v221
	v_exp_f32_e32 v222, v222
	v_exp_f32_e32 v223, v223
	v_pk_add_f32 v[216:217], v[216:217], 1.0 op_sel_hi:[1,0]
	v_pk_add_f32 v[218:219], v[218:219], 1.0 op_sel_hi:[1,0]
	v_pk_add_f32 v[220:221], v[220:221], 1.0 op_sel_hi:[1,0]
	v_pk_add_f32 v[222:223], v[222:223], 1.0 op_sel_hi:[1,0]
	v_rcp_f32_e32 v216, v216
	v_rcp_f32_e32 v217, v217
	v_rcp_f32_e32 v218, v218
	v_rcp_f32_e32 v219, v219
	v_rcp_f32_e32 v220, v220
	v_rcp_f32_e32 v221, v221
	v_rcp_f32_e32 v222, v222
	v_rcp_f32_e32 v223, v223
	v_lshlrev_b32_e32 v242, 16, v142
	v_and_b32_e32 v243, 0xffff0000, v142
	v_lshlrev_b32_e32 v244, 16, v143
	v_and_b32_e32 v245, 0xffff0000, v143
	v_lshlrev_b32_e32 v246, 16, v144
	v_and_b32_e32 v247, 0xffff0000, v144
	v_lshlrev_b32_e32 v248, 16, v145
	v_and_b32_e32 v249, 0xffff0000, v145
	v_pk_mul_f32 v[242:243], v[242:243], s[86:87] op_sel_hi:[1,0]
	v_pk_mul_f32 v[244:245], v[244:245], s[86:87] op_sel_hi:[1,0]
	v_pk_mul_f32 v[246:247], v[246:247], s[86:87] op_sel_hi:[1,0]
	v_pk_mul_f32 v[248:249], v[248:249], s[86:87] op_sel_hi:[1,0]
	v_exp_f32_e32 v242, v242
	v_exp_f32_e32 v243, v243
	v_exp_f32_e32 v244, v244
	v_exp_f32_e32 v245, v245
	v_exp_f32_e32 v246, v246
	v_exp_f32_e32 v247, v247
	v_exp_f32_e32 v248, v248
	v_exp_f32_e32 v249, v249
	v_pk_add_f32 v[242:243], v[242:243], 1.0 op_sel_hi:[1,0]
	v_pk_add_f32 v[244:245], v[244:245], 1.0 op_sel_hi:[1,0]
	v_pk_add_f32 v[246:247], v[246:247], 1.0 op_sel_hi:[1,0]
	v_pk_add_f32 v[248:249], v[248:249], 1.0 op_sel_hi:[1,0]
	v_pk_mul_f32 v[216:217], v[216:217], v[242:243]
	v_pk_mul_f32 v[218:219], v[218:219], v[244:245]
	v_pk_mul_f32 v[220:221], v[220:221], v[246:247]
	v_pk_mul_f32 v[222:223], v[222:223], v[248:249]
	v_pk_mul_f32 v[30:31], v[30:31], v[216:217]
	v_pk_mul_f32 v[32:33], v[32:33], v[218:219]
	v_pk_mul_f32 v[26:27], v[26:27], v[220:221]
	v_pk_mul_f32 v[28:29], v[28:29], v[222:223]
	s_waitcnt vmcnt(8)
	v_lshlrev_b32_e32 v216, 16, v146
	v_and_b32_e32 v217, 0xffff0000, v146
	v_lshlrev_b32_e32 v218, 16, v147
	v_and_b32_e32 v219, 0xffff0000, v147
	v_lshlrev_b32_e32 v220, 16, v148
	v_and_b32_e32 v221, 0xffff0000, v148
	v_lshlrev_b32_e32 v222, 16, v149
	v_and_b32_e32 v223, 0xffff0000, v149
	v_pk_mul_f32 v[216:217], v[216:217], s[86:87] op_sel_hi:[1,0]
	v_pk_mul_f32 v[218:219], v[218:219], s[86:87] op_sel_hi:[1,0]
	v_pk_mul_f32 v[220:221], v[220:221], s[86:87] op_sel_hi:[1,0]
	v_pk_mul_f32 v[222:223], v[222:223], s[86:87] op_sel_hi:[1,0]
	v_exp_f32_e32 v216, v216
	v_exp_f32_e32 v217, v217
	v_exp_f32_e32 v218, v218
	v_exp_f32_e32 v219, v219
	v_exp_f32_e32 v220, v220
	v_exp_f32_e32 v221, v221
	v_exp_f32_e32 v222, v222
	v_exp_f32_e32 v223, v223
	v_pk_add_f32 v[216:217], v[216:217], 1.0 op_sel_hi:[1,0]
	v_pk_add_f32 v[218:219], v[218:219], 1.0 op_sel_hi:[1,0]
	v_pk_add_f32 v[220:221], v[220:221], 1.0 op_sel_hi:[1,0]
	v_pk_add_f32 v[222:223], v[222:223], 1.0 op_sel_hi:[1,0]
	v_rcp_f32_e32 v216, v216
	v_rcp_f32_e32 v217, v217
	v_rcp_f32_e32 v218, v218
	v_rcp_f32_e32 v219, v219
	v_rcp_f32_e32 v220, v220
	v_rcp_f32_e32 v221, v221
	v_rcp_f32_e32 v222, v222
	v_rcp_f32_e32 v223, v223
	v_lshlrev_b32_e32 v242, 16, v150
	v_and_b32_e32 v243, 0xffff0000, v150
	v_lshlrev_b32_e32 v244, 16, v151
	v_and_b32_e32 v245, 0xffff0000, v151
	v_lshlrev_b32_e32 v246, 16, v152
	v_and_b32_e32 v247, 0xffff0000, v152
	v_lshlrev_b32_e32 v248, 16, v153
	v_and_b32_e32 v249, 0xffff0000, v153
	v_pk_mul_f32 v[242:243], v[242:243], s[86:87] op_sel_hi:[1,0]
	v_pk_mul_f32 v[244:245], v[244:245], s[86:87] op_sel_hi:[1,0]
	v_pk_mul_f32 v[246:247], v[246:247], s[86:87] op_sel_hi:[1,0]
	v_pk_mul_f32 v[248:249], v[248:249], s[86:87] op_sel_hi:[1,0]
	v_exp_f32_e32 v242, v242
	v_exp_f32_e32 v243, v243
	v_exp_f32_e32 v244, v244
	v_exp_f32_e32 v245, v245
	v_exp_f32_e32 v246, v246
	v_exp_f32_e32 v247, v247
	v_exp_f32_e32 v248, v248
	v_exp_f32_e32 v249, v249
	v_pk_add_f32 v[242:243], v[242:243], 1.0 op_sel_hi:[1,0]
	v_pk_add_f32 v[244:245], v[244:245], 1.0 op_sel_hi:[1,0]
	v_pk_add_f32 v[246:247], v[246:247], 1.0 op_sel_hi:[1,0]
	v_pk_add_f32 v[248:249], v[248:249], 1.0 op_sel_hi:[1,0]
	v_pk_mul_f32 v[216:217], v[216:217], v[242:243]
	v_pk_mul_f32 v[218:219], v[218:219], v[244:245]
	v_pk_mul_f32 v[220:221], v[220:221], v[246:247]
	v_pk_mul_f32 v[222:223], v[222:223], v[248:249]
	v_pk_mul_f32 v[54:55], v[54:55], v[216:217]
	v_pk_mul_f32 v[56:57], v[56:57], v[218:219]
	v_pk_mul_f32 v[50:51], v[50:51], v[220:221]
	v_pk_mul_f32 v[52:53], v[52:53], v[222:223]
	v_lshlrev_b32_e32 v216, 16, v154
	v_and_b32_e32 v217, 0xffff0000, v154
	v_lshlrev_b32_e32 v218, 16, v155
	v_and_b32_e32 v219, 0xffff0000, v155
	v_lshlrev_b32_e32 v220, 16, v156
	v_and_b32_e32 v221, 0xffff0000, v156
	v_lshlrev_b32_e32 v222, 16, v157
	v_and_b32_e32 v223, 0xffff0000, v157
	v_pk_mul_f32 v[216:217], v[216:217], s[86:87] op_sel_hi:[1,0]
	v_pk_mul_f32 v[218:219], v[218:219], s[86:87] op_sel_hi:[1,0]
	v_pk_mul_f32 v[220:221], v[220:221], s[86:87] op_sel_hi:[1,0]
	v_pk_mul_f32 v[222:223], v[222:223], s[86:87] op_sel_hi:[1,0]
	v_exp_f32_e32 v216, v216
	v_exp_f32_e32 v217, v217
	v_exp_f32_e32 v218, v218
	v_exp_f32_e32 v219, v219
	v_exp_f32_e32 v220, v220
	v_exp_f32_e32 v221, v221
	v_exp_f32_e32 v222, v222
	v_exp_f32_e32 v223, v223
	v_pk_add_f32 v[216:217], v[216:217], 1.0 op_sel_hi:[1,0]
	v_pk_add_f32 v[218:219], v[218:219], 1.0 op_sel_hi:[1,0]
	v_pk_add_f32 v[220:221], v[220:221], 1.0 op_sel_hi:[1,0]
	v_pk_add_f32 v[222:223], v[222:223], 1.0 op_sel_hi:[1,0]
	v_rcp_f32_e32 v216, v216
	v_rcp_f32_e32 v217, v217
	v_rcp_f32_e32 v218, v218
	v_rcp_f32_e32 v219, v219
	v_rcp_f32_e32 v220, v220
	v_rcp_f32_e32 v221, v221
	v_rcp_f32_e32 v222, v222
	v_rcp_f32_e32 v223, v223
	v_lshlrev_b32_e32 v242, 16, v158
	v_and_b32_e32 v243, 0xffff0000, v158
	v_lshlrev_b32_e32 v244, 16, v159
	v_and_b32_e32 v245, 0xffff0000, v159
	v_lshlrev_b32_e32 v246, 16, v160
	v_and_b32_e32 v247, 0xffff0000, v160
	v_lshlrev_b32_e32 v248, 16, v161
	v_and_b32_e32 v249, 0xffff0000, v161
	v_pk_mul_f32 v[242:243], v[242:243], s[86:87] op_sel_hi:[1,0]
	v_pk_mul_f32 v[244:245], v[244:245], s[86:87] op_sel_hi:[1,0]
	v_pk_mul_f32 v[246:247], v[246:247], s[86:87] op_sel_hi:[1,0]
	v_pk_mul_f32 v[248:249], v[248:249], s[86:87] op_sel_hi:[1,0]
	v_exp_f32_e32 v242, v242
	v_exp_f32_e32 v243, v243
	v_exp_f32_e32 v244, v244
	v_exp_f32_e32 v245, v245
	v_exp_f32_e32 v246, v246
	v_exp_f32_e32 v247, v247
	v_exp_f32_e32 v248, v248
	v_exp_f32_e32 v249, v249
	v_pk_add_f32 v[242:243], v[242:243], 1.0 op_sel_hi:[1,0]
	v_pk_add_f32 v[244:245], v[244:245], 1.0 op_sel_hi:[1,0]
	v_pk_add_f32 v[246:247], v[246:247], 1.0 op_sel_hi:[1,0]
	v_pk_add_f32 v[248:249], v[248:249], 1.0 op_sel_hi:[1,0]
	v_pk_mul_f32 v[216:217], v[216:217], v[242:243]
	v_pk_mul_f32 v[218:219], v[218:219], v[244:245]
	v_pk_mul_f32 v[220:221], v[220:221], v[246:247]
	v_pk_mul_f32 v[222:223], v[222:223], v[248:249]
	v_pk_mul_f32 v[22:23], v[22:23], v[216:217]
	v_pk_mul_f32 v[24:25], v[24:25], v[218:219]
	v_pk_mul_f32 v[18:19], v[18:19], v[220:221]
	v_pk_mul_f32 v[20:21], v[20:21], v[222:223]
	s_waitcnt vmcnt(4)
	v_lshlrev_b32_e32 v216, 16, v162
	v_and_b32_e32 v217, 0xffff0000, v162
	v_lshlrev_b32_e32 v218, 16, v163
	v_and_b32_e32 v219, 0xffff0000, v163
	v_lshlrev_b32_e32 v220, 16, v164
	v_and_b32_e32 v221, 0xffff0000, v164
	v_lshlrev_b32_e32 v222, 16, v165
	v_and_b32_e32 v223, 0xffff0000, v165
	v_pk_mul_f32 v[216:217], v[216:217], s[86:87] op_sel_hi:[1,0]
	v_pk_mul_f32 v[218:219], v[218:219], s[86:87] op_sel_hi:[1,0]
	v_pk_mul_f32 v[220:221], v[220:221], s[86:87] op_sel_hi:[1,0]
	v_pk_mul_f32 v[222:223], v[222:223], s[86:87] op_sel_hi:[1,0]
	v_exp_f32_e32 v216, v216
	v_exp_f32_e32 v217, v217
	v_exp_f32_e32 v218, v218
	v_exp_f32_e32 v219, v219
	v_exp_f32_e32 v220, v220
	v_exp_f32_e32 v221, v221
	v_exp_f32_e32 v222, v222
	v_exp_f32_e32 v223, v223
	v_pk_add_f32 v[216:217], v[216:217], 1.0 op_sel_hi:[1,0]
	v_pk_add_f32 v[218:219], v[218:219], 1.0 op_sel_hi:[1,0]
	v_pk_add_f32 v[220:221], v[220:221], 1.0 op_sel_hi:[1,0]
	v_pk_add_f32 v[222:223], v[222:223], 1.0 op_sel_hi:[1,0]
	v_rcp_f32_e32 v216, v216
	v_rcp_f32_e32 v217, v217
	v_rcp_f32_e32 v218, v218
	v_rcp_f32_e32 v219, v219
	v_rcp_f32_e32 v220, v220
	v_rcp_f32_e32 v221, v221
	v_rcp_f32_e32 v222, v222
	v_rcp_f32_e32 v223, v223
	v_lshlrev_b32_e32 v242, 16, v166
	v_and_b32_e32 v243, 0xffff0000, v166
	v_lshlrev_b32_e32 v244, 16, v167
	v_and_b32_e32 v245, 0xffff0000, v167
	v_lshlrev_b32_e32 v246, 16, v168
	v_and_b32_e32 v247, 0xffff0000, v168
	v_lshlrev_b32_e32 v248, 16, v169
	v_and_b32_e32 v249, 0xffff0000, v169
	v_pk_mul_f32 v[242:243], v[242:243], s[86:87] op_sel_hi:[1,0]
	v_pk_mul_f32 v[244:245], v[244:245], s[86:87] op_sel_hi:[1,0]
	v_pk_mul_f32 v[246:247], v[246:247], s[86:87] op_sel_hi:[1,0]
	v_pk_mul_f32 v[248:249], v[248:249], s[86:87] op_sel_hi:[1,0]
	v_exp_f32_e32 v242, v242
	v_exp_f32_e32 v243, v243
	v_exp_f32_e32 v244, v244
	v_exp_f32_e32 v245, v245
	v_exp_f32_e32 v246, v246
	v_exp_f32_e32 v247, v247
	v_exp_f32_e32 v248, v248
	v_exp_f32_e32 v249, v249
	v_pk_add_f32 v[242:243], v[242:243], 1.0 op_sel_hi:[1,0]
	v_pk_add_f32 v[244:245], v[244:245], 1.0 op_sel_hi:[1,0]
	v_pk_add_f32 v[246:247], v[246:247], 1.0 op_sel_hi:[1,0]
	v_pk_add_f32 v[248:249], v[248:249], 1.0 op_sel_hi:[1,0]
	v_pk_mul_f32 v[216:217], v[216:217], v[242:243]
	v_pk_mul_f32 v[218:219], v[218:219], v[244:245]
	v_pk_mul_f32 v[220:221], v[220:221], v[246:247]
	v_pk_mul_f32 v[222:223], v[222:223], v[248:249]
	v_pk_mul_f32 v[46:47], v[46:47], v[216:217]
	v_pk_mul_f32 v[48:49], v[48:49], v[218:219]
	v_pk_mul_f32 v[42:43], v[42:43], v[220:221]
	v_pk_mul_f32 v[44:45], v[44:45], v[222:223]
	v_lshlrev_b32_e32 v216, 16, v170
	v_and_b32_e32 v217, 0xffff0000, v170
	v_lshlrev_b32_e32 v218, 16, v171
	v_and_b32_e32 v219, 0xffff0000, v171
	v_lshlrev_b32_e32 v220, 16, v172
	v_and_b32_e32 v221, 0xffff0000, v172
	v_lshlrev_b32_e32 v222, 16, v173
	v_and_b32_e32 v223, 0xffff0000, v173
	v_pk_mul_f32 v[216:217], v[216:217], s[86:87] op_sel_hi:[1,0]
	v_pk_mul_f32 v[218:219], v[218:219], s[86:87] op_sel_hi:[1,0]
	v_pk_mul_f32 v[220:221], v[220:221], s[86:87] op_sel_hi:[1,0]
	v_pk_mul_f32 v[222:223], v[222:223], s[86:87] op_sel_hi:[1,0]
	v_exp_f32_e32 v216, v216
	v_exp_f32_e32 v217, v217
	v_exp_f32_e32 v218, v218
	v_exp_f32_e32 v219, v219
	v_exp_f32_e32 v220, v220
	v_exp_f32_e32 v221, v221
	v_exp_f32_e32 v222, v222
	v_exp_f32_e32 v223, v223
	v_pk_add_f32 v[216:217], v[216:217], 1.0 op_sel_hi:[1,0]
	v_pk_add_f32 v[218:219], v[218:219], 1.0 op_sel_hi:[1,0]
	v_pk_add_f32 v[220:221], v[220:221], 1.0 op_sel_hi:[1,0]
	v_pk_add_f32 v[222:223], v[222:223], 1.0 op_sel_hi:[1,0]
	v_rcp_f32_e32 v216, v216
	v_rcp_f32_e32 v217, v217
	v_rcp_f32_e32 v218, v218
	v_rcp_f32_e32 v219, v219
	v_rcp_f32_e32 v220, v220
	v_rcp_f32_e32 v221, v221
	v_rcp_f32_e32 v222, v222
	v_rcp_f32_e32 v223, v223
	v_lshlrev_b32_e32 v242, 16, v174
	v_and_b32_e32 v243, 0xffff0000, v174
	v_lshlrev_b32_e32 v244, 16, v175
	v_and_b32_e32 v245, 0xffff0000, v175
	v_lshlrev_b32_e32 v246, 16, v176
	v_and_b32_e32 v247, 0xffff0000, v176
	v_lshlrev_b32_e32 v248, 16, v177
	v_and_b32_e32 v249, 0xffff0000, v177
	v_pk_mul_f32 v[242:243], v[242:243], s[86:87] op_sel_hi:[1,0]
	v_pk_mul_f32 v[244:245], v[244:245], s[86:87] op_sel_hi:[1,0]
	v_pk_mul_f32 v[246:247], v[246:247], s[86:87] op_sel_hi:[1,0]
	v_pk_mul_f32 v[248:249], v[248:249], s[86:87] op_sel_hi:[1,0]
	v_exp_f32_e32 v242, v242
	v_exp_f32_e32 v243, v243
	v_exp_f32_e32 v244, v244
	v_exp_f32_e32 v245, v245
	v_exp_f32_e32 v246, v246
	v_exp_f32_e32 v247, v247
	v_exp_f32_e32 v248, v248
	v_exp_f32_e32 v249, v249
	v_pk_add_f32 v[242:243], v[242:243], 1.0 op_sel_hi:[1,0]
	v_pk_add_f32 v[244:245], v[244:245], 1.0 op_sel_hi:[1,0]
	v_pk_add_f32 v[246:247], v[246:247], 1.0 op_sel_hi:[1,0]
	v_pk_add_f32 v[248:249], v[248:249], 1.0 op_sel_hi:[1,0]
	v_pk_mul_f32 v[216:217], v[216:217], v[242:243]
	v_pk_mul_f32 v[218:219], v[218:219], v[244:245]
	v_pk_mul_f32 v[220:221], v[220:221], v[246:247]
	v_pk_mul_f32 v[222:223], v[222:223], v[248:249]
	v_pk_mul_f32 v[14:15], v[14:15], v[216:217]
	v_pk_mul_f32 v[16:17], v[16:17], v[218:219]
	v_pk_mul_f32 v[10:11], v[10:11], v[220:221]
	v_pk_mul_f32 v[12:13], v[12:13], v[222:223]
	s_waitcnt vmcnt(0)
	v_lshlrev_b32_e32 v216, 16, v178
	v_and_b32_e32 v217, 0xffff0000, v178
	v_lshlrev_b32_e32 v218, 16, v179
	v_and_b32_e32 v219, 0xffff0000, v179
	v_lshlrev_b32_e32 v220, 16, v180
	v_and_b32_e32 v221, 0xffff0000, v180
	v_lshlrev_b32_e32 v222, 16, v181
	v_and_b32_e32 v223, 0xffff0000, v181
	v_pk_mul_f32 v[216:217], v[216:217], s[86:87] op_sel_hi:[1,0]
	v_pk_mul_f32 v[218:219], v[218:219], s[86:87] op_sel_hi:[1,0]
	v_pk_mul_f32 v[220:221], v[220:221], s[86:87] op_sel_hi:[1,0]
	v_pk_mul_f32 v[222:223], v[222:223], s[86:87] op_sel_hi:[1,0]
	v_exp_f32_e32 v216, v216
	v_exp_f32_e32 v217, v217
	v_exp_f32_e32 v218, v218
	v_exp_f32_e32 v219, v219
	v_exp_f32_e32 v220, v220
	v_exp_f32_e32 v221, v221
	v_exp_f32_e32 v222, v222
	v_exp_f32_e32 v223, v223
	v_pk_add_f32 v[216:217], v[216:217], 1.0 op_sel_hi:[1,0]
	v_pk_add_f32 v[218:219], v[218:219], 1.0 op_sel_hi:[1,0]
	v_pk_add_f32 v[220:221], v[220:221], 1.0 op_sel_hi:[1,0]
	v_pk_add_f32 v[222:223], v[222:223], 1.0 op_sel_hi:[1,0]
	v_rcp_f32_e32 v216, v216
	v_rcp_f32_e32 v217, v217
	v_rcp_f32_e32 v218, v218
	v_rcp_f32_e32 v219, v219
	v_rcp_f32_e32 v220, v220
	v_rcp_f32_e32 v221, v221
	v_rcp_f32_e32 v222, v222
	v_rcp_f32_e32 v223, v223
	v_lshlrev_b32_e32 v242, 16, v182
	v_and_b32_e32 v243, 0xffff0000, v182
	v_lshlrev_b32_e32 v244, 16, v183
	v_and_b32_e32 v245, 0xffff0000, v183
	v_lshlrev_b32_e32 v246, 16, v184
	v_and_b32_e32 v247, 0xffff0000, v184
	v_lshlrev_b32_e32 v248, 16, v185
	v_and_b32_e32 v249, 0xffff0000, v185
	v_pk_mul_f32 v[242:243], v[242:243], s[86:87] op_sel_hi:[1,0]
	v_pk_mul_f32 v[244:245], v[244:245], s[86:87] op_sel_hi:[1,0]
	v_pk_mul_f32 v[246:247], v[246:247], s[86:87] op_sel_hi:[1,0]
	v_pk_mul_f32 v[248:249], v[248:249], s[86:87] op_sel_hi:[1,0]
	v_exp_f32_e32 v242, v242
	v_exp_f32_e32 v243, v243
	v_exp_f32_e32 v244, v244
	v_exp_f32_e32 v245, v245
	v_exp_f32_e32 v246, v246
	v_exp_f32_e32 v247, v247
	v_exp_f32_e32 v248, v248
	v_exp_f32_e32 v249, v249
	v_pk_add_f32 v[242:243], v[242:243], 1.0 op_sel_hi:[1,0]
	v_pk_add_f32 v[244:245], v[244:245], 1.0 op_sel_hi:[1,0]
	v_pk_add_f32 v[246:247], v[246:247], 1.0 op_sel_hi:[1,0]
	v_pk_add_f32 v[248:249], v[248:249], 1.0 op_sel_hi:[1,0]
	v_pk_mul_f32 v[216:217], v[216:217], v[242:243]
	v_pk_mul_f32 v[218:219], v[218:219], v[244:245]
	v_pk_mul_f32 v[220:221], v[220:221], v[246:247]
	v_pk_mul_f32 v[222:223], v[222:223], v[248:249]
	v_pk_mul_f32 v[38:39], v[38:39], v[216:217]
	v_pk_mul_f32 v[40:41], v[40:41], v[218:219]
	v_pk_mul_f32 v[34:35], v[34:35], v[220:221]
	v_pk_mul_f32 v[36:37], v[36:37], v[222:223]
	v_lshlrev_b32_e32 v216, 16, v186
	v_and_b32_e32 v217, 0xffff0000, v186
	v_lshlrev_b32_e32 v218, 16, v187
	v_and_b32_e32 v219, 0xffff0000, v187
	v_lshlrev_b32_e32 v220, 16, v188
	v_and_b32_e32 v221, 0xffff0000, v188
	v_lshlrev_b32_e32 v222, 16, v189
	v_and_b32_e32 v223, 0xffff0000, v189
	v_pk_mul_f32 v[216:217], v[216:217], s[86:87] op_sel_hi:[1,0]
	v_pk_mul_f32 v[218:219], v[218:219], s[86:87] op_sel_hi:[1,0]
	v_pk_mul_f32 v[220:221], v[220:221], s[86:87] op_sel_hi:[1,0]
	v_pk_mul_f32 v[222:223], v[222:223], s[86:87] op_sel_hi:[1,0]
	v_exp_f32_e32 v216, v216
	v_exp_f32_e32 v217, v217
	v_exp_f32_e32 v218, v218
	v_exp_f32_e32 v219, v219
	v_exp_f32_e32 v220, v220
	v_exp_f32_e32 v221, v221
	v_exp_f32_e32 v222, v222
	v_exp_f32_e32 v223, v223
	v_pk_add_f32 v[216:217], v[216:217], 1.0 op_sel_hi:[1,0]
	v_pk_add_f32 v[218:219], v[218:219], 1.0 op_sel_hi:[1,0]
	v_pk_add_f32 v[220:221], v[220:221], 1.0 op_sel_hi:[1,0]
	v_pk_add_f32 v[222:223], v[222:223], 1.0 op_sel_hi:[1,0]
	v_rcp_f32_e32 v216, v216
	v_rcp_f32_e32 v217, v217
	v_rcp_f32_e32 v218, v218
	v_rcp_f32_e32 v219, v219
	v_rcp_f32_e32 v220, v220
	v_rcp_f32_e32 v221, v221
	v_rcp_f32_e32 v222, v222
	v_rcp_f32_e32 v223, v223
	v_lshlrev_b32_e32 v242, 16, v190
	v_and_b32_e32 v243, 0xffff0000, v190
	v_lshlrev_b32_e32 v244, 16, v191
	v_and_b32_e32 v245, 0xffff0000, v191
	v_lshlrev_b32_e32 v246, 16, v192
	v_and_b32_e32 v247, 0xffff0000, v192
	v_lshlrev_b32_e32 v248, 16, v193
	v_and_b32_e32 v249, 0xffff0000, v193
	v_pk_mul_f32 v[242:243], v[242:243], s[86:87] op_sel_hi:[1,0]
	v_pk_mul_f32 v[244:245], v[244:245], s[86:87] op_sel_hi:[1,0]
	v_pk_mul_f32 v[246:247], v[246:247], s[86:87] op_sel_hi:[1,0]
	v_pk_mul_f32 v[248:249], v[248:249], s[86:87] op_sel_hi:[1,0]
	v_exp_f32_e32 v242, v242
	v_exp_f32_e32 v243, v243
	v_exp_f32_e32 v244, v244
	v_exp_f32_e32 v245, v245
	v_exp_f32_e32 v246, v246
	v_exp_f32_e32 v247, v247
	v_exp_f32_e32 v248, v248
	v_exp_f32_e32 v249, v249
	v_pk_add_f32 v[242:243], v[242:243], 1.0 op_sel_hi:[1,0]
	v_pk_add_f32 v[244:245], v[244:245], 1.0 op_sel_hi:[1,0]
	v_pk_add_f32 v[246:247], v[246:247], 1.0 op_sel_hi:[1,0]
	v_pk_add_f32 v[248:249], v[248:249], 1.0 op_sel_hi:[1,0]
	v_pk_mul_f32 v[216:217], v[216:217], v[242:243]
	v_pk_mul_f32 v[218:219], v[218:219], v[244:245]
	v_pk_mul_f32 v[220:221], v[220:221], v[246:247]
	v_pk_mul_f32 v[222:223], v[222:223], v[248:249]
	v_pk_mul_f32 v[6:7], v[6:7], v[216:217]
	v_pk_mul_f32 v[8:9], v[8:9], v[218:219]
	v_pk_mul_f32 v[2:3], v[2:3], v[220:221]
	v_pk_mul_f32 v[4:5], v[4:5], v[222:223]
	s_branch .Lem_done

.LBB0_504:
	v_add_u32_e32 v253, 0x10000, v163
	ds_read_b128 v[130:133], v253
	ds_read_b128 v[134:137], v253 offset:1024
	ds_read_b128 v[150:153], v253 offset:2048
	ds_read_b128 v[154:157], v253 offset:3072
	s_add_u32 s10, s52, 0xfff80080
	s_addc_u32 s11, s53, -1
	s_cmp_eq_u32 s29, 28
	s_cselect_b32 s11, s9, s11
	s_cselect_b32 s10, s8, s10
	s_cselect_b32 s55, s35, s7
	s_cselect_b32 s54, s34, s5
	s_add_i32 m0, s42, 0xc000
	ds_read_b128 v[158:161], v162
	ds_read_b128 v[166:169], v162 offset:1024
	ds_read_b128 v[170:173], v162 offset:2048
	ds_read_b128 v[174:177], v162 offset:3072
	ds_read_b128 v[178:181], v162 offset:4096
	ds_read_b128 v[182:185], v162 offset:5120
	ds_read_b128 v[186:189], v162 offset:6144
	ds_read_b128 v[190:193], v162 offset:7168
	global_load_lds_dwordx4 v146, s[52:53]
	s_add_i32 m0, s42, 0xe000
	s_nop 0
	global_load_lds_dwordx4 v148, s[52:53]
	s_waitcnt lgkmcnt(8)
	s_setprio 1
	s_barrier
	s_waitcnt lgkmcnt(0)
	v_mfma_f32_16x16x32_bf16 v[126:129], v[130:133], v[158:161], v[126:129]
	v_mfma_f32_16x16x32_bf16 v[122:125], v[150:153], v[158:161], v[122:125]
	v_mfma_f32_16x16x32_bf16 v[118:121], v[130:133], v[170:173], v[118:121]
	v_mfma_f32_16x16x32_bf16 v[114:117], v[150:153], v[170:173], v[114:117]
	v_mfma_f32_16x16x32_bf16 v[110:113], v[130:133], v[178:181], v[110:113]
	v_mfma_f32_16x16x32_bf16 v[106:109], v[150:153], v[178:181], v[106:109]
	v_mfma_f32_16x16x32_bf16 v[102:105], v[130:133], v[186:189], v[102:105]
	v_mfma_f32_16x16x32_bf16 v[98:101], v[150:153], v[186:189], v[98:101]
	v_mfma_f32_16x16x32_bf16 v[126:129], v[134:137], v[166:169], v[126:129]
	v_mfma_f32_16x16x32_bf16 v[122:125], v[154:157], v[166:169], v[122:125]
	v_mfma_f32_16x16x32_bf16 v[118:121], v[134:137], v[174:177], v[118:121]
	v_mfma_f32_16x16x32_bf16 v[114:117], v[154:157], v[174:177], v[114:117]
	v_mfma_f32_16x16x32_bf16 v[110:113], v[134:137], v[182:185], v[110:113]
	v_mfma_f32_16x16x32_bf16 v[106:109], v[154:157], v[182:185], v[106:109]
	v_mfma_f32_16x16x32_bf16 v[102:105], v[134:137], v[190:193], v[102:105]
	v_mfma_f32_16x16x32_bf16 v[98:101], v[154:157], v[190:193], v[98:101]
	s_barrier
	s_setprio 0
	s_mov_b32 m0, s41
	ds_read_b128 v[206:209], v253 offset:16384
	ds_read_b128 v[210:213], v253 offset:17408
	v_lshl_add_u64 v[222:223], s[54:55], 0, v[194:195]
	ds_read_b128 v[214:217], v253 offset:18432
	ds_read_b128 v[218:221], v253 offset:19456
	global_load_lds_dwordx4 v[222:223], off
	v_lshl_add_u64 v[224:225], s[54:55], 0, v[138:139]
	s_mov_b32 m0, s57
	s_nop 0
	global_load_lds_dwordx4 v[224:225], off
	s_setprio 1
	s_barrier
	s_waitcnt lgkmcnt(0)
	v_mfma_f32_16x16x32_bf16 v[62:65], v[206:209], v[158:161], v[62:65]
	v_mfma_f32_16x16x32_bf16 v[58:61], v[214:217], v[158:161], v[58:61]
	v_mfma_f32_16x16x32_bf16 v[54:57], v[206:209], v[170:173], v[54:57]
	v_mfma_f32_16x16x32_bf16 v[46:49], v[214:217], v[170:173], v[46:49]
	v_mfma_f32_16x16x32_bf16 v[50:53], v[206:209], v[178:181], v[50:53]
	v_mfma_f32_16x16x32_bf16 v[42:45], v[214:217], v[178:181], v[42:45]
	v_mfma_f32_16x16x32_bf16 v[38:41], v[206:209], v[186:189], v[38:41]
	v_mfma_f32_16x16x32_bf16 v[34:37], v[214:217], v[186:189], v[34:37]
	v_mfma_f32_16x16x32_bf16 v[62:65], v[210:213], v[166:169], v[62:65]
	v_mfma_f32_16x16x32_bf16 v[58:61], v[218:221], v[166:169], v[58:61]
	v_mfma_f32_16x16x32_bf16 v[54:57], v[210:213], v[174:177], v[54:57]
	v_mfma_f32_16x16x32_bf16 v[46:49], v[218:221], v[174:177], v[46:49]
	v_mfma_f32_16x16x32_bf16 v[50:53], v[210:213], v[182:185], v[50:53]
	v_mfma_f32_16x16x32_bf16 v[42:45], v[218:221], v[182:185], v[42:45]
	s_mov_b32 m0, s42
	v_mfma_f32_16x16x32_bf16 v[38:41], v[210:213], v[190:193], v[38:41]
	v_lshl_add_u64 v[226:227], s[10:11], 0, v[142:143]
	v_mfma_f32_16x16x32_bf16 v[34:37], v[218:221], v[190:193], v[34:37]
	s_barrier
	s_setprio 0
	ds_read_b128 v[158:161], v162 offset:16384
	ds_read_b128 v[166:169], v162 offset:17408
	ds_read_b128 v[170:173], v162 offset:18432
	ds_read_b128 v[174:177], v162 offset:19456
	ds_read_b128 v[178:181], v162 offset:20480
	ds_read_b128 v[182:185], v162 offset:21504
	ds_read_b128 v[186:189], v162 offset:22528
	ds_read_b128 v[190:193], v162 offset:23552
	global_load_lds_dwordx4 v[226:227], off
	v_lshl_add_u64 v[228:229], s[10:11], 0, v[140:141]
	s_mov_b32 m0, s58
	s_nop 0
	global_load_lds_dwordx4 v[228:229], off
	s_setprio 1
	s_barrier
	s_waitcnt lgkmcnt(0)
	v_mfma_f32_16x16x32_bf16 v[94:97], v[130:133], v[158:161], v[94:97]
	v_mfma_f32_16x16x32_bf16 v[90:93], v[150:153], v[158:161], v[90:93]
	v_mfma_f32_16x16x32_bf16 v[86:89], v[130:133], v[170:173], v[86:89]
	v_mfma_f32_16x16x32_bf16 v[82:85], v[150:153], v[170:173], v[82:85]
	v_mfma_f32_16x16x32_bf16 v[78:81], v[130:133], v[178:181], v[78:81]
	v_mfma_f32_16x16x32_bf16 v[74:77], v[150:153], v[178:181], v[74:77]
	v_mfma_f32_16x16x32_bf16 v[70:73], v[130:133], v[186:189], v[70:73]
	v_mfma_f32_16x16x32_bf16 v[66:69], v[150:153], v[186:189], v[66:69]
	v_mfma_f32_16x16x32_bf16 v[94:97], v[134:137], v[166:169], v[94:97]
	v_mfma_f32_16x16x32_bf16 v[90:93], v[154:157], v[166:169], v[90:93]
	v_mfma_f32_16x16x32_bf16 v[86:89], v[134:137], v[174:177], v[86:89]
	v_mfma_f32_16x16x32_bf16 v[82:85], v[154:157], v[174:177], v[82:85]
	v_mfma_f32_16x16x32_bf16 v[78:81], v[134:137], v[182:185], v[78:81]
	v_mfma_f32_16x16x32_bf16 v[74:77], v[154:157], v[182:185], v[74:77]
	v_mfma_f32_16x16x32_bf16 v[70:73], v[134:137], v[190:193], v[70:73]
	v_mfma_f32_16x16x32_bf16 v[66:69], v[154:157], v[190:193], v[66:69]
	s_barrier
	s_setprio 0
	s_add_u32 s86, s54, 0x80000
	s_addc_u32 s87, s55, 0
	s_mov_b32 m0, s59
	s_nop 0
	global_load_lds_dwordx4 v194, s[86:87]
	s_mov_b32 m0, s60
	s_nop 0
	global_load_lds_dwordx4 v138, s[86:87]
	s_waitcnt vmcnt(6)
	s_setprio 1
	s_barrier
	v_mfma_f32_16x16x32_bf16 v[30:33], v[206:209], v[158:161], v[30:33]
	v_mfma_f32_16x16x32_bf16 v[18:21], v[214:217], v[158:161], v[18:21]
	v_mfma_f32_16x16x32_bf16 v[26:29], v[206:209], v[170:173], v[26:29]
	v_mfma_f32_16x16x32_bf16 v[14:17], v[214:217], v[170:173], v[14:17]
	v_mfma_f32_16x16x32_bf16 v[22:25], v[206:209], v[178:181], v[22:25]
	v_mfma_f32_16x16x32_bf16 v[6:9], v[214:217], v[178:181], v[6:9]
	v_mfma_f32_16x16x32_bf16 v[10:13], v[206:209], v[186:189], v[10:13]
	v_mfma_f32_16x16x32_bf16 v[2:5], v[214:217], v[186:189], v[2:5]
	v_mfma_f32_16x16x32_bf16 v[30:33], v[210:213], v[166:169], v[30:33]
	v_mfma_f32_16x16x32_bf16 v[18:21], v[218:221], v[166:169], v[18:21]
	v_mfma_f32_16x16x32_bf16 v[26:29], v[210:213], v[174:177], v[26:29]
	v_mfma_f32_16x16x32_bf16 v[14:17], v[218:221], v[174:177], v[14:17]
	v_mfma_f32_16x16x32_bf16 v[22:25], v[210:213], v[182:185], v[22:25]
	v_mfma_f32_16x16x32_bf16 v[6:9], v[218:221], v[182:185], v[6:9]
	v_mfma_f32_16x16x32_bf16 v[10:13], v[210:213], v[190:193], v[10:13]
	v_mfma_f32_16x16x32_bf16 v[2:5], v[218:221], v[190:193], v[2:5]
	s_barrier
	s_setprio 0
	ds_read_b128 v[130:133], v253 offset:32768
	ds_read_b128 v[134:137], v253 offset:33792
	ds_read_b128 v[150:153], v253 offset:34816
	ds_read_b128 v[154:157], v253 offset:35840
	s_add_u32 s10, s10, 0x80000
	s_addc_u32 s11, s11, 0
	s_mov_b32 m0, s61
	ds_read_b128 v[158:161], v162 offset:32768
	ds_read_b128 v[166:169], v162 offset:33792
	ds_read_b128 v[170:173], v162 offset:34816
	ds_read_b128 v[174:177], v162 offset:35840
	ds_read_b128 v[178:181], v162 offset:36864
	ds_read_b128 v[182:185], v162 offset:37888
	ds_read_b128 v[186:189], v162 offset:38912
	ds_read_b128 v[190:193], v162 offset:39936
	global_load_lds_dwordx4 v142, s[10:11]
	s_mov_b32 m0, s62
	s_nop 0
	global_load_lds_dwordx4 v140, s[10:11]
	s_waitcnt lgkmcnt(8)
	s_setprio 1
	s_barrier
	s_waitcnt lgkmcnt(0)
	v_mfma_f32_16x16x32_bf16 v[126:129], v[130:133], v[158:161], v[126:129]
	v_mfma_f32_16x16x32_bf16 v[122:125], v[150:153], v[158:161], v[122:125]
	v_mfma_f32_16x16x32_bf16 v[118:121], v[130:133], v[170:173], v[118:121]
	v_mfma_f32_16x16x32_bf16 v[114:117], v[150:153], v[170:173], v[114:117]
	v_mfma_f32_16x16x32_bf16 v[110:113], v[130:133], v[178:181], v[110:113]
	v_mfma_f32_16x16x32_bf16 v[106:109], v[150:153], v[178:181], v[106:109]
	v_mfma_f32_16x16x32_bf16 v[102:105], v[130:133], v[186:189], v[102:105]
	v_mfma_f32_16x16x32_bf16 v[98:101], v[150:153], v[186:189], v[98:101]
	v_mfma_f32_16x16x32_bf16 v[126:129], v[134:137], v[166:169], v[126:129]
	v_mfma_f32_16x16x32_bf16 v[122:125], v[154:157], v[166:169], v[122:125]
	v_mfma_f32_16x16x32_bf16 v[118:121], v[134:137], v[174:177], v[118:121]
	v_mfma_f32_16x16x32_bf16 v[114:117], v[154:157], v[174:177], v[114:117]
	v_mfma_f32_16x16x32_bf16 v[110:113], v[134:137], v[182:185], v[110:113]
	v_mfma_f32_16x16x32_bf16 v[106:109], v[154:157], v[182:185], v[106:109]
	v_mfma_f32_16x16x32_bf16 v[102:105], v[134:137], v[190:193], v[102:105]
	v_mfma_f32_16x16x32_bf16 v[98:101], v[154:157], v[190:193], v[98:101]
	s_barrier
	s_setprio 0
	s_mov_b32 m0, s70
	ds_read_b128 v[206:209], v253 offset:49152
	ds_read_b128 v[210:213], v253 offset:50176
	v_lshl_add_u64 v[222:223], v[222:223], 0, s[76:77]
	ds_read_b128 v[214:217], v253 offset:51200
	ds_read_b128 v[218:221], v253 offset:52224
	global_load_lds_dwordx4 v[222:223], off
	v_lshl_add_u64 v[222:223], v[224:225], 0, s[76:77]
	s_mov_b32 m0, s71
	s_nop 0
	global_load_lds_dwordx4 v[222:223], off
	s_setprio 1
	s_barrier
	s_waitcnt lgkmcnt(0)
	v_mfma_f32_16x16x32_bf16 v[62:65], v[206:209], v[158:161], v[62:65]
	v_mfma_f32_16x16x32_bf16 v[58:61], v[214:217], v[158:161], v[58:61]
	v_mfma_f32_16x16x32_bf16 v[54:57], v[206:209], v[170:173], v[54:57]
	v_mfma_f32_16x16x32_bf16 v[46:49], v[214:217], v[170:173], v[46:49]
	v_mfma_f32_16x16x32_bf16 v[50:53], v[206:209], v[178:181], v[50:53]
	v_mfma_f32_16x16x32_bf16 v[42:45], v[214:217], v[178:181], v[42:45]
	v_mfma_f32_16x16x32_bf16 v[38:41], v[206:209], v[186:189], v[38:41]
	v_mfma_f32_16x16x32_bf16 v[34:37], v[214:217], v[186:189], v[34:37]
	v_mfma_f32_16x16x32_bf16 v[62:65], v[210:213], v[166:169], v[62:65]
	v_mfma_f32_16x16x32_bf16 v[58:61], v[218:221], v[166:169], v[58:61]
	v_mfma_f32_16x16x32_bf16 v[54:57], v[210:213], v[174:177], v[54:57]
	v_mfma_f32_16x16x32_bf16 v[46:49], v[218:221], v[174:177], v[46:49]
	v_mfma_f32_16x16x32_bf16 v[50:53], v[210:213], v[182:185], v[50:53]
	v_mfma_f32_16x16x32_bf16 v[42:45], v[218:221], v[182:185], v[42:45]
	s_mov_b32 m0, s78
	v_mfma_f32_16x16x32_bf16 v[38:41], v[210:213], v[190:193], v[38:41]
	v_lshl_add_u64 v[222:223], v[226:227], 0, s[76:77]
	v_mfma_f32_16x16x32_bf16 v[34:37], v[218:221], v[190:193], v[34:37]
	s_barrier
	s_setprio 0
	ds_read_b128 v[158:161], v162 offset:49152
	ds_read_b128 v[166:169], v162 offset:50176
	ds_read_b128 v[170:173], v162 offset:51200
	ds_read_b128 v[174:177], v162 offset:52224
	ds_read_b128 v[178:181], v162 offset:53248
	ds_read_b128 v[182:185], v162 offset:54272
	ds_read_b128 v[186:189], v162 offset:55296
	ds_read_b128 v[190:193], v162 offset:56320
	global_load_lds_dwordx4 v[222:223], off
	v_lshl_add_u64 v[222:223], v[228:229], 0, s[76:77]
	s_mov_b32 m0, s79
	s_nop 0
	global_load_lds_dwordx4 v[222:223], off
	s_setprio 1
	s_barrier
	s_waitcnt lgkmcnt(0)
	v_mfma_f32_16x16x32_bf16 v[94:97], v[130:133], v[158:161], v[94:97]
	v_mfma_f32_16x16x32_bf16 v[90:93], v[150:153], v[158:161], v[90:93]
	v_mfma_f32_16x16x32_bf16 v[86:89], v[130:133], v[170:173], v[86:89]
	v_mfma_f32_16x16x32_bf16 v[82:85], v[150:153], v[170:173], v[82:85]
	v_mfma_f32_16x16x32_bf16 v[78:81], v[130:133], v[178:181], v[78:81]
	v_mfma_f32_16x16x32_bf16 v[74:77], v[150:153], v[178:181], v[74:77]
	v_mfma_f32_16x16x32_bf16 v[70:73], v[130:133], v[186:189], v[70:73]
	v_mfma_f32_16x16x32_bf16 v[66:69], v[150:153], v[186:189], v[66:69]
	v_mfma_f32_16x16x32_bf16 v[94:97], v[134:137], v[166:169], v[94:97]
	v_mfma_f32_16x16x32_bf16 v[90:93], v[154:157], v[166:169], v[90:93]
	v_mfma_f32_16x16x32_bf16 v[86:89], v[134:137], v[174:177], v[86:89]
	v_mfma_f32_16x16x32_bf16 v[82:85], v[154:157], v[174:177], v[82:85]
	v_mfma_f32_16x16x32_bf16 v[78:81], v[134:137], v[182:185], v[78:81]
	v_mfma_f32_16x16x32_bf16 v[74:77], v[154:157], v[182:185], v[74:77]
	v_mfma_f32_16x16x32_bf16 v[70:73], v[134:137], v[190:193], v[70:73]
	v_mfma_f32_16x16x32_bf16 v[66:69], v[154:157], v[190:193], v[66:69]
	s_barrier
	s_setprio 0
	s_add_u32 s10, s54, 0x80080
	s_addc_u32 s11, s55, 0
	s_mov_b32 m0, s80
	s_nop 0
	global_load_lds_dwordx4 v194, s[10:11]
	s_mov_b32 m0, s81
	s_nop 0
	global_load_lds_dwordx4 v138, s[10:11]
	s_waitcnt vmcnt(6)
	s_setprio 1
	s_barrier
	v_mfma_f32_16x16x32_bf16 v[30:33], v[206:209], v[158:161], v[30:33]
	v_mfma_f32_16x16x32_bf16 v[18:21], v[214:217], v[158:161], v[18:21]
	v_mfma_f32_16x16x32_bf16 v[26:29], v[206:209], v[170:173], v[26:29]
	v_mfma_f32_16x16x32_bf16 v[14:17], v[214:217], v[170:173], v[14:17]
	v_mfma_f32_16x16x32_bf16 v[22:25], v[206:209], v[178:181], v[22:25]
	v_mfma_f32_16x16x32_bf16 v[6:9], v[214:217], v[178:181], v[6:9]
	v_mfma_f32_16x16x32_bf16 v[10:13], v[206:209], v[186:189], v[10:13]
	v_mfma_f32_16x16x32_bf16 v[2:5], v[214:217], v[186:189], v[2:5]
	s_add_i32 s29, s29, 2
	s_add_u32 s52, s52, 0x100
	s_addc_u32 s53, s53, 0
	s_add_u32 s5, s5, 0x100
	s_addc_u32 s7, s7, 0
	s_cmp_gt_u32 s29, 29
	v_mfma_f32_16x16x32_bf16 v[30:33], v[210:213], v[166:169], v[30:33]
	v_mfma_f32_16x16x32_bf16 v[18:21], v[218:221], v[166:169], v[18:21]
	v_mfma_f32_16x16x32_bf16 v[26:29], v[210:213], v[174:177], v[26:29]
	v_mfma_f32_16x16x32_bf16 v[14:17], v[218:221], v[174:177], v[14:17]
	v_mfma_f32_16x16x32_bf16 v[22:25], v[210:213], v[182:185], v[22:25]
	v_mfma_f32_16x16x32_bf16 v[6:9], v[218:221], v[182:185], v[6:9]
	v_mfma_f32_16x16x32_bf16 v[10:13], v[210:213], v[190:193], v[10:13]
	v_mfma_f32_16x16x32_bf16 v[2:5], v[218:221], v[190:193], v[2:5]
	s_barrier
	s_setprio 0
	s_cbranch_scc0 .LBB0_504
	v_readlane_b32 s10, v250, 21
	s_cmp_gt_i32 s40, 63
	v_readlane_b32 s11, v250, 22
	s_mov_b64 s[20:21], s[48:49]
	s_cselect_b32 s11, s21, s11
	s_cselect_b32 s10, s20, s10
	v_readlane_b32 s20, v252, 0
	v_readlane_b32 s26, v252, 6
	v_readlane_b32 s27, v252, 7
	s_cselect_b32 s53, s3, s27
	s_cselect_b32 s52, s2, s26
	s_sub_i32 s5, s40, 64
	s_cmp_gt_i32 s40, 63
	s_cselect_b32 s54, s5, s40
	s_lshr_b32 s5, s40, 3
	s_cmp_gt_i32 s40, 63
	s_mulk_i32 s5, 0x1800
	v_lshl_or_b32 v130, s28, 8, v164
	s_cselect_b32 s28, 0xc000, s5
	s_ashr_i32 s29, s28, 31
	s_lshl_b64 s[28:29], s[28:29], 2
	s_add_u32 s28, s63, s28
	v_ashrrev_i32_e32 v131, 31, v130
	s_addc_u32 s29, s67, s29
	v_lshlrev_b64 v[130:131], 2, v[130:131]
	v_lshl_add_u64 v[132:133], s[28:29], 0, v[130:131]
	s_mov_b64 s[28:29], 0x6484000
	s_ashr_i32 s55, s54, 31
	v_lshl_add_u64 v[154:155], v[132:133], 0, s[28:29]
	s_lshl_b64 s[28:29], s[54:55], 19
	v_lshl_add_u64 v[134:135], s[28:29], 0, v[144:145]
	v_lshlrev_b64 v[134:135], 2, v[134:135]
	v_lshl_add_u64 v[136:137], s[10:11], 0, v[134:135]
	v_lshl_add_u64 v[134:135], s[52:53], 0, v[134:135]
	s_mov_b32 s5, 0x6484000
	v_lshl_add_u64 v[150:151], v[136:137], 0, v[130:131]
	v_lshl_add_u64 v[152:153], v[134:135], 0, v[130:131]
	v_add_co_u32_e32 v130, vcc, s5, v132
	s_mov_b64 s[10:11], 0x20000
	s_nop 0
	v_addc_co_u32_e32 v131, vcc, 0, v133, vcc
	v_add_co_u32_e32 v156, vcc, s13, v150
	global_load_dwordx4 v[134:137], v[130:131], off
	s_nop 0
	global_load_dwordx4 v[130:133], v[154:155], off offset:16
	global_load_dwordx4 v[166:169], v[150:151], off offset:16
	global_load_dwordx4 v[170:173], v[150:151], off
	v_lshl_add_u64 v[158:159], v[150:151], 0, s[10:11]
	v_addc_co_u32_e32 v157, vcc, 0, v151, vcc
	s_mov_b32 s5, 0x40000
	global_load_dwordx4 v[174:177], v[156:157], off
	global_load_dwordx4 v[178:181], v[158:159], off offset:16
	s_mov_b64 s[10:11], 0x40000
	v_add_co_u32_e32 v158, vcc, s5, v150
	v_lshl_add_u64 v[160:161], v[150:151], 0, s[10:11]
	s_nop 0
	v_addc_co_u32_e32 v159, vcc, 0, v151, vcc
	s_mov_b32 s7, 0x60000
	global_load_dwordx4 v[182:185], v[158:159], off
	global_load_dwordx4 v[186:189], v[160:161], off offset:16
	s_mov_b64 s[10:11], 0x60000
	v_add_co_u32_e32 v160, vcc, s7, v150
	v_lshl_add_u64 v[206:207], v[150:151], 0, s[10:11]
	s_nop 0
	v_addc_co_u32_e32 v161, vcc, 0, v151, vcc
	global_load_dwordx4 v[190:193], v[160:161], off
	s_nop 0
	global_load_dwordx4 v[206:209], v[206:207], off offset:16
	v_readlane_b32 s21, v252, 1
	v_readlane_b32 s22, v252, 2
	v_readlane_b32 s23, v252, 3
	v_readlane_b32 s24, v252, 4
	v_readlane_b32 s25, v252, 5
	s_waitcnt vmcnt(0)
	v_pk_fma_f32 v[124:125], v[124:125], v[132:133], v[168:169]
	v_pk_fma_f32 v[122:123], v[122:123], v[130:131], v[166:167]
	global_store_dwordx4 v[152:153], v[122:125], off offset:16
	v_pk_fma_f32 v[128:129], v[128:129], v[136:137], v[172:173]
	v_pk_fma_f32 v[126:127], v[126:127], v[134:135], v[170:171]
	v_pk_fma_f32 v[122:123], v[120:121], v[136:137], v[176:177]
	v_pk_fma_f32 v[120:121], v[118:119], v[134:135], v[174:175]
	v_add_co_u32_e32 v118, vcc, s13, v152
	v_pk_fma_f32 v[116:117], v[116:117], v[132:133], v[180:181]
	s_nop 0
	v_addc_co_u32_e32 v119, vcc, 0, v153, vcc
	v_pk_fma_f32 v[114:115], v[114:115], v[130:131], v[178:179]
	global_store_dwordx4 v[118:119], v[114:117], off offset:16
	v_pk_fma_f32 v[108:109], v[108:109], v[132:133], v[188:189]
	v_pk_fma_f32 v[106:107], v[106:107], v[130:131], v[186:187]
	v_pk_fma_f32 v[114:115], v[112:113], v[136:137], v[184:185]
	v_pk_fma_f32 v[112:113], v[110:111], v[134:135], v[182:183]
	v_add_co_u32_e32 v110, vcc, s5, v152
	global_store_dwordx4 v[152:153], v[126:129], off
	s_nop 0
	v_addc_co_u32_e32 v111, vcc, 0, v153, vcc
	global_store_dwordx4 v[110:111], v[106:109], off offset:16
	v_pk_fma_f32 v[100:101], v[100:101], v[132:133], v[208:209]
	v_pk_fma_f32 v[98:99], v[98:99], v[130:131], v[206:207]
	v_pk_fma_f32 v[106:107], v[104:105], v[136:137], v[192:193]
	v_pk_fma_f32 v[104:105], v[102:103], v[134:135], v[190:191]
	v_add_co_u32_e32 v102, vcc, s7, v152
	global_store_dwordx4 v[118:119], v[120:123], off
	s_nop 0
	v_addc_co_u32_e32 v103, vcc, 0, v153, vcc
	global_store_dwordx4 v[110:111], v[112:115], off
	global_store_dwordx4 v[102:103], v[104:107], off
	global_store_dwordx4 v[102:103], v[98:101], off offset:16
	s_mov_b32 s5, 0x100000
	s_mov_b64 s[10:11], 0x100000
	v_add_co_u32_e32 v98, vcc, s5, v150
	v_lshl_add_u64 v[100:101], v[150:151], 0, s[10:11]
	s_nop 0
	v_addc_co_u32_e32 v99, vcc, 0, v151, vcc
	global_load_dwordx4 v[112:115], v[98:99], off
	global_load_dwordx4 v[120:123], v[100:101], off offset:16
	s_mov_b64 s[10:11], 0x120000
	v_add_co_u32_e32 v100, vcc, s45, v150
	v_lshl_add_u64 v[104:105], v[150:151], 0, s[10:11]
	s_nop 0
	v_addc_co_u32_e32 v101, vcc, 0, v151, vcc
	s_mov_b64 s[10:11], 0x140000
	s_mov_b32 s7, 0x140000
	global_load_dwordx4 v[124:127], v[100:101], off
	global_load_dwordx4 v[166:169], v[104:105], off offset:16
	v_lshl_add_u64 v[106:107], v[150:151], 0, s[10:11]
	v_add_co_u32_e32 v104, vcc, s7, v150
	s_mov_b64 s[10:11], 0x160000
	s_nop 0
	v_addc_co_u32_e32 v105, vcc, 0, v151, vcc
	v_lshl_add_u64 v[108:109], v[150:151], 0, s[10:11]
	s_mov_b32 s10, 0x160000
	global_load_dwordx4 v[170:173], v[104:105], off
	global_load_dwordx4 v[174:177], v[106:107], off offset:16
	v_add_co_u32_e32 v106, vcc, s10, v150
	s_waitcnt vmcnt(0)
	v_pk_fma_f32 v[112:113], v[94:95], v[134:135], v[112:113]
	v_addc_co_u32_e32 v107, vcc, 0, v151, vcc
	global_load_dwordx4 v[178:181], v[106:107], off
	global_load_dwordx4 v[182:185], v[108:109], off offset:16
	v_add_co_u32_e32 v94, vcc, s5, v152
	v_pk_fma_f32 v[92:93], v[92:93], v[132:133], v[122:123]
	s_nop 0
	v_addc_co_u32_e32 v95, vcc, 0, v153, vcc
	v_pk_fma_f32 v[90:91], v[90:91], v[130:131], v[120:121]
	global_store_dwordx4 v[94:95], v[90:93], off offset:16
	v_pk_fma_f32 v[84:85], v[84:85], v[132:133], v[168:169]
	v_pk_fma_f32 v[82:83], v[82:83], v[130:131], v[166:167]
	v_pk_fma_f32 v[90:91], v[88:89], v[136:137], v[126:127]
	v_pk_fma_f32 v[88:89], v[86:87], v[134:135], v[124:125]
	v_add_co_u32_e32 v86, vcc, s45, v152
	v_pk_fma_f32 v[114:115], v[96:97], v[136:137], v[114:115]
	s_nop 0
	v_addc_co_u32_e32 v87, vcc, 0, v153, vcc
	global_store_dwordx4 v[86:87], v[82:85], off offset:16
	v_pk_fma_f32 v[76:77], v[76:77], v[132:133], v[176:177]
	v_pk_fma_f32 v[74:75], v[74:75], v[130:131], v[174:175]
	v_pk_fma_f32 v[82:83], v[80:81], v[136:137], v[172:173]
	v_pk_fma_f32 v[80:81], v[78:79], v[134:135], v[170:171]
	v_add_co_u32_e32 v78, vcc, s7, v152
	global_store_dwordx4 v[94:95], v[112:115], off
	s_nop 0
	v_addc_co_u32_e32 v79, vcc, 0, v153, vcc
	global_store_dwordx4 v[78:79], v[74:77], off offset:16
	global_store_dwordx4 v[86:87], v[88:91], off
	global_store_dwordx4 v[78:79], v[80:83], off
	v_add_co_u32_e32 v74, vcc, s10, v152
	s_waitcnt vmcnt(0)
	v_pk_fma_f32 v[72:73], v[72:73], v[136:137], v[180:181]
	v_pk_fma_f32 v[70:71], v[70:71], v[134:135], v[178:179]
	v_addc_co_u32_e32 v75, vcc, 0, v153, vcc
	v_pk_fma_f32 v[68:69], v[68:69], v[132:133], v[184:185]
	v_pk_fma_f32 v[66:67], v[66:67], v[130:131], v[182:183]
	global_store_dwordx4 v[74:75], v[70:73], off
	global_store_dwordx4 v[74:75], v[66:69], off offset:16
	s_mov_b64 s[10:11], 0x20200
	v_lshl_add_u64 v[76:77], v[150:151], 0, s[10:11]
	s_mov_b64 s[10:11], 0x40200
	global_load_dwordx4 v[80:83], v[150:151], off offset:512
	global_load_dwordx4 v[70:73], v[154:155], off offset:512
	global_load_dwordx4 v[66:69], v[154:155], off offset:528
	global_load_dwordx4 v[88:91], v[150:151], off offset:528
	global_load_dwordx4 v[112:115], v[156:157], off offset:512
	global_load_dwordx4 v[120:123], v[158:159], off offset:512
	global_load_dwordx4 v[124:127], v[76:77], off offset:16
	v_lshl_add_u64 v[76:77], v[150:151], 0, s[10:11]
	s_mov_b64 s[10:11], 0x60200
	global_load_dwordx4 v[128:131], v[76:77], off offset:16
	global_load_dwordx4 v[132:135], v[160:161], off offset:512
	v_lshl_add_u64 v[76:77], v[150:151], 0, s[10:11]
	global_load_dwordx4 v[154:157], v[76:77], off offset:16
	s_waitcnt vmcnt(0)
	v_pk_fma_f32 v[64:65], v[64:65], v[72:73], v[82:83]
	v_pk_fma_f32 v[62:63], v[62:63], v[70:71], v[80:81]
	v_pk_fma_f32 v[60:61], v[60:61], v[68:69], v[90:91]
	v_pk_fma_f32 v[58:59], v[58:59], v[66:67], v[88:89]
	v_pk_fma_f32 v[52:53], v[52:53], v[72:73], v[122:123]
	v_pk_fma_f32 v[50:51], v[50:51], v[70:71], v[120:121]
	v_pk_fma_f32 v[48:49], v[48:49], v[68:69], v[126:127]
	v_pk_fma_f32 v[46:47], v[46:47], v[66:67], v[124:125]
	v_pk_fma_f32 v[56:57], v[56:57], v[72:73], v[114:115]
	v_pk_fma_f32 v[54:55], v[54:55], v[70:71], v[112:113]
	global_store_dwordx4 v[152:153], v[62:65], off offset:512
	global_store_dwordx4 v[152:153], v[58:61], off offset:528
	global_store_dwordx4 v[118:119], v[54:57], off offset:512
	global_store_dwordx4 v[110:111], v[50:53], off offset:512
	v_pk_fma_f32 v[44:45], v[44:45], v[68:69], v[130:131]
	v_pk_fma_f32 v[42:43], v[42:43], v[66:67], v[128:129]
	v_pk_fma_f32 v[40:41], v[40:41], v[72:73], v[134:135]
	v_pk_fma_f32 v[38:39], v[38:39], v[70:71], v[132:133]
	v_pk_fma_f32 v[36:37], v[36:37], v[68:69], v[156:157]
	v_pk_fma_f32 v[34:35], v[34:35], v[66:67], v[154:155]
	global_store_dwordx4 v[118:119], v[46:49], off offset:528
	global_store_dwordx4 v[110:111], v[42:45], off offset:528
	global_store_dwordx4 v[102:103], v[38:41], off offset:512
	global_store_dwordx4 v[102:103], v[34:37], off offset:528
	s_mov_b64 s[10:11], 0x100200
	v_lshl_add_u64 v[50:51], v[150:151], 0, s[10:11]
	s_mov_b64 s[10:11], 0x120200
	v_lshl_add_u64 v[54:55], v[150:151], 0, s[10:11]
	s_mov_b64 s[10:11], 0x140200
	v_lshl_add_u64 v[58:59], v[150:151], 0, s[10:11]
	s_mov_b64 s[10:11], 0x160200
	global_load_dwordx4 v[34:37], v[98:99], off offset:512
	global_load_dwordx4 v[38:41], v[100:101], off offset:512
	global_load_dwordx4 v[42:45], v[104:105], off offset:512
	global_load_dwordx4 v[46:49], v[106:107], off offset:512
	v_lshl_add_u64 v[62:63], v[150:151], 0, s[10:11]
	global_load_dwordx4 v[50:53], v[50:51], off offset:16
	s_waitcnt vmcnt(0)
	v_pk_fma_f32 v[32:33], v[32:33], v[72:73], v[36:37]
	global_load_dwordx4 v[54:57], v[54:55], off offset:16
	v_pk_fma_f32 v[30:31], v[30:31], v[70:71], v[34:35]
	global_load_dwordx4 v[58:61], v[58:59], off offset:16
	v_pk_fma_f32 v[28:29], v[28:29], v[72:73], v[40:41]
	global_load_dwordx4 v[62:65], v[62:63], off offset:16
	v_pk_fma_f32 v[26:27], v[26:27], v[70:71], v[38:39]
	v_pk_fma_f32 v[24:25], v[24:25], v[72:73], v[44:45]
	v_pk_fma_f32 v[22:23], v[22:23], v[70:71], v[42:43]
	v_pk_fma_f32 v[12:13], v[12:13], v[72:73], v[48:49]
	v_pk_fma_f32 v[10:11], v[10:11], v[70:71], v[46:47]
	v_pk_fma_f32 v[20:21], v[20:21], v[68:69], v[52:53]
	v_pk_fma_f32 v[18:19], v[18:19], v[66:67], v[50:51]
	global_store_dwordx4 v[94:95], v[30:33], off offset:512
	global_store_dwordx4 v[86:87], v[26:29], off offset:512
	global_store_dwordx4 v[78:79], v[22:25], off offset:512
	global_store_dwordx4 v[74:75], v[10:13], off offset:512
	s_waitcnt vmcnt(0)
	v_pk_fma_f32 v[16:17], v[16:17], v[68:69], v[56:57]
	v_pk_fma_f32 v[14:15], v[14:15], v[66:67], v[54:55]
	v_pk_fma_f32 v[8:9], v[8:9], v[68:69], v[60:61]
	v_pk_fma_f32 v[6:7], v[6:7], v[66:67], v[58:59]
	v_pk_fma_f32 v[4:5], v[4:5], v[68:69], v[64:65]
	v_pk_fma_f32 v[2:3], v[2:3], v[66:67], v[62:63]
	global_store_dwordx4 v[94:95], v[18:21], off offset:528
	global_store_dwordx4 v[86:87], v[14:17], off offset:528
	global_store_dwordx4 v[78:79], v[6:9], off offset:528
	global_store_dwordx4 v[74:75], v[2:5], off offset:528
	s_and_b64 vcc, exec, s[0:1]
	s_mov_b32 s40, s6
	s_mov_b32 s28, s4
	s_mov_b64 s[54:55], s[34:35]
	s_mov_b64 s[52:53], s[8:9]
	s_cbranch_vccz .LBB0_501
	s_waitcnt vmcnt(0)
	v_readlane_b32 s28, v250, 12
	v_readlane_b32 s26, v250, 15
	s_cmpk_gt_u32 s12, 0xff
	v_readlane_b32 s29, v250, 13
	v_readlane_b32 s27, v250, 16
	s_mov_b32 s70, 0x800000
	v_readlane_b32 s79, v250, 18
	s_cbranch_scc1 .LBB0_508
	s_barrier
